# v18 plus write-through (sc1) policy on the in-projection GEMM epilogue stores only, so the 4 MB/round of outputs stop evicting A/B tiles from L2
# speedup vs baseline: 1.0071x; 1.0071x over previous
; DI unsigned pk2(float lo, float hi) { f32x2 v = {lo, hi}; bf16v2 r = __builtin_convertvector(v, bf16v2); return __builtin_bit_cast(unsigned, r); }
; template <int ACT> DI void store_act(const f32x4 (&acc)[2][2][4][2], bf16_t* base, int row0, int col0) {
;     ...
;         for (int m = 0; m < 4; ++m) { bf16_t* rowp = base + (size_t)(row0 + ai * 128 + m * 16) * D + col0;
; #pragma unroll
;             for (int bj = 0; bj < 2; ++bj) { const f32x4 v0 = acc[ai][bj][m][0], v1 = acc[ai][bj][m][1];
;                 u32x4 w; w.x = pk2(act_fn<ACT>(v0[0]), act_fn<ACT>(v0[1])); w.y = pk2(act_fn<ACT>(v0[2]), act_fn<ACT>(v0[3]));
;                 w.z = pk2(act_fn<ACT>(v1[0]), act_fn<ACT>(v1[1])); w.w = pk2(act_fn<ACT>(v1[2]), act_fn<ACT>(v1[3]));
;                 *(u32x4*)(rowp + bj * 128) = w; } }
;     DI void operator()(const f32x4 (&acc)[2][2][4][2], const pg8::Unit& u, int wr, int wc, int fr, int fq) const {
;     ...
;         int idx, ct;
;         if (pn < 20) { idx = pn >> 2; ct = pn & 3; } else { idx = 6; ct = pn - 28; }
;         bf16_t* base = (idx <= 4) ? out9 + (size_t)idx * ARR : out9 + 5 * ARR; const int col0 = 256 * ct + cl;
;         if (idx == 0) store_act<1>(acc, base, row0, col0);
;         else if (idx <= 3) store_act<0>(acc, base, row0, col0);
;         else if (idx == 4) store_act<0>(acc, base, row0, col0);
;         else store_act<3>(acc, base, row0, col0);
.LBB0_244:
	s_cmp_lt_i32 s36, 32
	s_cbranch_scc0 .LBB0_257
	s_ashr_i32 s2, s36, 2
	s_and_b32 s3, s36, 3
	s_sub_i32 s15, s36, 28
	s_cmp_lt_i32 s36, 20
	s_cselect_b32 s22, s2, 6
	s_cselect_b32 s15, s3, s15
	s_ashr_i32 s23, s22, 31
	s_lshl_b64 s[2:3], s[22:23], 25
	s_cmp_lt_i32 s22, 5
	s_cselect_b32 s2, s2, 0xa000000
	s_cselect_b32 s3, s3, 0
	s_add_u32 s2, s68, s2
	s_addc_u32 s3, s69, s3
	s_cmp_lg_u32 s22, 0
	v_lshl_or_b32 v156, s15, 8, v166
	s_cbranch_scc0 .LBB0_263
	s_cmp_gt_i32 s22, 3
	s_mov_b64 s[24:25], -1
	s_cbranch_scc0 .LBB0_252
	v_ashrrev_i32_e32 v157, 31, v156
	v_ashrrev_i32_e32 v155, 31, v154
	v_lshl_add_u64 v[158:159], v[156:157], 1, s[2:3]
	v_lshlrev_b64 v[160:161], 11, v[154:155]
	s_cmp_lg_u32 s22, 4
	v_lshl_add_u64 v[160:161], v[158:159], 0, v[160:161]
	s_mov_b64 s[22:23], -1
	s_cbranch_scc0 .LBB0_249
	v_mul_f32_e32 v48, 0x3d372713, v126
	v_mul_f32_e32 v48, v126, v48
	v_fma_f32 v48, v126, v48, v126
	v_mul_f32_e32 v48, 0xc0135761, v48
	v_exp_f32_e32 v48, v48
	s_mov_b32 s15, 0x40000
	s_mov_b64 s[22:23], 0x40000
	v_add_f32_e32 v48, 1.0, v48
	v_rcp_f32_e32 v162, v48
	v_mul_f32_e32 v48, 0x3d372713, v127
	v_mul_f32_e32 v48, v127, v48
	v_fma_f32 v48, v127, v48, v127
	v_mul_f32_e32 v48, 0xc0135761, v48
	v_exp_f32_e32 v48, v48
	s_nop 0
	v_add_f32_e32 v48, 1.0, v48
	v_rcp_f32_e32 v163, v48
	v_mul_f32_e32 v48, 0x3d372713, v128
	v_mul_f32_e32 v48, v128, v48
	v_fma_f32 v48, v128, v48, v128
	v_mul_f32_e32 v48, 0xc0135761, v48
	v_exp_f32_e32 v48, v48
	v_pk_mul_f32 v[162:163], v[126:127], v[162:163]
	v_add_f32_e32 v48, 1.0, v48
	v_cvt_pk_bf16_f32 v178, v162, v163
	v_rcp_f32_e32 v162, v48
	v_mul_f32_e32 v48, 0x3d372713, v129
	v_mul_f32_e32 v48, v129, v48
	v_fma_f32 v48, v129, v48, v129
	v_mul_f32_e32 v48, 0xc0135761, v48
	v_exp_f32_e32 v48, v48
	s_nop 0
	v_add_f32_e32 v48, 1.0, v48
	v_rcp_f32_e32 v163, v48
	v_mul_f32_e32 v48, 0x3d372713, v118
	v_mul_f32_e32 v48, v118, v48
	v_fma_f32 v48, v118, v48, v118
	v_mul_f32_e32 v48, 0xc0135761, v48
	v_exp_f32_e32 v48, v48
	v_pk_mul_f32 v[162:163], v[128:129], v[162:163]
	v_add_f32_e32 v48, 1.0, v48
	v_cvt_pk_bf16_f32 v179, v162, v163
	v_rcp_f32_e32 v162, v48
	v_mul_f32_e32 v48, 0x3d372713, v119
	v_mul_f32_e32 v48, v119, v48
	v_fma_f32 v48, v119, v48, v119
	v_mul_f32_e32 v48, 0xc0135761, v48
	v_exp_f32_e32 v48, v48
	s_nop 0
	v_add_f32_e32 v48, 1.0, v48
	v_rcp_f32_e32 v163, v48
	v_mul_f32_e32 v48, 0x3d372713, v120
	v_mul_f32_e32 v48, v120, v48
	v_fma_f32 v48, v120, v48, v120
	v_mul_f32_e32 v48, 0xc0135761, v48
	v_exp_f32_e32 v48, v48
	v_pk_mul_f32 v[162:163], v[118:119], v[162:163]
	v_add_f32_e32 v48, 1.0, v48
	v_cvt_pk_bf16_f32 v180, v162, v163
	v_rcp_f32_e32 v162, v48
	v_mul_f32_e32 v48, 0x3d372713, v121
	v_mul_f32_e32 v48, v121, v48
	v_fma_f32 v48, v121, v48, v121
	v_mul_f32_e32 v48, 0xc0135761, v48
	v_exp_f32_e32 v48, v48
	s_nop 0
	v_add_f32_e32 v48, 1.0, v48
	v_rcp_f32_e32 v163, v48
	v_mul_f32_e32 v48, 0x3d372713, v122
	v_mul_f32_e32 v48, v122, v48
	v_fma_f32 v48, v122, v48, v122
	v_mul_f32_e32 v48, 0xc0135761, v48
	v_exp_f32_e32 v48, v48
	v_pk_mul_f32 v[162:163], v[120:121], v[162:163]
	v_add_f32_e32 v48, 1.0, v48
	v_cvt_pk_bf16_f32 v181, v162, v163
	v_rcp_f32_e32 v162, v48
	v_mul_f32_e32 v48, 0x3d372713, v123
	v_mul_f32_e32 v48, v123, v48
	v_fma_f32 v48, v123, v48, v123
	v_mul_f32_e32 v48, 0xc0135761, v48
	v_exp_f32_e32 v48, v48
	global_store_dwordx4 v[160:161], v[178:181], off sc1
	v_add_f32_e32 v48, 1.0, v48
	v_rcp_f32_e32 v163, v48
	v_mul_f32_e32 v48, 0x3d372713, v124
	v_mul_f32_e32 v48, v124, v48
	v_fma_f32 v48, v124, v48, v124
	v_mul_f32_e32 v48, 0xc0135761, v48
	v_exp_f32_e32 v48, v48
	v_pk_mul_f32 v[162:163], v[122:123], v[162:163]
	v_add_f32_e32 v48, 1.0, v48
	v_cvt_pk_bf16_f32 v178, v162, v163
	v_rcp_f32_e32 v162, v48
	v_mul_f32_e32 v48, 0x3d372713, v125
	v_mul_f32_e32 v48, v125, v48
	v_fma_f32 v48, v125, v48, v125
	v_mul_f32_e32 v48, 0xc0135761, v48
	v_exp_f32_e32 v48, v48
	s_nop 0
	v_add_f32_e32 v48, 1.0, v48
	v_rcp_f32_e32 v163, v48
	v_mul_f32_e32 v48, 0x3d372713, v114
	v_mul_f32_e32 v48, v114, v48
	v_fma_f32 v48, v114, v48, v114
	v_mul_f32_e32 v48, 0xc0135761, v48
	v_exp_f32_e32 v48, v48
	v_pk_mul_f32 v[162:163], v[124:125], v[162:163]
	v_add_f32_e32 v48, 1.0, v48
	v_cvt_pk_bf16_f32 v179, v162, v163
	v_rcp_f32_e32 v162, v48
	v_mul_f32_e32 v48, 0x3d372713, v115
	v_mul_f32_e32 v48, v115, v48
	v_fma_f32 v48, v115, v48, v115
	v_mul_f32_e32 v48, 0xc0135761, v48
	v_exp_f32_e32 v48, v48
	s_nop 0
	v_add_f32_e32 v48, 1.0, v48
	v_rcp_f32_e32 v163, v48
	v_mul_f32_e32 v48, 0x3d372713, v116
	v_mul_f32_e32 v48, v116, v48
	v_fma_f32 v48, v116, v48, v116
	v_mul_f32_e32 v48, 0xc0135761, v48
	v_exp_f32_e32 v48, v48
	v_pk_mul_f32 v[162:163], v[114:115], v[162:163]
	v_add_f32_e32 v48, 1.0, v48
	v_cvt_pk_bf16_f32 v180, v162, v163
	v_rcp_f32_e32 v162, v48
	v_mul_f32_e32 v48, 0x3d372713, v117
	v_mul_f32_e32 v48, v117, v48
	v_fma_f32 v48, v117, v48, v117
	v_mul_f32_e32 v48, 0xc0135761, v48
	v_exp_f32_e32 v48, v48
	s_nop 0
	v_add_f32_e32 v48, 1.0, v48
	v_rcp_f32_e32 v163, v48
	v_mul_f32_e32 v48, 0x3d372713, v110
	v_mul_f32_e32 v48, v110, v48
	v_fma_f32 v48, v110, v48, v110
	v_mul_f32_e32 v48, 0xc0135761, v48
	v_exp_f32_e32 v48, v48
	v_pk_mul_f32 v[162:163], v[116:117], v[162:163]
	v_add_f32_e32 v48, 1.0, v48
	v_rcp_f32_e32 v170, v48
	v_mul_f32_e32 v48, 0x3d372713, v111
	v_mul_f32_e32 v48, v111, v48
	v_fma_f32 v48, v111, v48, v111
	v_mul_f32_e32 v48, 0xc0135761, v48
	v_exp_f32_e32 v48, v48
	v_cvt_pk_bf16_f32 v181, v162, v163
	global_store_dwordx4 v[160:161], v[178:181], off offset:256 sc1
	v_or_b32_e32 v162, 16, v154
	v_add_f32_e32 v48, 1.0, v48
	v_rcp_f32_e32 v171, v48
	v_mul_f32_e32 v48, 0x3d372713, v112
; DI unsigned pk2(float lo, float hi) { f32x2 v = {lo, hi}; bf16v2 r = __builtin_convertvector(v, bf16v2); return __builtin_bit_cast(unsigned, r); }
; DI float geluf_(float x) { const float t = x + 0.044715f * x * x * x; return x * frcp(1.0f + fexp2(-2.3022082f * t)); }
; template <int ACT> DI float act_fn(float x) {
;     ...
;     if (ACT == 3) return geluf_(x);
; template <int ACT> DI void store_act(const f32x4 (&acc)[2][2][4][2], bf16_t* base, int row0, int col0) {
;     ...
;         for (int m = 0; m < 4; ++m) { bf16_t* rowp = base + (size_t)(row0 + ai * 128 + m * 16) * D + col0;
; #pragma unroll
;             for (int bj = 0; bj < 2; ++bj) { const f32x4 v0 = acc[ai][bj][m][0], v1 = acc[ai][bj][m][1];
;                 u32x4 w; w.x = pk2(act_fn<ACT>(v0[0]), act_fn<ACT>(v0[1])); w.y = pk2(act_fn<ACT>(v0[2]), act_fn<ACT>(v0[3]));
;                 w.z = pk2(act_fn<ACT>(v1[0]), act_fn<ACT>(v1[1])); w.w = pk2(act_fn<ACT>(v1[2]), act_fn<ACT>(v1[3]));
;                 *(u32x4*)(rowp + bj * 128) = w; } }
	v_mul_f32_e32 v48, v112, v48
	v_fma_f32 v48, v112, v48, v112
	v_mul_f32_e32 v48, 0xc0135761, v48
	v_exp_f32_e32 v48, v48
	v_pk_mul_f32 v[170:171], v[110:111], v[170:171]
	v_ashrrev_i32_e32 v163, 31, v162
	v_cvt_pk_bf16_f32 v178, v170, v171
	v_add_f32_e32 v48, 1.0, v48
	v_rcp_f32_e32 v170, v48
	v_mul_f32_e32 v48, 0x3d372713, v113
	v_mul_f32_e32 v48, v113, v48
	v_fma_f32 v48, v113, v48, v113
	v_mul_f32_e32 v48, 0xc0135761, v48
	v_exp_f32_e32 v48, v48
	v_lshlrev_b64 v[162:163], 11, v[162:163]
	v_lshl_add_u64 v[162:163], v[158:159], 0, v[162:163]
	v_add_f32_e32 v48, 1.0, v48
	v_rcp_f32_e32 v171, v48
	v_mul_f32_e32 v48, 0x3d372713, v102
	v_mul_f32_e32 v48, v102, v48
	v_fma_f32 v48, v102, v48, v102
	v_mul_f32_e32 v48, 0xc0135761, v48
	v_exp_f32_e32 v48, v48
	v_pk_mul_f32 v[170:171], v[112:113], v[170:171]
	v_add_f32_e32 v48, 1.0, v48
	v_cvt_pk_bf16_f32 v179, v170, v171
	v_rcp_f32_e32 v170, v48
	v_mul_f32_e32 v48, 0x3d372713, v103
	v_mul_f32_e32 v48, v103, v48
	v_fma_f32 v48, v103, v48, v103
	v_mul_f32_e32 v48, 0xc0135761, v48
	v_exp_f32_e32 v48, v48
	s_nop 0
	v_add_f32_e32 v48, 1.0, v48
	v_rcp_f32_e32 v171, v48
	v_mul_f32_e32 v48, 0x3d372713, v104
	v_mul_f32_e32 v48, v104, v48
	v_fma_f32 v48, v104, v48, v104
	v_mul_f32_e32 v48, 0xc0135761, v48
	v_exp_f32_e32 v48, v48
	v_pk_mul_f32 v[170:171], v[102:103], v[170:171]
	v_add_f32_e32 v48, 1.0, v48
	v_cvt_pk_bf16_f32 v180, v170, v171
	v_rcp_f32_e32 v170, v48
	v_mul_f32_e32 v48, 0x3d372713, v105
	v_mul_f32_e32 v48, v105, v48
	v_fma_f32 v48, v105, v48, v105
	v_mul_f32_e32 v48, 0xc0135761, v48
	v_exp_f32_e32 v48, v48
	s_nop 0
	v_add_f32_e32 v48, 1.0, v48
	v_rcp_f32_e32 v171, v48
	v_mul_f32_e32 v48, 0x3d372713, v106
	v_mul_f32_e32 v48, v106, v48
	v_fma_f32 v48, v106, v48, v106
	v_mul_f32_e32 v48, 0xc0135761, v48
	v_exp_f32_e32 v48, v48
	v_pk_mul_f32 v[170:171], v[104:105], v[170:171]
	v_add_f32_e32 v48, 1.0, v48
	v_cvt_pk_bf16_f32 v181, v170, v171
	v_rcp_f32_e32 v170, v48
	v_mul_f32_e32 v48, 0x3d372713, v107
	v_mul_f32_e32 v48, v107, v48
	v_fma_f32 v48, v107, v48, v107
	v_mul_f32_e32 v48, 0xc0135761, v48
	v_exp_f32_e32 v48, v48
	global_store_dwordx4 v[162:163], v[178:181], off sc1
	v_add_f32_e32 v48, 1.0, v48
	v_rcp_f32_e32 v171, v48
	v_mul_f32_e32 v48, 0x3d372713, v108
	v_mul_f32_e32 v48, v108, v48
	v_fma_f32 v48, v108, v48, v108
	v_mul_f32_e32 v48, 0xc0135761, v48
	v_exp_f32_e32 v48, v48
	v_pk_mul_f32 v[170:171], v[106:107], v[170:171]
	v_add_f32_e32 v48, 1.0, v48
	v_cvt_pk_bf16_f32 v178, v170, v171
	v_rcp_f32_e32 v170, v48
	v_mul_f32_e32 v48, 0x3d372713, v109
	v_mul_f32_e32 v48, v109, v48
	v_fma_f32 v48, v109, v48, v109
	v_mul_f32_e32 v48, 0xc0135761, v48
	v_exp_f32_e32 v48, v48
	s_nop 0
	v_add_f32_e32 v48, 1.0, v48
	v_rcp_f32_e32 v171, v48
	v_mul_f32_e32 v48, 0x3d372713, v98
	v_mul_f32_e32 v48, v98, v48
	v_fma_f32 v48, v98, v48, v98
	v_mul_f32_e32 v48, 0xc0135761, v48
	v_exp_f32_e32 v48, v48
	v_pk_mul_f32 v[170:171], v[108:109], v[170:171]
	v_add_f32_e32 v48, 1.0, v48
	v_cvt_pk_bf16_f32 v179, v170, v171
	v_rcp_f32_e32 v170, v48
	v_mul_f32_e32 v48, 0x3d372713, v99
	v_mul_f32_e32 v48, v99, v48
	v_fma_f32 v48, v99, v48, v99
	v_mul_f32_e32 v48, 0xc0135761, v48
	v_exp_f32_e32 v48, v48
	s_nop 0
	v_add_f32_e32 v48, 1.0, v48
	v_rcp_f32_e32 v171, v48
	v_mul_f32_e32 v48, 0x3d372713, v100
	v_mul_f32_e32 v48, v100, v48
	v_fma_f32 v48, v100, v48, v100
	v_mul_f32_e32 v48, 0xc0135761, v48
	v_exp_f32_e32 v48, v48
	v_pk_mul_f32 v[170:171], v[98:99], v[170:171]
	v_add_f32_e32 v48, 1.0, v48
	v_cvt_pk_bf16_f32 v180, v170, v171
	v_rcp_f32_e32 v170, v48
	v_mul_f32_e32 v48, 0x3d372713, v101
	v_mul_f32_e32 v48, v101, v48
	v_fma_f32 v48, v101, v48, v101
	v_mul_f32_e32 v48, 0xc0135761, v48
	v_exp_f32_e32 v48, v48
	s_nop 0
	v_add_f32_e32 v48, 1.0, v48
	v_rcp_f32_e32 v171, v48
	v_mul_f32_e32 v48, 0x3d372713, v94
	v_mul_f32_e32 v48, v94, v48
	v_fma_f32 v48, v94, v48, v94
	v_mul_f32_e32 v48, 0xc0135761, v48
	v_exp_f32_e32 v48, v48
	v_pk_mul_f32 v[170:171], v[100:101], v[170:171]
	v_add_f32_e32 v48, 1.0, v48
	v_cvt_pk_bf16_f32 v181, v170, v171
	v_rcp_f32_e32 v170, v48
	v_mul_f32_e32 v48, 0x3d372713, v95
	v_mul_f32_e32 v48, v95, v48
	v_fma_f32 v48, v95, v48, v95
	v_mul_f32_e32 v48, 0xc0135761, v48
	v_exp_f32_e32 v48, v48
	global_store_dwordx4 v[162:163], v[178:181], off offset:256 sc1
	v_or_b32_e32 v162, 32, v154
	v_ashrrev_i32_e32 v163, 31, v162
	v_add_f32_e32 v48, 1.0, v48
	v_rcp_f32_e32 v171, v48
	v_mul_f32_e32 v48, 0x3d372713, v96
	v_mul_f32_e32 v48, v96, v48
	v_fma_f32 v48, v96, v48, v96
	v_mul_f32_e32 v48, 0xc0135761, v48
	v_exp_f32_e32 v48, v48
	v_pk_mul_f32 v[170:171], v[94:95], v[170:171]
	v_lshlrev_b64 v[162:163], 11, v[162:163]
	v_cvt_pk_bf16_f32 v178, v170, v171
	v_add_f32_e32 v48, 1.0, v48
	v_rcp_f32_e32 v170, v48
	v_mul_f32_e32 v48, 0x3d372713, v97
	v_mul_f32_e32 v48, v97, v48
	v_fma_f32 v48, v97, v48, v97
	v_mul_f32_e32 v48, 0xc0135761, v48
	v_exp_f32_e32 v48, v48
	v_lshl_add_u64 v[162:163], v[158:159], 0, v[162:163]
	v_add_f32_e32 v48, 1.0, v48
	v_rcp_f32_e32 v171, v48
	v_mul_f32_e32 v48, 0x3d372713, v86
	v_mul_f32_e32 v48, v86, v48
	v_fma_f32 v48, v86, v48, v86
	v_mul_f32_e32 v48, 0xc0135761, v48
	v_exp_f32_e32 v48, v48
	v_pk_mul_f32 v[170:171], v[96:97], v[170:171]
	v_add_f32_e32 v48, 1.0, v48
	v_cvt_pk_bf16_f32 v179, v170, v171
	v_rcp_f32_e32 v170, v48
	v_mul_f32_e32 v48, 0x3d372713, v87
	v_mul_f32_e32 v48, v87, v48
	v_fma_f32 v48, v87, v48, v87
	v_mul_f32_e32 v48, 0xc0135761, v48
	v_exp_f32_e32 v48, v48
	s_nop 0
	v_add_f32_e32 v48, 1.0, v48
	v_rcp_f32_e32 v171, v48
	v_mul_f32_e32 v48, 0x3d372713, v88
	v_mul_f32_e32 v48, v88, v48
	v_fma_f32 v48, v88, v48, v88
	v_mul_f32_e32 v48, 0xc0135761, v48
; DI unsigned pk2(float lo, float hi) { f32x2 v = {lo, hi}; bf16v2 r = __builtin_convertvector(v, bf16v2); return __builtin_bit_cast(unsigned, r); }
; DI float geluf_(float x) { const float t = x + 0.044715f * x * x * x; return x * frcp(1.0f + fexp2(-2.3022082f * t)); }
; template <int ACT> DI float act_fn(float x) {
;     ...
;     if (ACT == 3) return geluf_(x);
; template <int ACT> DI void store_act(const f32x4 (&acc)[2][2][4][2], bf16_t* base, int row0, int col0) {
;     ...
;         for (int m = 0; m < 4; ++m) { bf16_t* rowp = base + (size_t)(row0 + ai * 128 + m * 16) * D + col0;
; #pragma unroll
;             for (int bj = 0; bj < 2; ++bj) { const f32x4 v0 = acc[ai][bj][m][0], v1 = acc[ai][bj][m][1];
;                 u32x4 w; w.x = pk2(act_fn<ACT>(v0[0]), act_fn<ACT>(v0[1])); w.y = pk2(act_fn<ACT>(v0[2]), act_fn<ACT>(v0[3]));
;                 w.z = pk2(act_fn<ACT>(v1[0]), act_fn<ACT>(v1[1])); w.w = pk2(act_fn<ACT>(v1[2]), act_fn<ACT>(v1[3]));
;                 *(u32x4*)(rowp + bj * 128) = w; } }
	v_exp_f32_e32 v48, v48
	v_pk_mul_f32 v[170:171], v[86:87], v[170:171]
	v_add_f32_e32 v48, 1.0, v48
	v_cvt_pk_bf16_f32 v180, v170, v171
	v_rcp_f32_e32 v170, v48
	v_mul_f32_e32 v48, 0x3d372713, v89
	v_mul_f32_e32 v48, v89, v48
	v_fma_f32 v48, v89, v48, v89
	v_mul_f32_e32 v48, 0xc0135761, v48
	v_exp_f32_e32 v48, v48
	s_nop 0
	v_add_f32_e32 v48, 1.0, v48
	v_rcp_f32_e32 v171, v48
	v_mul_f32_e32 v48, 0x3d372713, v90
	v_mul_f32_e32 v48, v90, v48
	v_fma_f32 v48, v90, v48, v90
	v_mul_f32_e32 v48, 0xc0135761, v48
	v_exp_f32_e32 v48, v48
	v_pk_mul_f32 v[170:171], v[88:89], v[170:171]
	v_add_f32_e32 v48, 1.0, v48
	v_cvt_pk_bf16_f32 v181, v170, v171
	v_rcp_f32_e32 v170, v48
	v_mul_f32_e32 v48, 0x3d372713, v91
	v_mul_f32_e32 v48, v91, v48
	v_fma_f32 v48, v91, v48, v91
	v_mul_f32_e32 v48, 0xc0135761, v48
	v_exp_f32_e32 v48, v48
	global_store_dwordx4 v[162:163], v[178:181], off sc1
	v_add_f32_e32 v48, 1.0, v48
	v_rcp_f32_e32 v171, v48
	v_mul_f32_e32 v48, 0x3d372713, v92
	v_mul_f32_e32 v48, v92, v48
	v_fma_f32 v48, v92, v48, v92
	v_mul_f32_e32 v48, 0xc0135761, v48
	v_exp_f32_e32 v48, v48
	v_pk_mul_f32 v[170:171], v[90:91], v[170:171]
	v_add_f32_e32 v48, 1.0, v48
	v_cvt_pk_bf16_f32 v178, v170, v171
	v_rcp_f32_e32 v170, v48
	v_mul_f32_e32 v48, 0x3d372713, v93
	v_mul_f32_e32 v48, v93, v48
	v_fma_f32 v48, v93, v48, v93
	v_mul_f32_e32 v48, 0xc0135761, v48
	v_exp_f32_e32 v48, v48
	s_nop 0
	v_add_f32_e32 v48, 1.0, v48
	v_rcp_f32_e32 v171, v48
	v_mul_f32_e32 v48, 0x3d372713, v82
	v_mul_f32_e32 v48, v82, v48
	v_fma_f32 v48, v82, v48, v82
	v_mul_f32_e32 v48, 0xc0135761, v48
	v_exp_f32_e32 v48, v48
	v_pk_mul_f32 v[170:171], v[92:93], v[170:171]
	v_add_f32_e32 v48, 1.0, v48
	v_cvt_pk_bf16_f32 v179, v170, v171
	v_rcp_f32_e32 v170, v48
	v_mul_f32_e32 v48, 0x3d372713, v83
	v_mul_f32_e32 v48, v83, v48
	v_fma_f32 v48, v83, v48, v83
	v_mul_f32_e32 v48, 0xc0135761, v48
	v_exp_f32_e32 v48, v48
	s_nop 0
	v_add_f32_e32 v48, 1.0, v48
	v_rcp_f32_e32 v171, v48
	v_mul_f32_e32 v48, 0x3d372713, v84
	v_mul_f32_e32 v48, v84, v48
	v_fma_f32 v48, v84, v48, v84
	v_mul_f32_e32 v48, 0xc0135761, v48
	v_exp_f32_e32 v48, v48
	v_pk_mul_f32 v[170:171], v[82:83], v[170:171]
	v_add_f32_e32 v48, 1.0, v48
	v_cvt_pk_bf16_f32 v180, v170, v171
	v_rcp_f32_e32 v170, v48
	v_mul_f32_e32 v48, 0x3d372713, v85
	v_mul_f32_e32 v48, v85, v48
	v_fma_f32 v48, v85, v48, v85
	v_mul_f32_e32 v48, 0xc0135761, v48
	v_exp_f32_e32 v48, v48
	s_nop 0
	v_add_f32_e32 v48, 1.0, v48
	v_rcp_f32_e32 v171, v48
	v_mul_f32_e32 v48, 0x3d372713, v78
	v_mul_f32_e32 v48, v78, v48
	v_fma_f32 v48, v78, v48, v78
	v_mul_f32_e32 v48, 0xc0135761, v48
	v_exp_f32_e32 v48, v48
	v_pk_mul_f32 v[170:171], v[84:85], v[170:171]
	v_add_f32_e32 v48, 1.0, v48
	v_cvt_pk_bf16_f32 v181, v170, v171
	v_rcp_f32_e32 v170, v48
	v_mul_f32_e32 v48, 0x3d372713, v79
	v_mul_f32_e32 v48, v79, v48
	v_fma_f32 v48, v79, v48, v79
	v_mul_f32_e32 v48, 0xc0135761, v48
	v_exp_f32_e32 v48, v48
	global_store_dwordx4 v[162:163], v[178:181], off offset:256 sc1
	v_or_b32_e32 v162, 48, v154
	v_ashrrev_i32_e32 v163, 31, v162
	v_add_f32_e32 v48, 1.0, v48
	v_rcp_f32_e32 v171, v48
	v_mul_f32_e32 v48, 0x3d372713, v80
	v_mul_f32_e32 v48, v80, v48
	v_fma_f32 v48, v80, v48, v80
	v_mul_f32_e32 v48, 0xc0135761, v48
	v_exp_f32_e32 v48, v48
	v_pk_mul_f32 v[170:171], v[78:79], v[170:171]
	v_lshlrev_b64 v[162:163], 11, v[162:163]
	v_cvt_pk_bf16_f32 v178, v170, v171
	v_add_f32_e32 v48, 1.0, v48
	v_rcp_f32_e32 v170, v48
	v_mul_f32_e32 v48, 0x3d372713, v81
	v_mul_f32_e32 v48, v81, v48
	v_fma_f32 v48, v81, v48, v81
	v_mul_f32_e32 v48, 0xc0135761, v48
	v_exp_f32_e32 v48, v48
	v_lshl_add_u64 v[162:163], v[158:159], 0, v[162:163]
	v_add_f32_e32 v48, 1.0, v48
	v_rcp_f32_e32 v171, v48
	v_mul_f32_e32 v48, 0x3d372713, v70
	v_mul_f32_e32 v48, v70, v48
	v_fma_f32 v48, v70, v48, v70
	v_mul_f32_e32 v48, 0xc0135761, v48
	v_exp_f32_e32 v48, v48
	v_pk_mul_f32 v[170:171], v[80:81], v[170:171]
	v_add_f32_e32 v48, 1.0, v48
	v_cvt_pk_bf16_f32 v179, v170, v171
	v_rcp_f32_e32 v170, v48
	v_mul_f32_e32 v48, 0x3d372713, v71
	v_mul_f32_e32 v48, v71, v48
	v_fma_f32 v48, v71, v48, v71
	v_mul_f32_e32 v48, 0xc0135761, v48
	v_exp_f32_e32 v48, v48
	s_nop 0
	v_add_f32_e32 v48, 1.0, v48
	v_rcp_f32_e32 v171, v48
	v_mul_f32_e32 v48, 0x3d372713, v72
	v_mul_f32_e32 v48, v72, v48
	v_fma_f32 v48, v72, v48, v72
	v_mul_f32_e32 v48, 0xc0135761, v48
	v_exp_f32_e32 v48, v48
	v_pk_mul_f32 v[170:171], v[70:71], v[170:171]
	v_add_f32_e32 v48, 1.0, v48
	v_cvt_pk_bf16_f32 v180, v170, v171
	v_rcp_f32_e32 v170, v48
	v_mul_f32_e32 v48, 0x3d372713, v73
	v_mul_f32_e32 v48, v73, v48
	v_fma_f32 v48, v73, v48, v73
	v_mul_f32_e32 v48, 0xc0135761, v48
	v_exp_f32_e32 v48, v48
	s_nop 0
	v_add_f32_e32 v48, 1.0, v48
	v_rcp_f32_e32 v171, v48
	v_mul_f32_e32 v48, 0x3d372713, v74
	v_mul_f32_e32 v48, v74, v48
	v_fma_f32 v48, v74, v48, v74
	v_mul_f32_e32 v48, 0xc0135761, v48
	v_exp_f32_e32 v48, v48
	v_pk_mul_f32 v[170:171], v[72:73], v[170:171]
	v_add_f32_e32 v48, 1.0, v48
	v_cvt_pk_bf16_f32 v181, v170, v171
	v_rcp_f32_e32 v170, v48
	v_mul_f32_e32 v48, 0x3d372713, v75
	v_mul_f32_e32 v48, v75, v48
	v_fma_f32 v48, v75, v48, v75
	v_mul_f32_e32 v48, 0xc0135761, v48
	v_exp_f32_e32 v48, v48
	global_store_dwordx4 v[162:163], v[178:181], off sc1
	v_add_f32_e32 v48, 1.0, v48
	v_rcp_f32_e32 v171, v48
	v_mul_f32_e32 v48, 0x3d372713, v76
	v_mul_f32_e32 v48, v76, v48
	v_fma_f32 v48, v76, v48, v76
	v_mul_f32_e32 v48, 0xc0135761, v48
	v_exp_f32_e32 v48, v48
	v_pk_mul_f32 v[170:171], v[74:75], v[170:171]
	v_add_f32_e32 v48, 1.0, v48
	v_cvt_pk_bf16_f32 v178, v170, v171
	v_rcp_f32_e32 v170, v48
	v_mul_f32_e32 v48, 0x3d372713, v77
	v_mul_f32_e32 v48, v77, v48
	v_fma_f32 v48, v77, v48, v77
; DI unsigned pk2(float lo, float hi) { f32x2 v = {lo, hi}; bf16v2 r = __builtin_convertvector(v, bf16v2); return __builtin_bit_cast(unsigned, r); }
; DI float geluf_(float x) { const float t = x + 0.044715f * x * x * x; return x * frcp(1.0f + fexp2(-2.3022082f * t)); }
; template <int ACT> DI float act_fn(float x) {
;     ...
;     if (ACT == 3) return geluf_(x);
; template <int ACT> DI void store_act(const f32x4 (&acc)[2][2][4][2], bf16_t* base, int row0, int col0) {
;     ...
;         for (int m = 0; m < 4; ++m) { bf16_t* rowp = base + (size_t)(row0 + ai * 128 + m * 16) * D + col0;
; #pragma unroll
;             for (int bj = 0; bj < 2; ++bj) { const f32x4 v0 = acc[ai][bj][m][0], v1 = acc[ai][bj][m][1];
;                 u32x4 w; w.x = pk2(act_fn<ACT>(v0[0]), act_fn<ACT>(v0[1])); w.y = pk2(act_fn<ACT>(v0[2]), act_fn<ACT>(v0[3]));
;                 w.z = pk2(act_fn<ACT>(v1[0]), act_fn<ACT>(v1[1])); w.w = pk2(act_fn<ACT>(v1[2]), act_fn<ACT>(v1[3]));
;                 *(u32x4*)(rowp + bj * 128) = w; } }
	v_mul_f32_e32 v48, 0xc0135761, v48
	v_exp_f32_e32 v48, v48
	s_nop 0
	v_add_f32_e32 v48, 1.0, v48
	v_rcp_f32_e32 v171, v48
	v_mul_f32_e32 v48, 0x3d372713, v66
	v_mul_f32_e32 v48, v66, v48
	v_fma_f32 v48, v66, v48, v66
	v_mul_f32_e32 v48, 0xc0135761, v48
	v_exp_f32_e32 v48, v48
	v_pk_mul_f32 v[170:171], v[76:77], v[170:171]
	v_add_f32_e32 v48, 1.0, v48
	v_cvt_pk_bf16_f32 v179, v170, v171
	v_rcp_f32_e32 v170, v48
	v_mul_f32_e32 v48, 0x3d372713, v67
	v_mul_f32_e32 v48, v67, v48
	v_fma_f32 v48, v67, v48, v67
	v_mul_f32_e32 v48, 0xc0135761, v48
	v_exp_f32_e32 v48, v48
	s_nop 0
	v_add_f32_e32 v48, 1.0, v48
	v_rcp_f32_e32 v171, v48
	v_mul_f32_e32 v48, 0x3d372713, v68
	v_mul_f32_e32 v48, v68, v48
	v_fma_f32 v48, v68, v48, v68
	v_mul_f32_e32 v48, 0xc0135761, v48
	v_exp_f32_e32 v48, v48
	v_pk_mul_f32 v[170:171], v[66:67], v[170:171]
	v_add_f32_e32 v48, 1.0, v48
	v_cvt_pk_bf16_f32 v180, v170, v171
	v_rcp_f32_e32 v170, v48
	v_mul_f32_e32 v48, 0x3d372713, v69
	v_mul_f32_e32 v48, v69, v48
	v_fma_f32 v48, v69, v48, v69
	v_mul_f32_e32 v48, 0xc0135761, v48
	v_exp_f32_e32 v48, v48
	s_nop 0
	v_add_f32_e32 v48, 1.0, v48
	v_rcp_f32_e32 v171, v48
	v_mul_f32_e32 v48, 0x3d372713, v62
	v_mul_f32_e32 v48, v62, v48
	v_fma_f32 v48, v62, v48, v62
	v_mul_f32_e32 v48, 0xc0135761, v48
	v_exp_f32_e32 v48, v48
	v_pk_mul_f32 v[170:171], v[68:69], v[170:171]
	v_add_f32_e32 v48, 1.0, v48
	v_cvt_pk_bf16_f32 v181, v170, v171
	v_rcp_f32_e32 v170, v48
	v_mul_f32_e32 v48, 0x3d372713, v63
	v_mul_f32_e32 v48, v63, v48
	v_fma_f32 v48, v63, v48, v63
	v_mul_f32_e32 v48, 0xc0135761, v48
	v_exp_f32_e32 v48, v48
	global_store_dwordx4 v[162:163], v[178:181], off offset:256 sc1
	v_lshl_add_u64 v[162:163], v[160:161], 0, s[22:23]
	s_mov_b64 s[22:23], 0x48000
	v_add_f32_e32 v48, 1.0, v48
	v_rcp_f32_e32 v171, v48
	v_mul_f32_e32 v48, 0x3d372713, v64
	v_mul_f32_e32 v48, v64, v48
	v_fma_f32 v48, v64, v48, v64
	v_mul_f32_e32 v48, 0xc0135761, v48
	v_exp_f32_e32 v48, v48
	v_pk_mul_f32 v[170:171], v[62:63], v[170:171]
	v_add_f32_e32 v48, 1.0, v48
	v_cvt_pk_bf16_f32 v178, v170, v171
	v_rcp_f32_e32 v170, v48
	v_mul_f32_e32 v48, 0x3d372713, v65
	v_mul_f32_e32 v48, v65, v48
	v_fma_f32 v48, v65, v48, v65
	v_mul_f32_e32 v48, 0xc0135761, v48
	v_exp_f32_e32 v48, v48
	s_nop 0
	v_add_f32_e32 v48, 1.0, v48
	v_rcp_f32_e32 v171, v48
	v_mul_f32_e32 v48, 0x3d372713, v54
	v_mul_f32_e32 v48, v54, v48
	v_fma_f32 v48, v54, v48, v54
	v_mul_f32_e32 v48, 0xc0135761, v48
	v_exp_f32_e32 v48, v48
	v_pk_mul_f32 v[170:171], v[64:65], v[170:171]
	v_add_f32_e32 v48, 1.0, v48
	v_cvt_pk_bf16_f32 v179, v170, v171
	v_rcp_f32_e32 v170, v48
	v_mul_f32_e32 v48, 0x3d372713, v55
	v_mul_f32_e32 v48, v55, v48
	v_fma_f32 v48, v55, v48, v55
	v_mul_f32_e32 v48, 0xc0135761, v48
	v_exp_f32_e32 v48, v48
	s_nop 0
	v_add_f32_e32 v48, 1.0, v48
	v_rcp_f32_e32 v171, v48
	v_mul_f32_e32 v48, 0x3d372713, v56
	v_mul_f32_e32 v48, v56, v48
	v_fma_f32 v48, v56, v48, v56
	v_mul_f32_e32 v48, 0xc0135761, v48
	v_exp_f32_e32 v48, v48
	v_pk_mul_f32 v[170:171], v[54:55], v[170:171]
	v_add_f32_e32 v48, 1.0, v48
	v_cvt_pk_bf16_f32 v180, v170, v171
	v_rcp_f32_e32 v170, v48
	v_mul_f32_e32 v48, 0x3d372713, v57
	v_mul_f32_e32 v48, v57, v48
	v_fma_f32 v48, v57, v48, v57
	v_mul_f32_e32 v48, 0xc0135761, v48
	v_exp_f32_e32 v48, v48
	s_nop 0
	v_add_f32_e32 v48, 1.0, v48
	v_rcp_f32_e32 v171, v48
	v_mul_f32_e32 v48, 0x3d372713, v58
	v_mul_f32_e32 v48, v58, v48
	v_fma_f32 v48, v58, v48, v58
	v_mul_f32_e32 v48, 0xc0135761, v48
	v_exp_f32_e32 v48, v48
	v_pk_mul_f32 v[170:171], v[56:57], v[170:171]
	v_add_f32_e32 v48, 1.0, v48
	v_cvt_pk_bf16_f32 v181, v170, v171
	v_add_co_u32_e32 v170, vcc, s15, v160
	s_mov_b32 s15, 0x48000
	s_nop 0
	v_addc_co_u32_e32 v171, vcc, 0, v161, vcc
	global_store_dwordx4 v[170:171], v[178:181], off sc1
	v_rcp_f32_e32 v170, v48
	v_mul_f32_e32 v48, 0x3d372713, v59
	v_mul_f32_e32 v48, v59, v48
	v_fma_f32 v48, v59, v48, v59
	v_mul_f32_e32 v48, 0xc0135761, v48
	v_exp_f32_e32 v48, v48
	s_nop 0
	v_add_f32_e32 v48, 1.0, v48
	v_rcp_f32_e32 v171, v48
	v_mul_f32_e32 v48, 0x3d372713, v60
	v_mul_f32_e32 v48, v60, v48
	v_fma_f32 v48, v60, v48, v60
	v_mul_f32_e32 v48, 0xc0135761, v48
	v_exp_f32_e32 v48, v48
	v_pk_mul_f32 v[170:171], v[58:59], v[170:171]
	v_add_f32_e32 v48, 1.0, v48
	v_cvt_pk_bf16_f32 v178, v170, v171
	v_rcp_f32_e32 v170, v48
	v_mul_f32_e32 v48, 0x3d372713, v61
	v_mul_f32_e32 v48, v61, v48
	v_fma_f32 v48, v61, v48, v61
	v_mul_f32_e32 v48, 0xc0135761, v48
	v_exp_f32_e32 v48, v48
	s_nop 0
	v_add_f32_e32 v48, 1.0, v48
	v_rcp_f32_e32 v171, v48
	v_mul_f32_e32 v48, 0x3d372713, v50
	v_mul_f32_e32 v48, v50, v48
	v_fma_f32 v48, v50, v48, v50
	v_mul_f32_e32 v48, 0xc0135761, v48
	v_exp_f32_e32 v48, v48
	v_pk_mul_f32 v[170:171], v[60:61], v[170:171]
	v_add_f32_e32 v48, 1.0, v48
	v_cvt_pk_bf16_f32 v179, v170, v171
	v_rcp_f32_e32 v170, v48
	v_mul_f32_e32 v48, 0x3d372713, v51
	v_mul_f32_e32 v48, v51, v48
	v_fma_f32 v48, v51, v48, v51
	v_mul_f32_e32 v48, 0xc0135761, v48
	v_exp_f32_e32 v48, v48
	s_nop 0
	v_add_f32_e32 v48, 1.0, v48
	v_rcp_f32_e32 v171, v48
	v_mul_f32_e32 v48, 0x3d372713, v52
	v_mul_f32_e32 v48, v52, v48
	v_fma_f32 v48, v52, v48, v52
	v_mul_f32_e32 v48, 0xc0135761, v48
	v_exp_f32_e32 v48, v48
	v_pk_mul_f32 v[170:171], v[50:51], v[170:171]
	v_add_f32_e32 v48, 1.0, v48
	v_cvt_pk_bf16_f32 v180, v170, v171
	v_rcp_f32_e32 v170, v48
	v_mul_f32_e32 v48, 0x3d372713, v53
	v_mul_f32_e32 v48, v53, v48
	v_fma_f32 v48, v53, v48, v53
	v_mul_f32_e32 v48, 0xc0135761, v48
	v_exp_f32_e32 v48, v48
	s_nop 0
	v_add_f32_e32 v48, 1.0, v48
	v_rcp_f32_e32 v171, v48
	v_mul_f32_e32 v48, 0x3d372713, v44
	v_mul_f32_e32 v48, v44, v48
	v_fma_f32 v48, v44, v48, v44
; DI unsigned pk2(float lo, float hi) { f32x2 v = {lo, hi}; bf16v2 r = __builtin_convertvector(v, bf16v2); return __builtin_bit_cast(unsigned, r); }
; DI float geluf_(float x) { const float t = x + 0.044715f * x * x * x; return x * frcp(1.0f + fexp2(-2.3022082f * t)); }
; template <int ACT> DI float act_fn(float x) {
;     ...
;     if (ACT == 3) return geluf_(x);
; template <int ACT> DI void store_act(const f32x4 (&acc)[2][2][4][2], bf16_t* base, int row0, int col0) {
;     ...
;         for (int m = 0; m < 4; ++m) { bf16_t* rowp = base + (size_t)(row0 + ai * 128 + m * 16) * D + col0;
; #pragma unroll
;             for (int bj = 0; bj < 2; ++bj) { const f32x4 v0 = acc[ai][bj][m][0], v1 = acc[ai][bj][m][1];
;                 u32x4 w; w.x = pk2(act_fn<ACT>(v0[0]), act_fn<ACT>(v0[1])); w.y = pk2(act_fn<ACT>(v0[2]), act_fn<ACT>(v0[3]));
;                 w.z = pk2(act_fn<ACT>(v1[0]), act_fn<ACT>(v1[1])); w.w = pk2(act_fn<ACT>(v1[2]), act_fn<ACT>(v1[3]));
;                 *(u32x4*)(rowp + bj * 128) = w; } }
	v_mul_f32_e32 v48, 0xc0135761, v48
	v_exp_f32_e32 v48, v48
	v_pk_mul_f32 v[170:171], v[52:53], v[170:171]
	v_add_f32_e32 v48, 1.0, v48
	v_cvt_pk_bf16_f32 v181, v170, v171
	v_rcp_f32_e32 v170, v48
	v_mul_f32_e32 v48, 0x3d372713, v45
	v_mul_f32_e32 v48, v45, v48
	v_fma_f32 v48, v45, v48, v45
	v_mul_f32_e32 v48, 0xc0135761, v48
	v_exp_f32_e32 v48, v48
	global_store_dwordx4 v[162:163], v[178:181], off offset:256 sc1
	v_lshl_add_u64 v[162:163], v[160:161], 0, s[22:23]
	s_mov_b64 s[22:23], 0x50000
	v_add_f32_e32 v48, 1.0, v48
	v_rcp_f32_e32 v171, v48
	v_mul_f32_e32 v48, 0x3d372713, v46
	v_mul_f32_e32 v48, v46, v48
	v_fma_f32 v48, v46, v48, v46
	v_mul_f32_e32 v48, 0xc0135761, v48
	v_exp_f32_e32 v48, v48
	v_pk_mul_f32 v[170:171], v[44:45], v[170:171]
	v_add_f32_e32 v48, 1.0, v48
	v_cvt_pk_bf16_f32 v178, v170, v171
	v_rcp_f32_e32 v170, v48
	v_mul_f32_e32 v48, 0x3d372713, v47
	v_mul_f32_e32 v48, v47, v48
	v_fma_f32 v48, v47, v48, v47
	v_mul_f32_e32 v48, 0xc0135761, v48
	v_exp_f32_e32 v48, v48
	s_nop 0
	v_add_f32_e32 v48, 1.0, v48
	v_rcp_f32_e32 v171, v48
	v_mul_f32_e32 v48, 0x3d372713, v36
	v_mul_f32_e32 v48, v36, v48
	v_fma_f32 v48, v36, v48, v36
	v_mul_f32_e32 v48, 0xc0135761, v48
	v_exp_f32_e32 v48, v48
	v_pk_mul_f32 v[170:171], v[46:47], v[170:171]
	v_add_f32_e32 v48, 1.0, v48
	v_cvt_pk_bf16_f32 v179, v170, v171
	v_rcp_f32_e32 v170, v48
	v_mul_f32_e32 v48, 0x3d372713, v37
	v_mul_f32_e32 v48, v37, v48
	v_fma_f32 v48, v37, v48, v37
	v_mul_f32_e32 v48, 0xc0135761, v48
	v_exp_f32_e32 v48, v48
	s_nop 0
	v_add_f32_e32 v48, 1.0, v48
	v_rcp_f32_e32 v171, v48
	v_mul_f32_e32 v48, 0x3d372713, v38
	v_mul_f32_e32 v48, v38, v48
	v_fma_f32 v48, v38, v48, v38
	v_mul_f32_e32 v48, 0xc0135761, v48
	v_exp_f32_e32 v48, v48
	v_pk_mul_f32 v[170:171], v[36:37], v[170:171]
	v_add_f32_e32 v48, 1.0, v48
	v_cvt_pk_bf16_f32 v180, v170, v171
	v_rcp_f32_e32 v170, v48
	v_mul_f32_e32 v48, 0x3d372713, v39
	v_mul_f32_e32 v48, v39, v48
	v_fma_f32 v48, v39, v48, v39
	v_mul_f32_e32 v48, 0xc0135761, v48
	v_exp_f32_e32 v48, v48
	s_nop 0
	v_add_f32_e32 v48, 1.0, v48
	v_rcp_f32_e32 v171, v48
	v_mul_f32_e32 v48, 0x3d372713, v40
	v_mul_f32_e32 v48, v40, v48
	v_fma_f32 v48, v40, v48, v40
	v_mul_f32_e32 v48, 0xc0135761, v48
	v_exp_f32_e32 v48, v48
	v_pk_mul_f32 v[170:171], v[38:39], v[170:171]
	v_add_f32_e32 v48, 1.0, v48
	v_cvt_pk_bf16_f32 v181, v170, v171
	v_add_co_u32_e32 v170, vcc, s15, v160
	s_mov_b32 s15, 0x50000
	s_nop 0
	v_addc_co_u32_e32 v171, vcc, 0, v161, vcc
	global_store_dwordx4 v[170:171], v[178:181], off sc1
	v_rcp_f32_e32 v170, v48
	v_mul_f32_e32 v48, 0x3d372713, v41
	v_mul_f32_e32 v48, v41, v48
	v_fma_f32 v48, v41, v48, v41
	v_mul_f32_e32 v48, 0xc0135761, v48
	v_exp_f32_e32 v48, v48
	s_nop 0
	v_add_f32_e32 v48, 1.0, v48
	v_rcp_f32_e32 v171, v48
	v_mul_f32_e32 v48, 0x3d372713, v42
	v_mul_f32_e32 v48, v42, v48
	v_fma_f32 v48, v42, v48, v42
	v_mul_f32_e32 v48, 0xc0135761, v48
	v_exp_f32_e32 v48, v48
	v_pk_mul_f32 v[170:171], v[40:41], v[170:171]
	v_add_f32_e32 v48, 1.0, v48
	v_cvt_pk_bf16_f32 v178, v170, v171
	v_rcp_f32_e32 v170, v48
	v_mul_f32_e32 v48, 0x3d372713, v43
	v_mul_f32_e32 v48, v43, v48
	v_fma_f32 v48, v43, v48, v43
	v_mul_f32_e32 v48, 0xc0135761, v48
	v_exp_f32_e32 v48, v48
	s_nop 0
	v_add_f32_e32 v48, 1.0, v48
	v_rcp_f32_e32 v171, v48
	v_mul_f32_e32 v48, 0x3d372713, v32
	v_mul_f32_e32 v48, v32, v48
	v_fma_f32 v48, v32, v48, v32
	v_mul_f32_e32 v48, 0xc0135761, v48
	v_exp_f32_e32 v48, v48
	v_pk_mul_f32 v[170:171], v[42:43], v[170:171]
	v_add_f32_e32 v48, 1.0, v48
	v_cvt_pk_bf16_f32 v179, v170, v171
	v_rcp_f32_e32 v170, v48
	v_mul_f32_e32 v48, 0x3d372713, v33
	v_mul_f32_e32 v48, v33, v48
	v_fma_f32 v48, v33, v48, v33
	v_mul_f32_e32 v48, 0xc0135761, v48
	v_exp_f32_e32 v48, v48
	s_nop 0
	v_add_f32_e32 v48, 1.0, v48
	v_rcp_f32_e32 v171, v48
	v_mul_f32_e32 v48, 0x3d372713, v34
	v_mul_f32_e32 v48, v34, v48
	v_fma_f32 v48, v34, v48, v34
	v_mul_f32_e32 v48, 0xc0135761, v48
	v_exp_f32_e32 v48, v48
	v_pk_mul_f32 v[170:171], v[32:33], v[170:171]
	v_add_f32_e32 v48, 1.0, v48
	v_cvt_pk_bf16_f32 v180, v170, v171
	v_rcp_f32_e32 v170, v48
	v_mul_f32_e32 v48, 0x3d372713, v35
	v_mul_f32_e32 v48, v35, v48
	v_fma_f32 v48, v35, v48, v35
	v_mul_f32_e32 v48, 0xc0135761, v48
	v_exp_f32_e32 v48, v48
	s_nop 0
	v_add_f32_e32 v48, 1.0, v48
	v_rcp_f32_e32 v171, v48
	v_mul_f32_e32 v48, 0x3d372713, v28
	v_mul_f32_e32 v48, v28, v48
	v_fma_f32 v48, v28, v48, v28
	v_mul_f32_e32 v48, 0xc0135761, v48
	v_exp_f32_e32 v48, v48
	v_pk_mul_f32 v[170:171], v[34:35], v[170:171]
	v_add_f32_e32 v48, 1.0, v48
	v_cvt_pk_bf16_f32 v181, v170, v171
	v_rcp_f32_e32 v170, v48
	v_mul_f32_e32 v48, 0x3d372713, v29
	v_mul_f32_e32 v48, v29, v48
	v_fma_f32 v48, v29, v48, v29
	v_mul_f32_e32 v48, 0xc0135761, v48
	v_exp_f32_e32 v48, v48
	global_store_dwordx4 v[162:163], v[178:181], off offset:256 sc1
	v_lshl_add_u64 v[162:163], v[160:161], 0, s[22:23]
	s_mov_b64 s[22:23], 0x58000
	v_add_f32_e32 v48, 1.0, v48
	v_rcp_f32_e32 v171, v48
	v_mul_f32_e32 v48, 0x3d372713, v30
	v_mul_f32_e32 v48, v30, v48
	v_fma_f32 v48, v30, v48, v30
	v_mul_f32_e32 v48, 0xc0135761, v48
	v_exp_f32_e32 v48, v48
	v_pk_mul_f32 v[170:171], v[28:29], v[170:171]
	v_add_f32_e32 v48, 1.0, v48
	v_cvt_pk_bf16_f32 v178, v170, v171
	v_rcp_f32_e32 v170, v48
	v_mul_f32_e32 v48, 0x3d372713, v31
	v_mul_f32_e32 v48, v31, v48
	v_fma_f32 v48, v31, v48, v31
	v_mul_f32_e32 v48, 0xc0135761, v48
	v_exp_f32_e32 v48, v48
	s_nop 0
	v_add_f32_e32 v48, 1.0, v48
	v_rcp_f32_e32 v171, v48
	v_mul_f32_e32 v48, 0x3d372713, v20
	v_mul_f32_e32 v48, v20, v48
	v_fma_f32 v48, v20, v48, v20
	v_mul_f32_e32 v48, 0xc0135761, v48
	v_exp_f32_e32 v48, v48
	v_pk_mul_f32 v[170:171], v[30:31], v[170:171]
; DI unsigned pk2(float lo, float hi) { f32x2 v = {lo, hi}; bf16v2 r = __builtin_convertvector(v, bf16v2); return __builtin_bit_cast(unsigned, r); }
; DI float geluf_(float x) { const float t = x + 0.044715f * x * x * x; return x * frcp(1.0f + fexp2(-2.3022082f * t)); }
; template <int ACT> DI float act_fn(float x) {
;     ...
;     if (ACT == 3) return geluf_(x);
; template <int ACT> DI void store_act(const f32x4 (&acc)[2][2][4][2], bf16_t* base, int row0, int col0) {
;     ...
;         for (int m = 0; m < 4; ++m) { bf16_t* rowp = base + (size_t)(row0 + ai * 128 + m * 16) * D + col0;
; #pragma unroll
;             for (int bj = 0; bj < 2; ++bj) { const f32x4 v0 = acc[ai][bj][m][0], v1 = acc[ai][bj][m][1];
;                 u32x4 w; w.x = pk2(act_fn<ACT>(v0[0]), act_fn<ACT>(v0[1])); w.y = pk2(act_fn<ACT>(v0[2]), act_fn<ACT>(v0[3]));
;                 w.z = pk2(act_fn<ACT>(v1[0]), act_fn<ACT>(v1[1])); w.w = pk2(act_fn<ACT>(v1[2]), act_fn<ACT>(v1[3]));
;                 *(u32x4*)(rowp + bj * 128) = w; } }
	v_add_f32_e32 v48, 1.0, v48
	v_cvt_pk_bf16_f32 v179, v170, v171
	v_rcp_f32_e32 v170, v48
	v_mul_f32_e32 v48, 0x3d372713, v21
	v_mul_f32_e32 v48, v21, v48
	v_fma_f32 v48, v21, v48, v21
	v_mul_f32_e32 v48, 0xc0135761, v48
	v_exp_f32_e32 v48, v48
	s_nop 0
	v_add_f32_e32 v48, 1.0, v48
	v_rcp_f32_e32 v171, v48
	v_mul_f32_e32 v48, 0x3d372713, v22
	v_mul_f32_e32 v48, v22, v48
	v_fma_f32 v48, v22, v48, v22
	v_mul_f32_e32 v48, 0xc0135761, v48
	v_exp_f32_e32 v48, v48
	v_pk_mul_f32 v[170:171], v[20:21], v[170:171]
	v_add_f32_e32 v48, 1.0, v48
	v_cvt_pk_bf16_f32 v180, v170, v171
	v_rcp_f32_e32 v170, v48
	v_mul_f32_e32 v48, 0x3d372713, v23
	v_mul_f32_e32 v48, v23, v48
	v_fma_f32 v48, v23, v48, v23
	v_mul_f32_e32 v48, 0xc0135761, v48
	v_exp_f32_e32 v48, v48
	s_nop 0
	v_add_f32_e32 v48, 1.0, v48
	v_rcp_f32_e32 v171, v48
	v_mul_f32_e32 v48, 0x3d372713, v24
	v_mul_f32_e32 v48, v24, v48
	v_fma_f32 v48, v24, v48, v24
	v_mul_f32_e32 v48, 0xc0135761, v48
	v_exp_f32_e32 v48, v48
	v_pk_mul_f32 v[170:171], v[22:23], v[170:171]
	v_add_f32_e32 v48, 1.0, v48
	v_cvt_pk_bf16_f32 v181, v170, v171
	v_add_co_u32_e32 v170, vcc, s15, v160
	s_mov_b32 s15, 0x58000
	s_nop 0
	v_addc_co_u32_e32 v171, vcc, 0, v161, vcc
	global_store_dwordx4 v[170:171], v[178:181], off sc1
	v_rcp_f32_e32 v170, v48
	v_mul_f32_e32 v48, 0x3d372713, v25
	v_mul_f32_e32 v48, v25, v48
	v_fma_f32 v48, v25, v48, v25
	v_mul_f32_e32 v48, 0xc0135761, v48
	v_exp_f32_e32 v48, v48
	s_nop 0
	v_add_f32_e32 v48, 1.0, v48
	v_rcp_f32_e32 v171, v48
	v_mul_f32_e32 v48, 0x3d372713, v26
	v_mul_f32_e32 v48, v26, v48
	v_fma_f32 v48, v26, v48, v26
	v_mul_f32_e32 v48, 0xc0135761, v48
	v_exp_f32_e32 v48, v48
	v_pk_mul_f32 v[170:171], v[24:25], v[170:171]
	v_add_f32_e32 v48, 1.0, v48
	v_cvt_pk_bf16_f32 v178, v170, v171
	v_rcp_f32_e32 v170, v48
	v_mul_f32_e32 v48, 0x3d372713, v27
	v_mul_f32_e32 v48, v27, v48
	v_fma_f32 v48, v27, v48, v27
	v_mul_f32_e32 v48, 0xc0135761, v48
	v_exp_f32_e32 v48, v48
	s_nop 0
	v_add_f32_e32 v48, 1.0, v48
	v_rcp_f32_e32 v171, v48
	v_mul_f32_e32 v48, 0x3d372713, v16
	v_mul_f32_e32 v48, v16, v48
	v_fma_f32 v48, v16, v48, v16
	v_mul_f32_e32 v48, 0xc0135761, v48
	v_exp_f32_e32 v48, v48
	v_pk_mul_f32 v[170:171], v[26:27], v[170:171]
	v_add_f32_e32 v48, 1.0, v48
	v_cvt_pk_bf16_f32 v179, v170, v171
	v_rcp_f32_e32 v170, v48
	v_mul_f32_e32 v48, 0x3d372713, v17
	v_mul_f32_e32 v48, v17, v48
	v_fma_f32 v48, v17, v48, v17
	v_mul_f32_e32 v48, 0xc0135761, v48
	v_exp_f32_e32 v48, v48
	s_nop 0
	v_add_f32_e32 v48, 1.0, v48
	v_rcp_f32_e32 v171, v48
	v_mul_f32_e32 v48, 0x3d372713, v18
	v_mul_f32_e32 v48, v18, v48
	v_fma_f32 v48, v18, v48, v18
	v_mul_f32_e32 v48, 0xc0135761, v48
	v_exp_f32_e32 v48, v48
	v_pk_mul_f32 v[170:171], v[16:17], v[170:171]
	v_add_f32_e32 v48, 1.0, v48
	v_cvt_pk_bf16_f32 v180, v170, v171
	v_rcp_f32_e32 v170, v48
	v_mul_f32_e32 v48, 0x3d372713, v19
	v_mul_f32_e32 v48, v19, v48
	v_fma_f32 v48, v19, v48, v19
	v_mul_f32_e32 v48, 0xc0135761, v48
	v_exp_f32_e32 v48, v48
	s_nop 0
	v_add_f32_e32 v48, 1.0, v48
	v_rcp_f32_e32 v171, v48
	v_mul_f32_e32 v48, 0x3d372713, v12
	v_mul_f32_e32 v48, v12, v48
	v_fma_f32 v48, v12, v48, v12
	v_mul_f32_e32 v48, 0xc0135761, v48
	v_exp_f32_e32 v48, v48
	v_pk_mul_f32 v[170:171], v[18:19], v[170:171]
	v_add_f32_e32 v48, 1.0, v48
	v_cvt_pk_bf16_f32 v181, v170, v171
	v_rcp_f32_e32 v170, v48
	v_mul_f32_e32 v48, 0x3d372713, v13
	v_mul_f32_e32 v48, v13, v48
	v_fma_f32 v48, v13, v48, v13
	v_mul_f32_e32 v48, 0xc0135761, v48
	v_exp_f32_e32 v48, v48
	global_store_dwordx4 v[162:163], v[178:181], off offset:256 sc1
	v_lshl_add_u64 v[162:163], v[160:161], 0, s[22:23]
	s_mov_b64 s[22:23], 0
	v_add_f32_e32 v48, 1.0, v48
	v_rcp_f32_e32 v171, v48
	v_mul_f32_e32 v48, 0x3d372713, v14
	v_mul_f32_e32 v48, v14, v48
	v_fma_f32 v48, v14, v48, v14
	v_mul_f32_e32 v48, 0xc0135761, v48
	v_exp_f32_e32 v48, v48
	v_pk_mul_f32 v[170:171], v[12:13], v[170:171]
	v_add_f32_e32 v48, 1.0, v48
	v_cvt_pk_bf16_f32 v178, v170, v171
	v_rcp_f32_e32 v170, v48
	v_mul_f32_e32 v48, 0x3d372713, v15
	v_mul_f32_e32 v48, v15, v48
	v_fma_f32 v48, v15, v48, v15
	v_mul_f32_e32 v48, 0xc0135761, v48
	v_exp_f32_e32 v48, v48
	s_nop 0
	v_add_f32_e32 v48, 1.0, v48
	v_rcp_f32_e32 v171, v48
	v_mul_f32_e32 v48, 0x3d372713, v4
	v_mul_f32_e32 v48, v4, v48
	v_fma_f32 v48, v4, v48, v4
	v_mul_f32_e32 v48, 0xc0135761, v48
	v_exp_f32_e32 v48, v48
	v_pk_mul_f32 v[170:171], v[14:15], v[170:171]
	v_add_f32_e32 v48, 1.0, v48
	v_cvt_pk_bf16_f32 v179, v170, v171
	v_rcp_f32_e32 v170, v48
	v_mul_f32_e32 v48, 0x3d372713, v5
	v_mul_f32_e32 v48, v5, v48
	v_fma_f32 v48, v5, v48, v5
	v_mul_f32_e32 v48, 0xc0135761, v48
	v_exp_f32_e32 v48, v48
	s_nop 0
	v_add_f32_e32 v48, 1.0, v48
	v_rcp_f32_e32 v171, v48
	v_mul_f32_e32 v48, 0x3d372713, v6
	v_mul_f32_e32 v48, v6, v48
	v_fma_f32 v48, v6, v48, v6
	v_mul_f32_e32 v48, 0xc0135761, v48
	v_exp_f32_e32 v48, v48
	v_pk_mul_f32 v[170:171], v[4:5], v[170:171]
	v_add_f32_e32 v48, 1.0, v48
	v_cvt_pk_bf16_f32 v180, v170, v171
	v_rcp_f32_e32 v170, v48
	v_mul_f32_e32 v48, 0x3d372713, v7
	v_mul_f32_e32 v48, v7, v48
	v_fma_f32 v48, v7, v48, v7
	v_mul_f32_e32 v48, 0xc0135761, v48
	v_exp_f32_e32 v48, v48
	s_nop 0
	v_add_f32_e32 v48, 1.0, v48
	v_rcp_f32_e32 v171, v48
	v_mul_f32_e32 v48, 0x3d372713, v8
	v_mul_f32_e32 v48, v8, v48
	v_fma_f32 v48, v8, v48, v8
	v_mul_f32_e32 v48, 0xc0135761, v48
	v_exp_f32_e32 v48, v48
	v_pk_mul_f32 v[170:171], v[6:7], v[170:171]
	v_add_f32_e32 v48, 1.0, v48
	v_cvt_pk_bf16_f32 v181, v170, v171
	v_add_co_u32_e32 v170, vcc, s15, v160
	s_nop 1
	v_addc_co_u32_e32 v171, vcc, 0, v161, vcc
	global_store_dwordx4 v[170:171], v[178:181], off sc1
	v_rcp_f32_e32 v170, v48
	v_mul_f32_e32 v48, 0x3d372713, v9
; DI unsigned pk2(float lo, float hi) { f32x2 v = {lo, hi}; bf16v2 r = __builtin_convertvector(v, bf16v2); return __builtin_bit_cast(unsigned, r); }
; template <int ACT> DI void store_act(const f32x4 (&acc)[2][2][4][2], bf16_t* base, int row0, int col0) {
;     ...
;         for (int m = 0; m < 4; ++m) { bf16_t* rowp = base + (size_t)(row0 + ai * 128 + m * 16) * D + col0;
; #pragma unroll
;             for (int bj = 0; bj < 2; ++bj) { const f32x4 v0 = acc[ai][bj][m][0], v1 = acc[ai][bj][m][1];
;                 u32x4 w; w.x = pk2(act_fn<ACT>(v0[0]), act_fn<ACT>(v0[1])); w.y = pk2(act_fn<ACT>(v0[2]), act_fn<ACT>(v0[3]));
;                 w.z = pk2(act_fn<ACT>(v1[0]), act_fn<ACT>(v1[1])); w.w = pk2(act_fn<ACT>(v1[2]), act_fn<ACT>(v1[3]));
;                 *(u32x4*)(rowp + bj * 128) = w; } }
	v_mul_f32_e32 v48, v9, v48
	v_fma_f32 v48, v9, v48, v9
	v_mul_f32_e32 v48, 0xc0135761, v48
	v_exp_f32_e32 v48, v48
	s_nop 0
	v_add_f32_e32 v48, 1.0, v48
	v_rcp_f32_e32 v171, v48
	v_mul_f32_e32 v48, 0x3d372713, v10
	v_mul_f32_e32 v48, v10, v48
	v_fma_f32 v48, v10, v48, v10
	v_mul_f32_e32 v48, 0xc0135761, v48
	v_exp_f32_e32 v48, v48
	v_pk_mul_f32 v[170:171], v[8:9], v[170:171]
	v_add_f32_e32 v48, 1.0, v48
	v_cvt_pk_bf16_f32 v178, v170, v171
	v_rcp_f32_e32 v170, v48
	v_mul_f32_e32 v48, 0x3d372713, v11
	v_mul_f32_e32 v48, v11, v48
	v_fma_f32 v48, v11, v48, v11
	v_mul_f32_e32 v48, 0xc0135761, v48
	v_exp_f32_e32 v48, v48
	s_nop 0
	v_add_f32_e32 v48, 1.0, v48
	v_rcp_f32_e32 v171, v48
	v_mul_f32_e32 v48, 0x3d372713, v0
	v_mul_f32_e32 v48, v0, v48
	v_fma_f32 v48, v0, v48, v0
	v_mul_f32_e32 v48, 0xc0135761, v48
	v_exp_f32_e32 v48, v48
	v_pk_mul_f32 v[170:171], v[10:11], v[170:171]
	v_add_f32_e32 v48, 1.0, v48
	v_cvt_pk_bf16_f32 v179, v170, v171
	v_rcp_f32_e32 v170, v48
	v_mul_f32_e32 v48, 0x3d372713, v1
	v_mul_f32_e32 v48, v1, v48
	v_fma_f32 v48, v1, v48, v1
	v_mul_f32_e32 v48, 0xc0135761, v48
	v_exp_f32_e32 v48, v48
	s_nop 0
	v_add_f32_e32 v48, 1.0, v48
	v_rcp_f32_e32 v171, v48
	v_mul_f32_e32 v48, 0x3d372713, v2
	v_mul_f32_e32 v48, v2, v48
	v_fma_f32 v48, v2, v48, v2
	v_mul_f32_e32 v48, 0xc0135761, v48
	v_exp_f32_e32 v48, v48
	v_pk_mul_f32 v[170:171], v[0:1], v[170:171]
	v_add_f32_e32 v48, 1.0, v48
	v_cvt_pk_bf16_f32 v180, v170, v171
	v_rcp_f32_e32 v170, v48
	v_mul_f32_e32 v48, 0x3d372713, v3
	v_mul_f32_e32 v48, v3, v48
	v_fma_f32 v48, v3, v48, v3
	v_mul_f32_e32 v48, 0xc0135761, v48
	v_exp_f32_e32 v48, v48
	s_nop 0
	v_add_f32_e32 v48, 1.0, v48
	v_rcp_f32_e32 v171, v48
	s_nop 0
	v_pk_mul_f32 v[170:171], v[2:3], v[170:171]
	s_nop 0
	v_cvt_pk_bf16_f32 v181, v170, v171
	global_store_dwordx4 v[162:163], v[178:181], off offset:256 sc1
.LBB0_249:
	s_andn2_b64 vcc, exec, s[22:23]
	s_cbranch_vccnz .LBB0_251
	v_cvt_pk_bf16_f32 v178, v126, v127
	v_cvt_pk_bf16_f32 v179, v128, v129
	v_cvt_pk_bf16_f32 v180, v118, v119
	v_cvt_pk_bf16_f32 v181, v120, v121
	global_store_dwordx4 v[160:161], v[178:181], off sc1
	v_cvt_pk_bf16_f32 v162, v102, v103
	v_cvt_pk_bf16_f32 v163, v104, v105
	v_cvt_pk_bf16_f32 v178, v122, v123
	v_cvt_pk_bf16_f32 v179, v124, v125
	v_cvt_pk_bf16_f32 v180, v114, v115
	v_cvt_pk_bf16_f32 v181, v116, v117
	global_store_dwordx4 v[160:161], v[178:181], off offset:256 sc1
	v_or_b32_e32 v160, 16, v154
	v_ashrrev_i32_e32 v161, 31, v160
	v_lshlrev_b64 v[160:161], 11, v[160:161]
	v_lshl_add_u64 v[170:171], v[158:159], 0, v[160:161]
	v_cvt_pk_bf16_f32 v160, v110, v111
	v_cvt_pk_bf16_f32 v161, v112, v113
	global_store_dwordx4 v[170:171], v[160:163], off sc1
	s_mov_b32 s15, 0x40000
	s_mov_b64 s[22:23], 0x40000
	v_cvt_pk_bf16_f32 v160, v106, v107
	v_cvt_pk_bf16_f32 v161, v108, v109
	v_cvt_pk_bf16_f32 v162, v98, v99
	v_cvt_pk_bf16_f32 v163, v100, v101
	global_store_dwordx4 v[170:171], v[160:163], off offset:256 sc1
	s_nop 1
	v_or_b32_e32 v160, 32, v154
	v_ashrrev_i32_e32 v161, 31, v160
	v_lshlrev_b64 v[160:161], 11, v[160:161]
	v_lshl_add_u64 v[170:171], v[158:159], 0, v[160:161]
	v_cvt_pk_bf16_f32 v160, v94, v95
	v_cvt_pk_bf16_f32 v161, v96, v97
	v_cvt_pk_bf16_f32 v162, v86, v87
	v_cvt_pk_bf16_f32 v163, v88, v89
	global_store_dwordx4 v[170:171], v[160:163], off sc1
	s_nop 1
	v_cvt_pk_bf16_f32 v160, v90, v91
	v_cvt_pk_bf16_f32 v161, v92, v93
	v_cvt_pk_bf16_f32 v162, v82, v83
	v_cvt_pk_bf16_f32 v163, v84, v85
	global_store_dwordx4 v[170:171], v[160:163], off offset:256 sc1
	s_nop 1
	v_or_b32_e32 v160, 48, v154
	v_ashrrev_i32_e32 v161, 31, v160
	v_lshlrev_b64 v[160:161], 11, v[160:161]
	v_lshl_add_u64 v[170:171], v[158:159], 0, v[160:161]
	v_cvt_pk_bf16_f32 v160, v78, v79
	v_cvt_pk_bf16_f32 v161, v80, v81
	v_cvt_pk_bf16_f32 v162, v70, v71
	v_cvt_pk_bf16_f32 v163, v72, v73
	global_store_dwordx4 v[170:171], v[160:163], off sc1
	s_nop 1
	v_cvt_pk_bf16_f32 v160, v74, v75
	v_cvt_pk_bf16_f32 v161, v76, v77
	v_cvt_pk_bf16_f32 v162, v66, v67
	v_cvt_pk_bf16_f32 v163, v68, v69
	global_store_dwordx4 v[170:171], v[160:163], off offset:256 sc1
	s_nop 1
	v_lshlrev_b64 v[160:161], 11, v[154:155]
	v_lshl_add_u64 v[162:163], v[158:159], 0, v[160:161]
	v_add_co_u32_e32 v178, vcc, s15, v162
	v_cvt_pk_bf16_f32 v158, v62, v63
	v_cvt_pk_bf16_f32 v159, v64, v65
	v_cvt_pk_bf16_f32 v160, v54, v55
	v_cvt_pk_bf16_f32 v161, v56, v57
	v_addc_co_u32_e32 v179, vcc, 0, v163, vcc
	s_mov_b32 s15, 0x48000
	v_lshl_add_u64 v[170:171], v[162:163], 0, s[22:23]
	global_store_dwordx4 v[178:179], v[158:161], off sc1
	v_add_co_u32_e32 v178, vcc, s15, v162
	s_nop 0
	v_cvt_pk_bf16_f32 v158, v58, v59
	v_cvt_pk_bf16_f32 v159, v60, v61
	v_cvt_pk_bf16_f32 v160, v50, v51
	v_cvt_pk_bf16_f32 v161, v52, v53
	global_store_dwordx4 v[170:171], v[158:161], off offset:256 sc1
	s_mov_b64 s[22:23], 0x48000
	v_addc_co_u32_e32 v179, vcc, 0, v163, vcc
	v_cvt_pk_bf16_f32 v158, v44, v45
	v_cvt_pk_bf16_f32 v159, v46, v47
	v_cvt_pk_bf16_f32 v160, v36, v37
	v_cvt_pk_bf16_f32 v161, v38, v39
	s_mov_b32 s15, 0x50000
	v_lshl_add_u64 v[170:171], v[162:163], 0, s[22:23]
	global_store_dwordx4 v[178:179], v[158:161], off sc1
	v_add_co_u32_e32 v178, vcc, s15, v162
	s_nop 0
	v_cvt_pk_bf16_f32 v158, v40, v41
	v_cvt_pk_bf16_f32 v159, v42, v43
	v_cvt_pk_bf16_f32 v160, v32, v33
	v_cvt_pk_bf16_f32 v161, v34, v35
	global_store_dwordx4 v[170:171], v[158:161], off offset:256 sc1
	s_mov_b64 s[22:23], 0x50000
	v_addc_co_u32_e32 v179, vcc, 0, v163, vcc
	v_cvt_pk_bf16_f32 v158, v28, v29
	v_cvt_pk_bf16_f32 v159, v30, v31
	v_cvt_pk_bf16_f32 v160, v20, v21
	v_cvt_pk_bf16_f32 v161, v22, v23
	v_lshl_add_u64 v[170:171], v[162:163], 0, s[22:23]
	global_store_dwordx4 v[178:179], v[158:161], off sc1
	s_mov_b64 s[22:23], 0x58000
	s_mov_b32 s15, 0x58000
	v_cvt_pk_bf16_f32 v158, v24, v25
	v_cvt_pk_bf16_f32 v159, v26, v27
	v_cvt_pk_bf16_f32 v160, v16, v17
	v_cvt_pk_bf16_f32 v161, v18, v19
	global_store_dwordx4 v[170:171], v[158:161], off offset:256 sc1
	v_lshl_add_u64 v[170:171], v[162:163], 0, s[22:23]
	v_add_co_u32_e32 v162, vcc, s15, v162
	v_cvt_pk_bf16_f32 v158, v12, v13
	v_cvt_pk_bf16_f32 v159, v14, v15
	v_cvt_pk_bf16_f32 v160, v4, v5
	v_cvt_pk_bf16_f32 v161, v6, v7
	v_addc_co_u32_e32 v163, vcc, 0, v163, vcc
	global_store_dwordx4 v[162:163], v[158:161], off sc1
	s_nop 1
	v_cvt_pk_bf16_f32 v158, v8, v9
	v_cvt_pk_bf16_f32 v159, v10, v11
	v_cvt_pk_bf16_f32 v160, v0, v1
	v_cvt_pk_bf16_f32 v161, v2, v3
	global_store_dwordx4 v[170:171], v[158:161], off offset:256 sc1

; DI unsigned pk2(float lo, float hi) { f32x2 v = {lo, hi}; bf16v2 r = __builtin_convertvector(v, bf16v2); return __builtin_bit_cast(unsigned, r); }
; template <int ACT> DI void store_act(const f32x4 (&acc)[2][2][4][2], bf16_t* base, int row0, int col0) {
;     ...
;         for (int m = 0; m < 4; ++m) { bf16_t* rowp = base + (size_t)(row0 + ai * 128 + m * 16) * D + col0;
; #pragma unroll
;             for (int bj = 0; bj < 2; ++bj) { const f32x4 v0 = acc[ai][bj][m][0], v1 = acc[ai][bj][m][1];
;                 u32x4 w; w.x = pk2(act_fn<ACT>(v0[0]), act_fn<ACT>(v0[1])); w.y = pk2(act_fn<ACT>(v0[2]), act_fn<ACT>(v0[3]));
;                 w.z = pk2(act_fn<ACT>(v1[0]), act_fn<ACT>(v1[1])); w.w = pk2(act_fn<ACT>(v1[2]), act_fn<ACT>(v1[3]));
;                 *(u32x4*)(rowp + bj * 128) = w; } }
.LBB0_252:
	s_andn2_b64 vcc, exec, s[24:25]
	s_cbranch_vccnz .LBB0_254
	v_ashrrev_i32_e32 v157, 31, v156
	v_ashrrev_i32_e32 v155, 31, v154
	v_lshl_add_u64 v[162:163], v[156:157], 1, s[2:3]
	v_lshlrev_b64 v[158:159], 11, v[154:155]
	v_lshl_add_u64 v[170:171], v[162:163], 0, v[158:159]
	v_cvt_pk_bf16_f32 v158, v126, v127
	v_cvt_pk_bf16_f32 v159, v128, v129
	v_cvt_pk_bf16_f32 v160, v118, v119
	v_cvt_pk_bf16_f32 v161, v120, v121
	global_store_dwordx4 v[170:171], v[158:161], off sc1
	s_mov_b32 s15, 0x40000
	s_mov_b64 s[22:23], 0x40000
	v_cvt_pk_bf16_f32 v158, v122, v123
	v_cvt_pk_bf16_f32 v159, v124, v125
	v_cvt_pk_bf16_f32 v160, v114, v115
	v_cvt_pk_bf16_f32 v161, v116, v117
	global_store_dwordx4 v[170:171], v[158:161], off offset:256 sc1
	s_nop 1
	v_or_b32_e32 v158, 16, v154
	v_ashrrev_i32_e32 v159, 31, v158
	v_lshlrev_b64 v[158:159], 11, v[158:159]
	v_lshl_add_u64 v[178:179], v[162:163], 0, v[158:159]
	v_cvt_pk_bf16_f32 v158, v110, v111
	v_cvt_pk_bf16_f32 v159, v112, v113
	v_cvt_pk_bf16_f32 v160, v102, v103
	v_cvt_pk_bf16_f32 v161, v104, v105
	global_store_dwordx4 v[178:179], v[158:161], off sc1
	s_nop 1
	v_cvt_pk_bf16_f32 v158, v106, v107
	v_cvt_pk_bf16_f32 v159, v108, v109
	v_cvt_pk_bf16_f32 v160, v98, v99
	v_cvt_pk_bf16_f32 v161, v100, v101
	global_store_dwordx4 v[178:179], v[158:161], off offset:256 sc1
	s_nop 1
	v_or_b32_e32 v158, 32, v154
	v_ashrrev_i32_e32 v159, 31, v158
	v_lshlrev_b64 v[158:159], 11, v[158:159]
	v_lshl_add_u64 v[178:179], v[162:163], 0, v[158:159]
	v_cvt_pk_bf16_f32 v158, v94, v95
	v_cvt_pk_bf16_f32 v159, v96, v97
	v_cvt_pk_bf16_f32 v160, v86, v87
	v_cvt_pk_bf16_f32 v161, v88, v89
	global_store_dwordx4 v[178:179], v[158:161], off sc1
	s_nop 1
	v_cvt_pk_bf16_f32 v158, v90, v91
	v_cvt_pk_bf16_f32 v159, v92, v93
	v_cvt_pk_bf16_f32 v160, v82, v83
	v_cvt_pk_bf16_f32 v161, v84, v85
	global_store_dwordx4 v[178:179], v[158:161], off offset:256 sc1
	v_add_co_u32_e32 v178, vcc, s15, v170
	s_nop 0
	v_or_b32_e32 v158, 48, v154
	v_ashrrev_i32_e32 v159, 31, v158
	v_lshlrev_b64 v[158:159], 11, v[158:159]
	v_lshl_add_u64 v[162:163], v[162:163], 0, v[158:159]
	v_cvt_pk_bf16_f32 v158, v78, v79
	v_cvt_pk_bf16_f32 v159, v80, v81
	v_cvt_pk_bf16_f32 v160, v70, v71
	v_cvt_pk_bf16_f32 v161, v72, v73
	global_store_dwordx4 v[162:163], v[158:161], off sc1
	v_addc_co_u32_e32 v179, vcc, 0, v171, vcc
	s_nop 0
	v_cvt_pk_bf16_f32 v158, v74, v75
	v_cvt_pk_bf16_f32 v159, v76, v77
	v_cvt_pk_bf16_f32 v160, v66, v67
	v_cvt_pk_bf16_f32 v161, v68, v69
	global_store_dwordx4 v[162:163], v[158:161], off offset:256 sc1
	s_mov_b32 s15, 0x48000
	v_lshl_add_u64 v[162:163], v[170:171], 0, s[22:23]
	v_cvt_pk_bf16_f32 v158, v62, v63
	v_cvt_pk_bf16_f32 v159, v64, v65
	v_cvt_pk_bf16_f32 v160, v54, v55
	v_cvt_pk_bf16_f32 v161, v56, v57
	global_store_dwordx4 v[178:179], v[158:161], off sc1
	v_add_co_u32_e32 v178, vcc, s15, v170
	s_nop 0
	v_cvt_pk_bf16_f32 v158, v58, v59
	v_cvt_pk_bf16_f32 v159, v60, v61
	v_cvt_pk_bf16_f32 v160, v50, v51
	v_cvt_pk_bf16_f32 v161, v52, v53
	global_store_dwordx4 v[162:163], v[158:161], off offset:256 sc1
	s_mov_b64 s[22:23], 0x48000
	v_addc_co_u32_e32 v179, vcc, 0, v171, vcc
	v_cvt_pk_bf16_f32 v158, v44, v45
	v_cvt_pk_bf16_f32 v159, v46, v47
	v_cvt_pk_bf16_f32 v160, v36, v37
	v_cvt_pk_bf16_f32 v161, v38, v39
	s_mov_b32 s15, 0x50000
	v_lshl_add_u64 v[162:163], v[170:171], 0, s[22:23]
	global_store_dwordx4 v[178:179], v[158:161], off sc1
	v_add_co_u32_e32 v178, vcc, s15, v170
	s_nop 0
	v_cvt_pk_bf16_f32 v158, v40, v41
	v_cvt_pk_bf16_f32 v159, v42, v43
	v_cvt_pk_bf16_f32 v160, v32, v33
	v_cvt_pk_bf16_f32 v161, v34, v35
	global_store_dwordx4 v[162:163], v[158:161], off offset:256 sc1
	s_mov_b64 s[22:23], 0x50000
	v_addc_co_u32_e32 v179, vcc, 0, v171, vcc
	v_cvt_pk_bf16_f32 v158, v28, v29
	v_cvt_pk_bf16_f32 v159, v30, v31
	v_cvt_pk_bf16_f32 v160, v20, v21
	v_cvt_pk_bf16_f32 v161, v22, v23
	v_lshl_add_u64 v[162:163], v[170:171], 0, s[22:23]
	global_store_dwordx4 v[178:179], v[158:161], off sc1
	s_mov_b64 s[22:23], 0x58000
	s_mov_b32 s15, 0x58000
	v_cvt_pk_bf16_f32 v158, v24, v25
	v_cvt_pk_bf16_f32 v159, v26, v27
	v_cvt_pk_bf16_f32 v160, v16, v17
	v_cvt_pk_bf16_f32 v161, v18, v19
	global_store_dwordx4 v[162:163], v[158:161], off offset:256 sc1
	v_lshl_add_u64 v[162:163], v[170:171], 0, s[22:23]
	v_add_co_u32_e32 v170, vcc, s15, v170
	v_cvt_pk_bf16_f32 v158, v12, v13
	v_cvt_pk_bf16_f32 v159, v14, v15
	v_cvt_pk_bf16_f32 v160, v4, v5
	v_cvt_pk_bf16_f32 v161, v6, v7
	v_addc_co_u32_e32 v171, vcc, 0, v171, vcc
	global_store_dwordx4 v[170:171], v[158:161], off sc1
	s_nop 1
	v_cvt_pk_bf16_f32 v158, v8, v9
	v_cvt_pk_bf16_f32 v159, v10, v11
	v_cvt_pk_bf16_f32 v160, v0, v1
	v_cvt_pk_bf16_f32 v161, v2, v3
	global_store_dwordx4 v[162:163], v[158:161], off offset:256 sc1

; DI unsigned pk2(float lo, float hi) { f32x2 v = {lo, hi}; bf16v2 r = __builtin_convertvector(v, bf16v2); return __builtin_bit_cast(unsigned, r); }
; DI float siluf_(float x) { return x * sigmoidf_(x); }
; template <int ACT> DI float act_fn(float x) {
;     ...
;     if (ACT == 1) return siluf_(x) * 0.08838834764831845f;
; template <int ACT> DI void store_act(const f32x4 (&acc)[2][2][4][2], bf16_t* base, int row0, int col0) {
;     ...
;         for (int m = 0; m < 4; ++m) { bf16_t* rowp = base + (size_t)(row0 + ai * 128 + m * 16) * D + col0;
; #pragma unroll
;             for (int bj = 0; bj < 2; ++bj) { const f32x4 v0 = acc[ai][bj][m][0], v1 = acc[ai][bj][m][1];
;                 u32x4 w; w.x = pk2(act_fn<ACT>(v0[0]), act_fn<ACT>(v0[1])); w.y = pk2(act_fn<ACT>(v0[2]), act_fn<ACT>(v0[3]));
;                 w.z = pk2(act_fn<ACT>(v1[0]), act_fn<ACT>(v1[1])); w.w = pk2(act_fn<ACT>(v1[2]), act_fn<ACT>(v1[3]));
;                 *(u32x4*)(rowp + bj * 128) = w; } }
.LBB0_255:
	v_mul_f32_e32 v48, 0xbfb8aa3b, v126
	v_exp_f32_e32 v48, v48
	s_mov_b32 s22, 0x3db504f3
	v_ashrrev_i32_e32 v157, 31, v156
	v_ashrrev_i32_e32 v155, 31, v154
	v_add_f32_e32 v48, 1.0, v48
	v_rcp_f32_e32 v160, v48
	v_mul_f32_e32 v48, 0xbfb8aa3b, v127
	v_exp_f32_e32 v48, v48
	v_lshl_add_u64 v[158:159], v[156:157], 1, s[2:3]
	v_lshlrev_b64 v[156:157], 11, v[154:155]
	v_lshl_add_u64 v[156:157], v[158:159], 0, v[156:157]
	v_add_f32_e32 v48, 1.0, v48
	v_rcp_f32_e32 v161, v48
	v_mul_f32_e32 v48, 0xbfb8aa3b, v128
	v_exp_f32_e32 v48, v48
	s_mov_b64 s[2:3], 0x40000
	v_pk_mul_f32 v[160:161], v[126:127], v[160:161]
	v_add_f32_e32 v48, 1.0, v48
	v_rcp_f32_e32 v162, v48
	v_mul_f32_e32 v48, 0xbfb8aa3b, v129
	v_exp_f32_e32 v48, v48
	v_pk_mul_f32 v[160:161], v[160:161], s[22:23] op_sel_hi:[1,0]
	v_add_f32_e32 v48, 1.0, v48
	v_rcp_f32_e32 v163, v48
	v_mul_f32_e32 v48, 0xbfb8aa3b, v118
	v_exp_f32_e32 v48, v48
	v_cvt_pk_bf16_f32 v160, v160, v161
	v_pk_mul_f32 v[162:163], v[128:129], v[162:163]
	v_add_f32_e32 v48, 1.0, v48
	v_pk_mul_f32 v[162:163], v[162:163], s[22:23] op_sel_hi:[1,0]
	s_nop 0
	v_cvt_pk_bf16_f32 v161, v162, v163
	v_rcp_f32_e32 v162, v48
	v_mul_f32_e32 v48, 0xbfb8aa3b, v119
	v_exp_f32_e32 v48, v48
	s_nop 0
	v_add_f32_e32 v48, 1.0, v48
	v_rcp_f32_e32 v163, v48
	v_mul_f32_e32 v48, 0xbfb8aa3b, v120
	v_exp_f32_e32 v48, v48
	v_pk_mul_f32 v[162:163], v[118:119], v[162:163]
	s_nop 0
	v_pk_mul_f32 v[162:163], v[162:163], s[22:23] op_sel_hi:[1,0]
	v_add_f32_e32 v48, 1.0, v48
	v_rcp_f32_e32 v170, v48
	v_mul_f32_e32 v48, 0xbfb8aa3b, v121
	v_exp_f32_e32 v48, v48
	v_cvt_pk_bf16_f32 v162, v162, v163
	v_add_f32_e32 v48, 1.0, v48
	v_rcp_f32_e32 v171, v48
	v_mul_f32_e32 v48, 0xbfb8aa3b, v122
	v_exp_f32_e32 v48, v48
	v_pk_mul_f32 v[170:171], v[120:121], v[170:171]
	s_nop 0
	v_pk_mul_f32 v[170:171], v[170:171], s[22:23] op_sel_hi:[1,0]
	v_add_f32_e32 v48, 1.0, v48
	v_cvt_pk_bf16_f32 v163, v170, v171
	global_store_dwordx4 v[156:157], v[160:163], off sc1
	s_nop 1
	v_rcp_f32_e32 v160, v48
	v_mul_f32_e32 v48, 0xbfb8aa3b, v123
	v_exp_f32_e32 v48, v48
	s_nop 0
	v_add_f32_e32 v48, 1.0, v48
	v_rcp_f32_e32 v161, v48
	v_mul_f32_e32 v48, 0xbfb8aa3b, v124
	v_exp_f32_e32 v48, v48
	v_pk_mul_f32 v[160:161], v[122:123], v[160:161]
	s_nop 0
	v_pk_mul_f32 v[160:161], v[160:161], s[22:23] op_sel_hi:[1,0]
	v_add_f32_e32 v48, 1.0, v48
	v_rcp_f32_e32 v162, v48
	v_mul_f32_e32 v48, 0xbfb8aa3b, v125
	v_exp_f32_e32 v48, v48
	v_cvt_pk_bf16_f32 v160, v160, v161
	v_add_f32_e32 v48, 1.0, v48
	v_rcp_f32_e32 v163, v48
	v_mul_f32_e32 v48, 0xbfb8aa3b, v114
	v_exp_f32_e32 v48, v48
	v_pk_mul_f32 v[162:163], v[124:125], v[162:163]
	s_nop 0
	v_pk_mul_f32 v[162:163], v[162:163], s[22:23] op_sel_hi:[1,0]
	v_add_f32_e32 v48, 1.0, v48
	v_cvt_pk_bf16_f32 v161, v162, v163
	v_rcp_f32_e32 v162, v48
	v_mul_f32_e32 v48, 0xbfb8aa3b, v115
	v_exp_f32_e32 v48, v48
	s_nop 0
	v_add_f32_e32 v48, 1.0, v48
	v_rcp_f32_e32 v163, v48
	v_mul_f32_e32 v48, 0xbfb8aa3b, v116
	v_exp_f32_e32 v48, v48
	v_pk_mul_f32 v[162:163], v[114:115], v[162:163]
	s_nop 0
	v_pk_mul_f32 v[162:163], v[162:163], s[22:23] op_sel_hi:[1,0]
	v_add_f32_e32 v48, 1.0, v48
	v_rcp_f32_e32 v170, v48
	v_mul_f32_e32 v48, 0xbfb8aa3b, v117
	v_exp_f32_e32 v48, v48
	v_cvt_pk_bf16_f32 v162, v162, v163
	v_add_f32_e32 v48, 1.0, v48
	v_rcp_f32_e32 v171, v48
	v_mul_f32_e32 v48, 0xbfb8aa3b, v110
	v_exp_f32_e32 v48, v48
	v_pk_mul_f32 v[170:171], v[116:117], v[170:171]
	s_nop 0
	v_pk_mul_f32 v[170:171], v[170:171], s[22:23] op_sel_hi:[1,0]
	v_add_f32_e32 v48, 1.0, v48
	v_cvt_pk_bf16_f32 v163, v170, v171
	global_store_dwordx4 v[156:157], v[160:163], off offset:256 sc1
	s_nop 1
	v_rcp_f32_e32 v162, v48
	v_mul_f32_e32 v48, 0xbfb8aa3b, v111
	v_exp_f32_e32 v48, v48
	v_or_b32_e32 v160, 16, v154
	v_ashrrev_i32_e32 v161, 31, v160
	v_lshlrev_b64 v[160:161], 11, v[160:161]
	v_add_f32_e32 v48, 1.0, v48
	v_rcp_f32_e32 v163, v48
	v_mul_f32_e32 v48, 0xbfb8aa3b, v112
	v_exp_f32_e32 v48, v48
	v_lshl_add_u64 v[160:161], v[158:159], 0, v[160:161]
	v_pk_mul_f32 v[162:163], v[110:111], v[162:163]
	v_add_f32_e32 v48, 1.0, v48
	v_pk_mul_f32 v[162:163], v[162:163], s[22:23] op_sel_hi:[1,0]
	s_nop 0
	v_cvt_pk_bf16_f32 v178, v162, v163
	v_rcp_f32_e32 v162, v48
	v_mul_f32_e32 v48, 0xbfb8aa3b, v113
	v_exp_f32_e32 v48, v48
	s_nop 0
	v_add_f32_e32 v48, 1.0, v48
	v_rcp_f32_e32 v163, v48
	v_mul_f32_e32 v48, 0xbfb8aa3b, v102
	v_exp_f32_e32 v48, v48
	v_pk_mul_f32 v[162:163], v[112:113], v[162:163]
	s_nop 0
	v_pk_mul_f32 v[162:163], v[162:163], s[22:23] op_sel_hi:[1,0]
	v_add_f32_e32 v48, 1.0, v48
	v_cvt_pk_bf16_f32 v179, v162, v163
	v_rcp_f32_e32 v162, v48
	v_mul_f32_e32 v48, 0xbfb8aa3b, v103
	v_exp_f32_e32 v48, v48
	s_nop 0
	v_add_f32_e32 v48, 1.0, v48
	v_rcp_f32_e32 v163, v48
	v_mul_f32_e32 v48, 0xbfb8aa3b, v104
	v_exp_f32_e32 v48, v48
	v_pk_mul_f32 v[162:163], v[102:103], v[162:163]
	s_nop 0
	v_pk_mul_f32 v[162:163], v[162:163], s[22:23] op_sel_hi:[1,0]
	v_add_f32_e32 v48, 1.0, v48
	v_cvt_pk_bf16_f32 v180, v162, v163
	v_rcp_f32_e32 v162, v48
	v_mul_f32_e32 v48, 0xbfb8aa3b, v105
	v_exp_f32_e32 v48, v48
	s_nop 0
	v_add_f32_e32 v48, 1.0, v48
	v_rcp_f32_e32 v163, v48
	v_mul_f32_e32 v48, 0xbfb8aa3b, v106
	v_exp_f32_e32 v48, v48
	v_pk_mul_f32 v[162:163], v[104:105], v[162:163]
	s_nop 0
	v_pk_mul_f32 v[162:163], v[162:163], s[22:23] op_sel_hi:[1,0]
	v_add_f32_e32 v48, 1.0, v48
	v_cvt_pk_bf16_f32 v181, v162, v163
	v_rcp_f32_e32 v162, v48
	v_mul_f32_e32 v48, 0xbfb8aa3b, v107
	v_exp_f32_e32 v48, v48
	global_store_dwordx4 v[160:161], v[178:181], off sc1
	v_add_f32_e32 v48, 1.0, v48
	v_rcp_f32_e32 v163, v48
	v_mul_f32_e32 v48, 0xbfb8aa3b, v108
	v_exp_f32_e32 v48, v48
	v_pk_mul_f32 v[162:163], v[106:107], v[162:163]
; DI unsigned pk2(float lo, float hi) { f32x2 v = {lo, hi}; bf16v2 r = __builtin_convertvector(v, bf16v2); return __builtin_bit_cast(unsigned, r); }
; DI float siluf_(float x) { return x * sigmoidf_(x); }
; template <int ACT> DI float act_fn(float x) {
;     ...
;     if (ACT == 1) return siluf_(x) * 0.08838834764831845f;
; template <int ACT> DI void store_act(const f32x4 (&acc)[2][2][4][2], bf16_t* base, int row0, int col0) {
;     ...
;         for (int m = 0; m < 4; ++m) { bf16_t* rowp = base + (size_t)(row0 + ai * 128 + m * 16) * D + col0;
; #pragma unroll
;             for (int bj = 0; bj < 2; ++bj) { const f32x4 v0 = acc[ai][bj][m][0], v1 = acc[ai][bj][m][1];
;                 u32x4 w; w.x = pk2(act_fn<ACT>(v0[0]), act_fn<ACT>(v0[1])); w.y = pk2(act_fn<ACT>(v0[2]), act_fn<ACT>(v0[3]));
;                 w.z = pk2(act_fn<ACT>(v1[0]), act_fn<ACT>(v1[1])); w.w = pk2(act_fn<ACT>(v1[2]), act_fn<ACT>(v1[3]));
;                 *(u32x4*)(rowp + bj * 128) = w; } }
	s_nop 0
	v_pk_mul_f32 v[162:163], v[162:163], s[22:23] op_sel_hi:[1,0]
	v_add_f32_e32 v48, 1.0, v48
	v_cvt_pk_bf16_f32 v178, v162, v163
	v_rcp_f32_e32 v162, v48
	v_mul_f32_e32 v48, 0xbfb8aa3b, v109
	v_exp_f32_e32 v48, v48
	s_nop 0
	v_add_f32_e32 v48, 1.0, v48
	v_rcp_f32_e32 v163, v48
	v_mul_f32_e32 v48, 0xbfb8aa3b, v98
	v_exp_f32_e32 v48, v48
	v_pk_mul_f32 v[162:163], v[108:109], v[162:163]
	s_nop 0
	v_pk_mul_f32 v[162:163], v[162:163], s[22:23] op_sel_hi:[1,0]
	v_add_f32_e32 v48, 1.0, v48
	v_cvt_pk_bf16_f32 v179, v162, v163
	v_rcp_f32_e32 v162, v48
	v_mul_f32_e32 v48, 0xbfb8aa3b, v99
	v_exp_f32_e32 v48, v48
	s_nop 0
	v_add_f32_e32 v48, 1.0, v48
	v_rcp_f32_e32 v163, v48
	v_mul_f32_e32 v48, 0xbfb8aa3b, v100
	v_exp_f32_e32 v48, v48
	v_pk_mul_f32 v[162:163], v[98:99], v[162:163]
	s_nop 0
	v_pk_mul_f32 v[162:163], v[162:163], s[22:23] op_sel_hi:[1,0]
	v_add_f32_e32 v48, 1.0, v48
	v_cvt_pk_bf16_f32 v180, v162, v163
	v_rcp_f32_e32 v162, v48
	v_mul_f32_e32 v48, 0xbfb8aa3b, v101
	v_exp_f32_e32 v48, v48
	s_nop 0
	v_add_f32_e32 v48, 1.0, v48
	v_rcp_f32_e32 v163, v48
	v_mul_f32_e32 v48, 0xbfb8aa3b, v94
	v_exp_f32_e32 v48, v48
	v_pk_mul_f32 v[162:163], v[100:101], v[162:163]
	s_nop 0
	v_pk_mul_f32 v[162:163], v[162:163], s[22:23] op_sel_hi:[1,0]
	v_add_f32_e32 v48, 1.0, v48
	v_cvt_pk_bf16_f32 v181, v162, v163
	v_rcp_f32_e32 v162, v48
	v_mul_f32_e32 v48, 0xbfb8aa3b, v95
	v_exp_f32_e32 v48, v48
	global_store_dwordx4 v[160:161], v[178:181], off offset:256 sc1
	v_or_b32_e32 v160, 32, v154
	v_ashrrev_i32_e32 v161, 31, v160
	v_add_f32_e32 v48, 1.0, v48
	v_rcp_f32_e32 v163, v48
	v_mul_f32_e32 v48, 0xbfb8aa3b, v96
	v_exp_f32_e32 v48, v48
	v_lshlrev_b64 v[160:161], 11, v[160:161]
	v_pk_mul_f32 v[162:163], v[94:95], v[162:163]
	v_lshl_add_u64 v[160:161], v[158:159], 0, v[160:161]
	v_pk_mul_f32 v[162:163], v[162:163], s[22:23] op_sel_hi:[1,0]
	v_add_f32_e32 v48, 1.0, v48
	v_cvt_pk_bf16_f32 v178, v162, v163
	v_rcp_f32_e32 v162, v48
	v_mul_f32_e32 v48, 0xbfb8aa3b, v97
	v_exp_f32_e32 v48, v48
	s_nop 0
	v_add_f32_e32 v48, 1.0, v48
	v_rcp_f32_e32 v163, v48
	v_mul_f32_e32 v48, 0xbfb8aa3b, v86
	v_exp_f32_e32 v48, v48
	v_pk_mul_f32 v[162:163], v[96:97], v[162:163]
	s_nop 0
	v_pk_mul_f32 v[162:163], v[162:163], s[22:23] op_sel_hi:[1,0]
	v_add_f32_e32 v48, 1.0, v48
	v_cvt_pk_bf16_f32 v179, v162, v163
	v_rcp_f32_e32 v162, v48
	v_mul_f32_e32 v48, 0xbfb8aa3b, v87
	v_exp_f32_e32 v48, v48
	s_nop 0
	v_add_f32_e32 v48, 1.0, v48
	v_rcp_f32_e32 v163, v48
	v_mul_f32_e32 v48, 0xbfb8aa3b, v88
	v_exp_f32_e32 v48, v48
	v_pk_mul_f32 v[162:163], v[86:87], v[162:163]
	s_nop 0
	v_pk_mul_f32 v[162:163], v[162:163], s[22:23] op_sel_hi:[1,0]
	v_add_f32_e32 v48, 1.0, v48
	v_cvt_pk_bf16_f32 v180, v162, v163
	v_rcp_f32_e32 v162, v48
	v_mul_f32_e32 v48, 0xbfb8aa3b, v89
	v_exp_f32_e32 v48, v48
	s_nop 0
	v_add_f32_e32 v48, 1.0, v48
	v_rcp_f32_e32 v163, v48
	v_mul_f32_e32 v48, 0xbfb8aa3b, v90
	v_exp_f32_e32 v48, v48
	v_pk_mul_f32 v[162:163], v[88:89], v[162:163]
	s_nop 0
	v_pk_mul_f32 v[162:163], v[162:163], s[22:23] op_sel_hi:[1,0]
	v_add_f32_e32 v48, 1.0, v48
	v_cvt_pk_bf16_f32 v181, v162, v163
	v_rcp_f32_e32 v162, v48
	v_mul_f32_e32 v48, 0xbfb8aa3b, v91
	v_exp_f32_e32 v48, v48
	global_store_dwordx4 v[160:161], v[178:181], off sc1
	v_add_f32_e32 v48, 1.0, v48
	v_rcp_f32_e32 v163, v48
	v_mul_f32_e32 v48, 0xbfb8aa3b, v92
	v_exp_f32_e32 v48, v48
	v_pk_mul_f32 v[162:163], v[90:91], v[162:163]
	s_nop 0
	v_pk_mul_f32 v[162:163], v[162:163], s[22:23] op_sel_hi:[1,0]
	v_add_f32_e32 v48, 1.0, v48
	v_cvt_pk_bf16_f32 v178, v162, v163
	v_rcp_f32_e32 v162, v48
	v_mul_f32_e32 v48, 0xbfb8aa3b, v93
	v_exp_f32_e32 v48, v48
	s_nop 0
	v_add_f32_e32 v48, 1.0, v48
	v_rcp_f32_e32 v163, v48
	v_mul_f32_e32 v48, 0xbfb8aa3b, v82
	v_exp_f32_e32 v48, v48
	v_pk_mul_f32 v[162:163], v[92:93], v[162:163]
	s_nop 0
	v_pk_mul_f32 v[162:163], v[162:163], s[22:23] op_sel_hi:[1,0]
	v_add_f32_e32 v48, 1.0, v48
	v_cvt_pk_bf16_f32 v179, v162, v163
	v_rcp_f32_e32 v162, v48
	v_mul_f32_e32 v48, 0xbfb8aa3b, v83
	v_exp_f32_e32 v48, v48
	s_nop 0
	v_add_f32_e32 v48, 1.0, v48
	v_rcp_f32_e32 v163, v48
	v_mul_f32_e32 v48, 0xbfb8aa3b, v84
	v_exp_f32_e32 v48, v48
	v_pk_mul_f32 v[162:163], v[82:83], v[162:163]
	s_nop 0
	v_pk_mul_f32 v[162:163], v[162:163], s[22:23] op_sel_hi:[1,0]
	v_add_f32_e32 v48, 1.0, v48
	v_cvt_pk_bf16_f32 v180, v162, v163
	v_rcp_f32_e32 v162, v48
	v_mul_f32_e32 v48, 0xbfb8aa3b, v85
	v_exp_f32_e32 v48, v48
	s_nop 0
	v_add_f32_e32 v48, 1.0, v48
	v_rcp_f32_e32 v163, v48
	v_mul_f32_e32 v48, 0xbfb8aa3b, v78
	v_exp_f32_e32 v48, v48
	v_pk_mul_f32 v[162:163], v[84:85], v[162:163]
	s_nop 0
	v_pk_mul_f32 v[162:163], v[162:163], s[22:23] op_sel_hi:[1,0]
	v_add_f32_e32 v48, 1.0, v48
	v_cvt_pk_bf16_f32 v181, v162, v163
	global_store_dwordx4 v[160:161], v[178:181], off offset:256 sc1
	v_or_b32_e32 v160, 48, v154
	v_ashrrev_i32_e32 v161, 31, v160
	v_lshlrev_b64 v[160:161], 11, v[160:161]
	v_lshl_add_u64 v[158:159], v[158:159], 0, v[160:161]
	v_rcp_f32_e32 v160, v48
	v_mul_f32_e32 v48, 0xbfb8aa3b, v79
	v_exp_f32_e32 v48, v48
	s_nop 0
	v_add_f32_e32 v48, 1.0, v48
	v_rcp_f32_e32 v161, v48
	v_mul_f32_e32 v48, 0xbfb8aa3b, v80
	v_exp_f32_e32 v48, v48
	v_pk_mul_f32 v[160:161], v[78:79], v[160:161]
	s_nop 0
	v_pk_mul_f32 v[160:161], v[160:161], s[22:23] op_sel_hi:[1,0]
	v_add_f32_e32 v48, 1.0, v48
	v_rcp_f32_e32 v162, v48
	v_mul_f32_e32 v48, 0xbfb8aa3b, v81
	v_exp_f32_e32 v48, v48
	v_cvt_pk_bf16_f32 v160, v160, v161
	v_add_f32_e32 v48, 1.0, v48
	v_rcp_f32_e32 v163, v48
	v_mul_f32_e32 v48, 0xbfb8aa3b, v70
	v_exp_f32_e32 v48, v48
	v_pk_mul_f32 v[162:163], v[80:81], v[162:163]
	s_nop 0
	v_pk_mul_f32 v[162:163], v[162:163], s[22:23] op_sel_hi:[1,0]
; DI unsigned pk2(float lo, float hi) { f32x2 v = {lo, hi}; bf16v2 r = __builtin_convertvector(v, bf16v2); return __builtin_bit_cast(unsigned, r); }
; DI float siluf_(float x) { return x * sigmoidf_(x); }
; template <int ACT> DI float act_fn(float x) {
;     ...
;     if (ACT == 1) return siluf_(x) * 0.08838834764831845f;
; template <int ACT> DI void store_act(const f32x4 (&acc)[2][2][4][2], bf16_t* base, int row0, int col0) {
;     ...
;         for (int m = 0; m < 4; ++m) { bf16_t* rowp = base + (size_t)(row0 + ai * 128 + m * 16) * D + col0;
; #pragma unroll
;             for (int bj = 0; bj < 2; ++bj) { const f32x4 v0 = acc[ai][bj][m][0], v1 = acc[ai][bj][m][1];
;                 u32x4 w; w.x = pk2(act_fn<ACT>(v0[0]), act_fn<ACT>(v0[1])); w.y = pk2(act_fn<ACT>(v0[2]), act_fn<ACT>(v0[3]));
;                 w.z = pk2(act_fn<ACT>(v1[0]), act_fn<ACT>(v1[1])); w.w = pk2(act_fn<ACT>(v1[2]), act_fn<ACT>(v1[3]));
;                 *(u32x4*)(rowp + bj * 128) = w; } }
	v_add_f32_e32 v48, 1.0, v48
	v_cvt_pk_bf16_f32 v161, v162, v163
	v_rcp_f32_e32 v162, v48
	v_mul_f32_e32 v48, 0xbfb8aa3b, v71
	v_exp_f32_e32 v48, v48
	s_nop 0
	v_add_f32_e32 v48, 1.0, v48
	v_rcp_f32_e32 v163, v48
	v_mul_f32_e32 v48, 0xbfb8aa3b, v72
	v_exp_f32_e32 v48, v48
	v_pk_mul_f32 v[162:163], v[70:71], v[162:163]
	s_nop 0
	v_pk_mul_f32 v[162:163], v[162:163], s[22:23] op_sel_hi:[1,0]
	v_add_f32_e32 v48, 1.0, v48
	v_rcp_f32_e32 v170, v48
	v_mul_f32_e32 v48, 0xbfb8aa3b, v73
	v_exp_f32_e32 v48, v48
	v_cvt_pk_bf16_f32 v162, v162, v163
	v_add_f32_e32 v48, 1.0, v48
	v_rcp_f32_e32 v171, v48
	v_mul_f32_e32 v48, 0xbfb8aa3b, v74
	v_exp_f32_e32 v48, v48
	v_pk_mul_f32 v[170:171], v[72:73], v[170:171]
	s_nop 0
	v_pk_mul_f32 v[170:171], v[170:171], s[22:23] op_sel_hi:[1,0]
	v_add_f32_e32 v48, 1.0, v48
	v_cvt_pk_bf16_f32 v163, v170, v171
	global_store_dwordx4 v[158:159], v[160:163], off sc1
	s_nop 1
	v_rcp_f32_e32 v160, v48
	v_mul_f32_e32 v48, 0xbfb8aa3b, v75
	v_exp_f32_e32 v48, v48
	s_nop 0
	v_add_f32_e32 v48, 1.0, v48
	v_rcp_f32_e32 v161, v48
	v_mul_f32_e32 v48, 0xbfb8aa3b, v76
	v_exp_f32_e32 v48, v48
	v_pk_mul_f32 v[160:161], v[74:75], v[160:161]
	s_nop 0
	v_pk_mul_f32 v[160:161], v[160:161], s[22:23] op_sel_hi:[1,0]
	v_add_f32_e32 v48, 1.0, v48
	v_rcp_f32_e32 v162, v48
	v_mul_f32_e32 v48, 0xbfb8aa3b, v77
	v_exp_f32_e32 v48, v48
	v_cvt_pk_bf16_f32 v160, v160, v161
	v_add_f32_e32 v48, 1.0, v48
	v_rcp_f32_e32 v163, v48
	v_mul_f32_e32 v48, 0xbfb8aa3b, v66
	v_exp_f32_e32 v48, v48
	v_pk_mul_f32 v[162:163], v[76:77], v[162:163]
	s_nop 0
	v_pk_mul_f32 v[162:163], v[162:163], s[22:23] op_sel_hi:[1,0]
	v_add_f32_e32 v48, 1.0, v48
	v_cvt_pk_bf16_f32 v161, v162, v163
	v_rcp_f32_e32 v162, v48
	v_mul_f32_e32 v48, 0xbfb8aa3b, v67
	v_exp_f32_e32 v48, v48
	s_nop 0
	v_add_f32_e32 v48, 1.0, v48
	v_rcp_f32_e32 v163, v48
	v_mul_f32_e32 v48, 0xbfb8aa3b, v68
	v_exp_f32_e32 v48, v48
	v_pk_mul_f32 v[162:163], v[66:67], v[162:163]
	s_nop 0
	v_pk_mul_f32 v[162:163], v[162:163], s[22:23] op_sel_hi:[1,0]
	v_add_f32_e32 v48, 1.0, v48
	v_rcp_f32_e32 v170, v48
	v_mul_f32_e32 v48, 0xbfb8aa3b, v69
	v_exp_f32_e32 v48, v48
	v_cvt_pk_bf16_f32 v162, v162, v163
	v_add_f32_e32 v48, 1.0, v48
	v_rcp_f32_e32 v171, v48
	v_mul_f32_e32 v48, 0xbfb8aa3b, v62
	v_exp_f32_e32 v48, v48
	v_pk_mul_f32 v[170:171], v[68:69], v[170:171]
	s_nop 0
	v_pk_mul_f32 v[170:171], v[170:171], s[22:23] op_sel_hi:[1,0]
	v_add_f32_e32 v48, 1.0, v48
	v_cvt_pk_bf16_f32 v163, v170, v171
	global_store_dwordx4 v[158:159], v[160:163], off offset:256 sc1
	v_lshl_add_u64 v[158:159], v[156:157], 0, s[2:3]
	s_mov_b32 s2, 0x40000
	v_rcp_f32_e32 v160, v48
	v_mul_f32_e32 v48, 0xbfb8aa3b, v63
	v_exp_f32_e32 v48, v48
	s_nop 0
	v_add_f32_e32 v48, 1.0, v48
	v_rcp_f32_e32 v161, v48
	v_mul_f32_e32 v48, 0xbfb8aa3b, v64
	v_exp_f32_e32 v48, v48
	v_pk_mul_f32 v[160:161], v[62:63], v[160:161]
	s_nop 0
	v_pk_mul_f32 v[160:161], v[160:161], s[22:23] op_sel_hi:[1,0]
	v_add_f32_e32 v48, 1.0, v48
	v_rcp_f32_e32 v162, v48
	v_mul_f32_e32 v48, 0xbfb8aa3b, v65
	v_exp_f32_e32 v48, v48
	v_cvt_pk_bf16_f32 v160, v160, v161
	v_add_f32_e32 v48, 1.0, v48
	v_rcp_f32_e32 v163, v48
	v_mul_f32_e32 v48, 0xbfb8aa3b, v54
	v_exp_f32_e32 v48, v48
	v_pk_mul_f32 v[162:163], v[64:65], v[162:163]
	s_nop 0
	v_pk_mul_f32 v[162:163], v[162:163], s[22:23] op_sel_hi:[1,0]
	v_add_f32_e32 v48, 1.0, v48
	v_cvt_pk_bf16_f32 v161, v162, v163
	v_rcp_f32_e32 v162, v48
	v_mul_f32_e32 v48, 0xbfb8aa3b, v55
	v_exp_f32_e32 v48, v48
	s_nop 0
	v_add_f32_e32 v48, 1.0, v48
	v_rcp_f32_e32 v163, v48
	v_mul_f32_e32 v48, 0xbfb8aa3b, v56
	v_exp_f32_e32 v48, v48
	v_pk_mul_f32 v[162:163], v[54:55], v[162:163]
	s_nop 0
	v_pk_mul_f32 v[162:163], v[162:163], s[22:23] op_sel_hi:[1,0]
	v_add_f32_e32 v48, 1.0, v48
	v_rcp_f32_e32 v170, v48
	v_mul_f32_e32 v48, 0xbfb8aa3b, v57
	v_exp_f32_e32 v48, v48
	v_cvt_pk_bf16_f32 v162, v162, v163
	v_add_f32_e32 v48, 1.0, v48
	v_rcp_f32_e32 v171, v48
	v_mul_f32_e32 v48, 0xbfb8aa3b, v58
	v_exp_f32_e32 v48, v48
	v_pk_mul_f32 v[170:171], v[56:57], v[170:171]
	s_nop 0
	v_pk_mul_f32 v[170:171], v[170:171], s[22:23] op_sel_hi:[1,0]
	v_add_f32_e32 v48, 1.0, v48
	v_cvt_pk_bf16_f32 v163, v170, v171
	v_add_co_u32_e32 v170, vcc, s2, v156
	s_mov_b64 s[2:3], 0x48000
	s_nop 0
	v_addc_co_u32_e32 v171, vcc, 0, v157, vcc
	global_store_dwordx4 v[170:171], v[160:163], off sc1
	s_nop 1
	v_rcp_f32_e32 v160, v48
	v_mul_f32_e32 v48, 0xbfb8aa3b, v59
	v_exp_f32_e32 v48, v48
	s_nop 0
	v_add_f32_e32 v48, 1.0, v48
	v_rcp_f32_e32 v161, v48
	v_mul_f32_e32 v48, 0xbfb8aa3b, v60
	v_exp_f32_e32 v48, v48
	v_pk_mul_f32 v[160:161], v[58:59], v[160:161]
	s_nop 0
	v_pk_mul_f32 v[160:161], v[160:161], s[22:23] op_sel_hi:[1,0]
	v_add_f32_e32 v48, 1.0, v48
	v_rcp_f32_e32 v162, v48
	v_mul_f32_e32 v48, 0xbfb8aa3b, v61
	v_exp_f32_e32 v48, v48
	v_cvt_pk_bf16_f32 v160, v160, v161
	v_add_f32_e32 v48, 1.0, v48
	v_rcp_f32_e32 v163, v48
	v_mul_f32_e32 v48, 0xbfb8aa3b, v50
	v_exp_f32_e32 v48, v48
	v_pk_mul_f32 v[162:163], v[60:61], v[162:163]
	s_nop 0
	v_pk_mul_f32 v[162:163], v[162:163], s[22:23] op_sel_hi:[1,0]
	v_add_f32_e32 v48, 1.0, v48
	v_cvt_pk_bf16_f32 v161, v162, v163
	v_rcp_f32_e32 v162, v48
	v_mul_f32_e32 v48, 0xbfb8aa3b, v51
	v_exp_f32_e32 v48, v48
	s_nop 0
	v_add_f32_e32 v48, 1.0, v48
	v_rcp_f32_e32 v163, v48
	v_mul_f32_e32 v48, 0xbfb8aa3b, v52
	v_exp_f32_e32 v48, v48
	v_pk_mul_f32 v[162:163], v[50:51], v[162:163]
	s_nop 0
	v_pk_mul_f32 v[162:163], v[162:163], s[22:23] op_sel_hi:[1,0]
	v_add_f32_e32 v48, 1.0, v48
	v_rcp_f32_e32 v170, v48
	v_mul_f32_e32 v48, 0xbfb8aa3b, v53
	v_exp_f32_e32 v48, v48
	v_cvt_pk_bf16_f32 v162, v162, v163
	v_add_f32_e32 v48, 1.0, v48
	v_rcp_f32_e32 v171, v48
; DI unsigned pk2(float lo, float hi) { f32x2 v = {lo, hi}; bf16v2 r = __builtin_convertvector(v, bf16v2); return __builtin_bit_cast(unsigned, r); }
; DI float fexp2(float x) { return __builtin_amdgcn_exp2f(x); }
; DI float frcp(float x) { return __builtin_amdgcn_rcpf(x); }
; DI float sigmoidf_(float x) { return frcp(1.0f + fexp2(-x * LOG2E)); }
; DI float siluf_(float x) { return x * sigmoidf_(x); }
; template <int ACT> DI void store_act(const f32x4 (&acc)[2][2][4][2], bf16_t* base, int row0, int col0) {
; #pragma unroll
;     for (int ai = 0; ai < 2; ++ai)
; #pragma unroll
;         for (int m = 0; m < 4; ++m) { bf16_t* rowp = base + (size_t)(row0 + ai * 128 + m * 16) * D + col0;
; #pragma unroll
;             for (int bj = 0; bj < 2; ++bj) { const f32x4 v0 = acc[ai][bj][m][0], v1 = acc[ai][bj][m][1];
;                 u32x4 w; w.x = pk2(act_fn<ACT>(v0[0]), act_fn<ACT>(v0[1])); w.y = pk2(act_fn<ACT>(v0[2]), act_fn<ACT>(v0[3]));
;                 w.z = pk2(act_fn<ACT>(v1[0]), act_fn<ACT>(v1[1])); w.w = pk2(act_fn<ACT>(v1[2]), act_fn<ACT>(v1[3]));
;                 *(u32x4*)(rowp + bj * 128) = w; } }
	v_mul_f32_e32 v48, 0xbfb8aa3b, v44
	v_exp_f32_e32 v48, v48
	v_pk_mul_f32 v[170:171], v[52:53], v[170:171]
	s_nop 0
	v_pk_mul_f32 v[170:171], v[170:171], s[22:23] op_sel_hi:[1,0]
	v_add_f32_e32 v48, 1.0, v48
	v_cvt_pk_bf16_f32 v163, v170, v171
	global_store_dwordx4 v[158:159], v[160:163], off offset:256 sc1
	v_lshl_add_u64 v[158:159], v[156:157], 0, s[2:3]
	s_mov_b32 s2, 0x48000
	v_rcp_f32_e32 v160, v48
	v_mul_f32_e32 v48, 0xbfb8aa3b, v45
	v_exp_f32_e32 v48, v48
	s_nop 0
	v_add_f32_e32 v48, 1.0, v48
	v_rcp_f32_e32 v161, v48
	v_mul_f32_e32 v48, 0xbfb8aa3b, v46
	v_exp_f32_e32 v48, v48
	v_pk_mul_f32 v[160:161], v[44:45], v[160:161]
	s_nop 0
	v_pk_mul_f32 v[160:161], v[160:161], s[22:23] op_sel_hi:[1,0]
	v_add_f32_e32 v48, 1.0, v48
	v_rcp_f32_e32 v162, v48
	v_mul_f32_e32 v48, 0xbfb8aa3b, v47
	v_exp_f32_e32 v48, v48
	v_cvt_pk_bf16_f32 v160, v160, v161
	v_add_f32_e32 v48, 1.0, v48
	v_rcp_f32_e32 v163, v48
	v_mul_f32_e32 v48, 0xbfb8aa3b, v36
	v_exp_f32_e32 v48, v48
	v_pk_mul_f32 v[162:163], v[46:47], v[162:163]
	s_nop 0
	v_pk_mul_f32 v[162:163], v[162:163], s[22:23] op_sel_hi:[1,0]
	v_add_f32_e32 v48, 1.0, v48
	v_cvt_pk_bf16_f32 v161, v162, v163
	v_rcp_f32_e32 v162, v48
	v_mul_f32_e32 v48, 0xbfb8aa3b, v37
	v_exp_f32_e32 v48, v48
	s_nop 0
	v_add_f32_e32 v48, 1.0, v48
	v_rcp_f32_e32 v163, v48
	v_mul_f32_e32 v48, 0xbfb8aa3b, v38
	v_exp_f32_e32 v48, v48
	v_pk_mul_f32 v[162:163], v[36:37], v[162:163]
	s_nop 0
	v_pk_mul_f32 v[162:163], v[162:163], s[22:23] op_sel_hi:[1,0]
	v_add_f32_e32 v48, 1.0, v48
	v_rcp_f32_e32 v170, v48
	v_mul_f32_e32 v48, 0xbfb8aa3b, v39
	v_exp_f32_e32 v48, v48
	v_cvt_pk_bf16_f32 v162, v162, v163
	v_add_f32_e32 v48, 1.0, v48
	v_rcp_f32_e32 v171, v48
	v_mul_f32_e32 v48, 0xbfb8aa3b, v40
	v_exp_f32_e32 v48, v48
	v_pk_mul_f32 v[170:171], v[38:39], v[170:171]
	s_nop 0
	v_pk_mul_f32 v[170:171], v[170:171], s[22:23] op_sel_hi:[1,0]
	v_add_f32_e32 v48, 1.0, v48
	v_cvt_pk_bf16_f32 v163, v170, v171
	v_add_co_u32_e32 v170, vcc, s2, v156
	s_mov_b64 s[2:3], 0x50000
	s_nop 0
	v_addc_co_u32_e32 v171, vcc, 0, v157, vcc
	global_store_dwordx4 v[170:171], v[160:163], off sc1
	s_nop 1
	v_rcp_f32_e32 v160, v48
	v_mul_f32_e32 v48, 0xbfb8aa3b, v41
	v_exp_f32_e32 v48, v48
	s_nop 0
	v_add_f32_e32 v48, 1.0, v48
	v_rcp_f32_e32 v161, v48
	v_mul_f32_e32 v48, 0xbfb8aa3b, v42
	v_exp_f32_e32 v48, v48
	v_pk_mul_f32 v[160:161], v[40:41], v[160:161]
	s_nop 0
	v_pk_mul_f32 v[160:161], v[160:161], s[22:23] op_sel_hi:[1,0]
	v_add_f32_e32 v48, 1.0, v48
	v_rcp_f32_e32 v162, v48
	v_mul_f32_e32 v48, 0xbfb8aa3b, v43
	v_exp_f32_e32 v48, v48
	v_cvt_pk_bf16_f32 v160, v160, v161
	v_add_f32_e32 v48, 1.0, v48
	v_rcp_f32_e32 v163, v48
	v_mul_f32_e32 v48, 0xbfb8aa3b, v32
	v_exp_f32_e32 v48, v48
	v_pk_mul_f32 v[162:163], v[42:43], v[162:163]
	s_nop 0
	v_pk_mul_f32 v[162:163], v[162:163], s[22:23] op_sel_hi:[1,0]
	v_add_f32_e32 v48, 1.0, v48
	v_cvt_pk_bf16_f32 v161, v162, v163
	v_rcp_f32_e32 v162, v48
	v_mul_f32_e32 v48, 0xbfb8aa3b, v33
	v_exp_f32_e32 v48, v48
	s_nop 0
	v_add_f32_e32 v48, 1.0, v48
	v_rcp_f32_e32 v163, v48
	v_mul_f32_e32 v48, 0xbfb8aa3b, v34
	v_exp_f32_e32 v48, v48
	v_pk_mul_f32 v[162:163], v[32:33], v[162:163]
	s_nop 0
	v_pk_mul_f32 v[162:163], v[162:163], s[22:23] op_sel_hi:[1,0]
	v_add_f32_e32 v48, 1.0, v48
	v_rcp_f32_e32 v170, v48
	v_mul_f32_e32 v48, 0xbfb8aa3b, v35
	v_exp_f32_e32 v48, v48
	v_cvt_pk_bf16_f32 v162, v162, v163
	v_add_f32_e32 v48, 1.0, v48
	v_rcp_f32_e32 v171, v48
	v_mul_f32_e32 v48, 0xbfb8aa3b, v28
	v_exp_f32_e32 v48, v48
	v_pk_mul_f32 v[170:171], v[34:35], v[170:171]
	s_nop 0
	v_pk_mul_f32 v[170:171], v[170:171], s[22:23] op_sel_hi:[1,0]
	v_add_f32_e32 v48, 1.0, v48
	v_cvt_pk_bf16_f32 v163, v170, v171
	global_store_dwordx4 v[158:159], v[160:163], off offset:256 sc1
	v_lshl_add_u64 v[158:159], v[156:157], 0, s[2:3]
	s_mov_b32 s2, 0x50000
	v_rcp_f32_e32 v160, v48
	v_mul_f32_e32 v48, 0xbfb8aa3b, v29
	v_exp_f32_e32 v48, v48
	s_nop 0
	v_add_f32_e32 v48, 1.0, v48
	v_rcp_f32_e32 v161, v48
	v_mul_f32_e32 v48, 0xbfb8aa3b, v30
	v_exp_f32_e32 v48, v48
	v_pk_mul_f32 v[160:161], v[28:29], v[160:161]
	s_nop 0
	v_pk_mul_f32 v[160:161], v[160:161], s[22:23] op_sel_hi:[1,0]
	v_add_f32_e32 v48, 1.0, v48
	v_rcp_f32_e32 v162, v48
	v_mul_f32_e32 v48, 0xbfb8aa3b, v31
	v_exp_f32_e32 v48, v48
	v_cvt_pk_bf16_f32 v160, v160, v161
	v_add_f32_e32 v48, 1.0, v48
	v_rcp_f32_e32 v163, v48
	v_mul_f32_e32 v48, 0xbfb8aa3b, v20
	v_exp_f32_e32 v48, v48
	v_pk_mul_f32 v[162:163], v[30:31], v[162:163]
	s_nop 0
	v_pk_mul_f32 v[162:163], v[162:163], s[22:23] op_sel_hi:[1,0]
	v_add_f32_e32 v48, 1.0, v48
	v_cvt_pk_bf16_f32 v161, v162, v163
	v_rcp_f32_e32 v162, v48
	v_mul_f32_e32 v48, 0xbfb8aa3b, v21
	v_exp_f32_e32 v48, v48
	s_nop 0
	v_add_f32_e32 v48, 1.0, v48
	v_rcp_f32_e32 v163, v48
	v_mul_f32_e32 v48, 0xbfb8aa3b, v22
	v_exp_f32_e32 v48, v48
	v_pk_mul_f32 v[162:163], v[20:21], v[162:163]
	s_nop 0
	v_pk_mul_f32 v[162:163], v[162:163], s[22:23] op_sel_hi:[1,0]
	v_add_f32_e32 v48, 1.0, v48
	v_rcp_f32_e32 v170, v48
	v_mul_f32_e32 v48, 0xbfb8aa3b, v23
	v_exp_f32_e32 v48, v48
	v_cvt_pk_bf16_f32 v162, v162, v163
	v_add_f32_e32 v48, 1.0, v48
	v_rcp_f32_e32 v171, v48
	v_mul_f32_e32 v48, 0xbfb8aa3b, v24
	v_exp_f32_e32 v48, v48
	v_pk_mul_f32 v[170:171], v[22:23], v[170:171]
; DI unsigned pk2(float lo, float hi) { f32x2 v = {lo, hi}; bf16v2 r = __builtin_convertvector(v, bf16v2); return __builtin_bit_cast(unsigned, r); }
; DI float fexp2(float x) { return __builtin_amdgcn_exp2f(x); }
; DI float frcp(float x) { return __builtin_amdgcn_rcpf(x); }
; DI float sigmoidf_(float x) { return frcp(1.0f + fexp2(-x * LOG2E)); }
; DI float siluf_(float x) { return x * sigmoidf_(x); }
; template <int ACT> DI void store_act(const f32x4 (&acc)[2][2][4][2], bf16_t* base, int row0, int col0) {
; #pragma unroll
;     for (int ai = 0; ai < 2; ++ai)
; #pragma unroll
;         for (int m = 0; m < 4; ++m) { bf16_t* rowp = base + (size_t)(row0 + ai * 128 + m * 16) * D + col0;
; #pragma unroll
;             for (int bj = 0; bj < 2; ++bj) { const f32x4 v0 = acc[ai][bj][m][0], v1 = acc[ai][bj][m][1];
;                 u32x4 w; w.x = pk2(act_fn<ACT>(v0[0]), act_fn<ACT>(v0[1])); w.y = pk2(act_fn<ACT>(v0[2]), act_fn<ACT>(v0[3]));
;                 w.z = pk2(act_fn<ACT>(v1[0]), act_fn<ACT>(v1[1])); w.w = pk2(act_fn<ACT>(v1[2]), act_fn<ACT>(v1[3]));
;                 *(u32x4*)(rowp + bj * 128) = w; } }
	s_nop 0
	v_pk_mul_f32 v[170:171], v[170:171], s[22:23] op_sel_hi:[1,0]
	v_add_f32_e32 v48, 1.0, v48
	v_cvt_pk_bf16_f32 v163, v170, v171
	v_add_co_u32_e32 v170, vcc, s2, v156
	s_mov_b64 s[2:3], 0x58000
	s_nop 0
	v_addc_co_u32_e32 v171, vcc, 0, v157, vcc
	global_store_dwordx4 v[170:171], v[160:163], off sc1
	s_nop 1
	v_rcp_f32_e32 v160, v48
	v_mul_f32_e32 v48, 0xbfb8aa3b, v25
	v_exp_f32_e32 v48, v48
	s_nop 0
	v_add_f32_e32 v48, 1.0, v48
	v_rcp_f32_e32 v161, v48
	v_mul_f32_e32 v48, 0xbfb8aa3b, v26
	v_exp_f32_e32 v48, v48
	v_pk_mul_f32 v[160:161], v[24:25], v[160:161]
	s_nop 0
	v_pk_mul_f32 v[160:161], v[160:161], s[22:23] op_sel_hi:[1,0]
	v_add_f32_e32 v48, 1.0, v48
	v_rcp_f32_e32 v162, v48
	v_mul_f32_e32 v48, 0xbfb8aa3b, v27
	v_exp_f32_e32 v48, v48
	v_cvt_pk_bf16_f32 v160, v160, v161
	v_add_f32_e32 v48, 1.0, v48
	v_rcp_f32_e32 v163, v48
	v_mul_f32_e32 v48, 0xbfb8aa3b, v16
	v_exp_f32_e32 v48, v48
	v_pk_mul_f32 v[162:163], v[26:27], v[162:163]
	s_nop 0
	v_pk_mul_f32 v[162:163], v[162:163], s[22:23] op_sel_hi:[1,0]
	v_add_f32_e32 v48, 1.0, v48
	v_cvt_pk_bf16_f32 v161, v162, v163
	v_rcp_f32_e32 v162, v48
	v_mul_f32_e32 v48, 0xbfb8aa3b, v17
	v_exp_f32_e32 v48, v48
	s_nop 0
	v_add_f32_e32 v48, 1.0, v48
	v_rcp_f32_e32 v163, v48
	v_mul_f32_e32 v48, 0xbfb8aa3b, v18
	v_exp_f32_e32 v48, v48
	v_pk_mul_f32 v[162:163], v[16:17], v[162:163]
	s_nop 0
	v_pk_mul_f32 v[162:163], v[162:163], s[22:23] op_sel_hi:[1,0]
	v_add_f32_e32 v48, 1.0, v48
	v_rcp_f32_e32 v170, v48
	v_mul_f32_e32 v48, 0xbfb8aa3b, v19
	v_exp_f32_e32 v48, v48
	v_cvt_pk_bf16_f32 v162, v162, v163
	v_add_f32_e32 v48, 1.0, v48
	v_rcp_f32_e32 v171, v48
	v_mul_f32_e32 v48, 0xbfb8aa3b, v12
	v_exp_f32_e32 v48, v48
	v_pk_mul_f32 v[170:171], v[18:19], v[170:171]
	s_nop 0
	v_pk_mul_f32 v[170:171], v[170:171], s[22:23] op_sel_hi:[1,0]
	v_add_f32_e32 v48, 1.0, v48
	v_cvt_pk_bf16_f32 v163, v170, v171
	global_store_dwordx4 v[158:159], v[160:163], off offset:256 sc1
	v_lshl_add_u64 v[158:159], v[156:157], 0, s[2:3]
	s_mov_b32 s2, 0x58000
	v_rcp_f32_e32 v160, v48
	v_mul_f32_e32 v48, 0xbfb8aa3b, v13
	v_exp_f32_e32 v48, v48
	v_add_co_u32_e32 v156, vcc, s2, v156
	v_add_f32_e32 v48, 1.0, v48
	v_rcp_f32_e32 v161, v48
	v_mul_f32_e32 v48, 0xbfb8aa3b, v14
	v_exp_f32_e32 v48, v48
	v_addc_co_u32_e32 v157, vcc, 0, v157, vcc
	v_pk_mul_f32 v[160:161], v[12:13], v[160:161]
	v_add_f32_e32 v48, 1.0, v48
	v_rcp_f32_e32 v162, v48
	v_mul_f32_e32 v48, 0xbfb8aa3b, v15
	v_exp_f32_e32 v48, v48
	v_pk_mul_f32 v[160:161], v[160:161], s[22:23] op_sel_hi:[1,0]
	v_add_f32_e32 v48, 1.0, v48
	v_rcp_f32_e32 v163, v48
	v_mul_f32_e32 v48, 0xbfb8aa3b, v4
	v_exp_f32_e32 v48, v48
	v_cvt_pk_bf16_f32 v160, v160, v161
	v_pk_mul_f32 v[162:163], v[14:15], v[162:163]
	v_add_f32_e32 v48, 1.0, v48
	v_pk_mul_f32 v[162:163], v[162:163], s[22:23] op_sel_hi:[1,0]
	s_nop 0
	v_cvt_pk_bf16_f32 v161, v162, v163
	v_rcp_f32_e32 v162, v48
	v_mul_f32_e32 v48, 0xbfb8aa3b, v5
	v_exp_f32_e32 v48, v48
	s_nop 0
	v_add_f32_e32 v48, 1.0, v48
	v_rcp_f32_e32 v163, v48
	v_mul_f32_e32 v48, 0xbfb8aa3b, v6
	v_exp_f32_e32 v48, v48
	v_pk_mul_f32 v[162:163], v[4:5], v[162:163]
	s_nop 0
	v_pk_mul_f32 v[162:163], v[162:163], s[22:23] op_sel_hi:[1,0]
	v_add_f32_e32 v48, 1.0, v48
	v_rcp_f32_e32 v170, v48
	v_mul_f32_e32 v48, 0xbfb8aa3b, v7
	v_exp_f32_e32 v48, v48
	v_cvt_pk_bf16_f32 v162, v162, v163
	v_add_f32_e32 v48, 1.0, v48
	v_rcp_f32_e32 v171, v48
	v_mul_f32_e32 v48, 0xbfb8aa3b, v8
	v_exp_f32_e32 v48, v48
	v_pk_mul_f32 v[170:171], v[6:7], v[170:171]
	s_nop 0
	v_pk_mul_f32 v[170:171], v[170:171], s[22:23] op_sel_hi:[1,0]
	v_add_f32_e32 v48, 1.0, v48
	v_cvt_pk_bf16_f32 v163, v170, v171
	global_store_dwordx4 v[156:157], v[160:163], off sc1
	v_rcp_f32_e32 v156, v48
	v_mul_f32_e32 v48, 0xbfb8aa3b, v9
	v_exp_f32_e32 v48, v48
	s_nop 0
	v_add_f32_e32 v48, 1.0, v48
	v_rcp_f32_e32 v157, v48
	v_mul_f32_e32 v48, 0xbfb8aa3b, v10
	v_exp_f32_e32 v48, v48
	v_pk_mul_f32 v[156:157], v[8:9], v[156:157]
	s_nop 0
	v_pk_mul_f32 v[156:157], v[156:157], s[22:23] op_sel_hi:[1,0]
	v_add_f32_e32 v48, 1.0, v48
	v_cvt_pk_bf16_f32 v160, v156, v157
	v_rcp_f32_e32 v156, v48
	v_mul_f32_e32 v48, 0xbfb8aa3b, v11
	v_exp_f32_e32 v48, v48
	s_nop 0
	v_add_f32_e32 v48, 1.0, v48
	v_rcp_f32_e32 v157, v48
	v_mul_f32_e32 v48, 0xbfb8aa3b, v0
	v_exp_f32_e32 v48, v48
	v_pk_mul_f32 v[156:157], v[10:11], v[156:157]
	s_nop 0
	v_pk_mul_f32 v[156:157], v[156:157], s[22:23] op_sel_hi:[1,0]
	v_add_f32_e32 v48, 1.0, v48
	v_cvt_pk_bf16_f32 v161, v156, v157
	v_rcp_f32_e32 v156, v48
	v_mul_f32_e32 v48, 0xbfb8aa3b, v1
	v_exp_f32_e32 v48, v48
	s_nop 0
	v_add_f32_e32 v48, 1.0, v48
	v_rcp_f32_e32 v157, v48
	v_mul_f32_e32 v48, 0xbfb8aa3b, v2
	v_exp_f32_e32 v48, v48
	v_pk_mul_f32 v[156:157], v[0:1], v[156:157]
	s_nop 0
	v_pk_mul_f32 v[156:157], v[156:157], s[22:23] op_sel_hi:[1,0]
	v_add_f32_e32 v48, 1.0, v48
	v_cvt_pk_bf16_f32 v162, v156, v157
	v_rcp_f32_e32 v156, v48
	v_mul_f32_e32 v48, 0xbfb8aa3b, v3
	v_exp_f32_e32 v48, v48
	s_nop 0
	v_add_f32_e32 v48, 1.0, v48
	v_rcp_f32_e32 v157, v48
	s_nop 0
	v_pk_mul_f32 v[156:157], v[2:3], v[156:157]
	s_nop 0
	v_pk_mul_f32 v[156:157], v[156:157], s[22:23] op_sel_hi:[1,0]
	s_nop 0
	v_cvt_pk_bf16_f32 v163, v156, v157
	global_store_dwordx4 v[158:159], v[160:163], off offset:256 sc1

; DI unsigned pk2(float lo, float hi) { f32x2 v = {lo, hi}; bf16v2 r = __builtin_convertvector(v, bf16v2); return __builtin_bit_cast(unsigned, r); }
; DI float fexp2(float x) { return __builtin_amdgcn_exp2f(x); }
; DI float frcp(float x) { return __builtin_amdgcn_rcpf(x); }
;     DI void operator()(const f32x4 (&acc)[2][2][4][2], const pg8::Unit& u, int wr, int wc, int fr, int fq) const {
;     ...
;         if (pn >= 32) {
;             bf16_t* sa = g3 + 2 * ARR; bf16_t* rh = g3 + 4 * ARR; const int col0 = 128 * (pn - 32) + cl;
; #pragma unroll
;             for (int ai = 0; ai < 2; ++ai)
; #pragma unroll
;                 for (int m = 0; m < 4; ++m) { const size_t off = (size_t)(row0 + ai * 128 + m * 16) * D + col0;
;                     const f32x4 a0 = acc[ai][0][m][0], a1 = acc[ai][0][m][1], b0 = acc[ai][1][m][0], b1 = acc[ai][1][m][1];
;                     const float av[8] = {a0[0], a0[1], a0[2], a0[3], a1[0], a1[1], a1[2], a1[3]}, bv[8] = {b0[0], b0[1], b0[2], b0[3], b1[0], b1[1], b1[2], b1[3]};
;                     float sg[8], ro[8];
; #pragma unroll
;                     for (int j = 0; j < 8; ++j) { const float da = 1.0f + fexp2(-av[j] * LOG2E), db = 1.0f + fexp2(-bv[j] * LOG2E); sg[j] = frcp(da); ro[j] = fminf(da * frcp(db), 3.0e38f); }
;                     *(u32x4*)(sa + off) = (u32x4){pk2(sg[0], sg[1]), pk2(sg[2], sg[3]), pk2(sg[4], sg[5]), pk2(sg[6], sg[7])};
;                     *(u32x4*)(rh + off) = (u32x4){pk2(ro[0], ro[1]), pk2(ro[2], ro[3]), pk2(ro[4], ro[5]), pk2(ro[6], ro[7])}; }
;             return;
.LBB0_257:
	s_andn2_b64 vcc, exec, s[2:3]
	s_cbranch_vccnz .LBB0_259
	v_mul_f32_e32 v155, 0xbfb8aa3b, v126
	v_exp_f32_e32 v158, v155
	v_mul_f32_e32 v155, 0xbfb8aa3b, v122
	v_exp_f32_e32 v159, v155
	v_ashrrev_i32_e32 v155, 31, v154
	v_lshlrev_b64 v[156:157], 10, v[154:155]
	v_add_f32_e32 v155, 1.0, v158
	v_add_f32_e32 v158, 1.0, v159
	v_mul_f32_e32 v160, 0xbfb8aa3b, v127
	v_mul_f32_e32 v161, 0xbfb8aa3b, v123
	v_rcp_f32_e32 v158, v158
	v_exp_f32_e32 v160, v160
	v_exp_f32_e32 v161, v161
	v_rcp_f32_e32 v159, v155
	v_mul_f32_e32 v155, v155, v158
	v_add_f32_e32 v158, 1.0, v160
	v_add_f32_e32 v160, 1.0, v161
	v_mul_f32_e32 v163, 0xbfb8aa3b, v124
	v_rcp_f32_e32 v160, v160
	v_exp_f32_e32 v163, v163
	v_mul_f32_e32 v162, 0xbfb8aa3b, v128
	v_rcp_f32_e32 v161, v158
	v_exp_f32_e32 v162, v162
	v_mul_f32_e32 v158, v158, v160
	v_add_f32_e32 v160, 1.0, v163
	v_mul_f32_e32 v171, 0xbfb8aa3b, v125
	v_rcp_f32_e32 v160, v160
	v_exp_f32_e32 v171, v171
	v_min_f32_e32 v170, 0x7f61b1e6, v158
	v_add_f32_e32 v158, 1.0, v162
	v_mul_f32_e32 v163, 0xbfb8aa3b, v129
	v_rcp_f32_e32 v162, v158
	v_exp_f32_e32 v163, v163
	v_mul_f32_e32 v158, v158, v160
	v_add_f32_e32 v160, 1.0, v171
	v_mul_f32_e32 v179, 0xbfb8aa3b, v114
	v_rcp_f32_e32 v160, v160
	v_exp_f32_e32 v179, v179
	v_min_f32_e32 v178, 0x7f61b1e6, v158
	v_add_f32_e32 v158, 1.0, v163
	v_mul_f32_e32 v171, 0xbfb8aa3b, v118
	v_rcp_f32_e32 v163, v158
	v_exp_f32_e32 v171, v171
	v_mul_f32_e32 v158, v158, v160
	v_add_f32_e32 v160, 1.0, v179
	v_mul_f32_e32 v181, 0xbfb8aa3b, v115
	v_rcp_f32_e32 v160, v160
	v_exp_f32_e32 v181, v181
	v_min_f32_e32 v180, 0x7f61b1e6, v158
	v_add_f32_e32 v158, 1.0, v171
	v_mul_f32_e32 v179, 0xbfb8aa3b, v119
	v_rcp_f32_e32 v171, v158
	v_exp_f32_e32 v179, v179
	v_mul_f32_e32 v158, v158, v160
	v_add_f32_e32 v160, 1.0, v181
	v_mul_f32_e32 v183, 0xbfb8aa3b, v116
	v_rcp_f32_e32 v160, v160
	v_exp_f32_e32 v183, v183
	v_min_f32_e32 v182, 0x7f61b1e6, v158
	v_add_f32_e32 v158, 1.0, v179
	v_mul_f32_e32 v181, 0xbfb8aa3b, v120
	v_rcp_f32_e32 v179, v158
	v_exp_f32_e32 v181, v181
	v_mul_f32_e32 v158, v158, v160
	v_add_f32_e32 v160, 1.0, v183
	v_rcp_f32_e32 v160, v160
	v_min_f32_e32 v184, 0x7f61b1e6, v158
	v_add_f32_e32 v158, 1.0, v181
	v_mul_f32_e32 v183, 0xbfb8aa3b, v117
	v_rcp_f32_e32 v181, v158
	v_exp_f32_e32 v183, v183
	v_mul_f32_e32 v158, v158, v160
	v_mul_f32_e32 v160, 0xbfb8aa3b, v121
	v_exp_f32_e32 v160, v160
	v_add_f32_e32 v183, 1.0, v183
	v_rcp_f32_e32 v183, v183
	v_min_f32_e32 v185, 0x7f61b1e6, v158
	v_add_f32_e32 v158, 1.0, v160
	v_rcp_f32_e32 v186, v158
	v_lshl_add_u32 v48, s36, 7, v167
	v_lshl_add_u64 v[156:157], v[156:157], 0, v[48:49]
	v_mul_f32_e32 v158, v158, v183
	v_lshlrev_b64 v[156:157], 1, v[156:157]
	v_min_f32_e32 v155, 0x7f61b1e6, v155
	v_min_f32_e32 v183, 0x7f61b1e6, v158
	v_cvt_pk_bf16_f32 v158, v159, v161
	v_cvt_pk_bf16_f32 v159, v162, v163
	v_cvt_pk_bf16_f32 v160, v171, v179
	v_cvt_pk_bf16_f32 v161, v181, v186
	v_lshl_add_u64 v[162:163], s[10:11], 0, v[156:157]
	global_store_dwordx4 v[162:163], v[158:161], off sc1
	v_lshl_add_u64 v[162:163], s[12:13], 0, v[156:157]
	v_mul_f32_e32 v171, 0xbfb8aa3b, v108
	v_cvt_pk_bf16_f32 v158, v155, v170
	v_cvt_pk_bf16_f32 v159, v178, v180
	v_cvt_pk_bf16_f32 v160, v182, v184
	v_cvt_pk_bf16_f32 v161, v185, v183
	global_store_dwordx4 v[162:163], v[158:161], off sc1
	v_mul_f32_e32 v155, 0xbfb8aa3b, v110
	v_exp_f32_e32 v155, v155
	v_mul_f32_e32 v159, 0xbfb8aa3b, v106
	v_exp_f32_e32 v160, v159
	v_mul_f32_e32 v162, 0xbfb8aa3b, v111
	v_mul_f32_e32 v163, 0xbfb8aa3b, v107
	v_exp_f32_e32 v162, v162
	v_add_f32_e32 v160, 1.0, v160
	v_rcp_f32_e32 v160, v160
	v_exp_f32_e32 v163, v163
	v_add_f32_e32 v155, 1.0, v155
	v_rcp_f32_e32 v161, v155
	v_mul_f32_e32 v155, v155, v160
	v_add_f32_e32 v160, 1.0, v162
	v_add_f32_e32 v162, 1.0, v163
	v_rcp_f32_e32 v162, v162
	v_exp_f32_e32 v171, v171
	v_mul_f32_e32 v163, 0xbfb8aa3b, v112
	v_exp_f32_e32 v163, v163
	v_rcp_f32_e32 v170, v160
	v_mul_f32_e32 v160, v160, v162
	v_add_f32_e32 v162, 1.0, v171
	v_mul_f32_e32 v179, 0xbfb8aa3b, v109
	v_rcp_f32_e32 v162, v162
	v_exp_f32_e32 v179, v179
	v_min_f32_e32 v178, 0x7f61b1e6, v160
	v_add_f32_e32 v160, 1.0, v163
	v_mul_f32_e32 v163, 0xbfb8aa3b, v113
	v_exp_f32_e32 v163, v163
	v_rcp_f32_e32 v171, v160
	v_mul_f32_e32 v160, v160, v162
	v_add_f32_e32 v162, 1.0, v179
	v_mul_f32_e32 v181, 0xbfb8aa3b, v98
	v_rcp_f32_e32 v162, v162
	v_exp_f32_e32 v181, v181
	v_min_f32_e32 v180, 0x7f61b1e6, v160
	v_add_f32_e32 v160, 1.0, v163
	v_mul_f32_e32 v163, 0xbfb8aa3b, v102
	v_exp_f32_e32 v163, v163
	v_rcp_f32_e32 v179, v160
	v_mul_f32_e32 v160, v160, v162
	v_add_f32_e32 v162, 1.0, v181
	v_mul_f32_e32 v183, 0xbfb8aa3b, v99
	v_rcp_f32_e32 v162, v162
	v_exp_f32_e32 v183, v183
	v_min_f32_e32 v182, 0x7f61b1e6, v160
	v_add_f32_e32 v160, 1.0, v163
	v_mul_f32_e32 v163, 0xbfb8aa3b, v103
	v_exp_f32_e32 v163, v163
	v_rcp_f32_e32 v181, v160
	v_mul_f32_e32 v160, v160, v162
	v_add_f32_e32 v162, 1.0, v183
	v_mul_f32_e32 v185, 0xbfb8aa3b, v100
	v_rcp_f32_e32 v162, v162
	v_exp_f32_e32 v185, v185
	v_min_f32_e32 v184, 0x7f61b1e6, v160
	v_add_f32_e32 v160, 1.0, v163
	v_mul_f32_e32 v163, 0xbfb8aa3b, v104
	v_exp_f32_e32 v163, v163
	v_rcp_f32_e32 v183, v160
	v_mul_f32_e32 v160, v160, v162
	v_add_f32_e32 v162, 1.0, v185
	v_rcp_f32_e32 v162, v162
	v_min_f32_e32 v186, 0x7f61b1e6, v160
	v_add_f32_e32 v160, 1.0, v163
	v_mul_f32_e32 v163, 0xbfb8aa3b, v101
	v_exp_f32_e32 v163, v163
	v_rcp_f32_e32 v185, v160
	v_mul_f32_e32 v160, v160, v162
	v_mul_f32_e32 v162, 0xbfb8aa3b, v105
	v_exp_f32_e32 v162, v162
	v_add_f32_e32 v163, 1.0, v163
	v_rcp_f32_e32 v163, v163
	v_or_b32_e32 v158, 16, v154
	v_min_f32_e32 v187, 0x7f61b1e6, v160
; DI unsigned pk2(float lo, float hi) { f32x2 v = {lo, hi}; bf16v2 r = __builtin_convertvector(v, bf16v2); return __builtin_bit_cast(unsigned, r); }
; DI float fexp2(float x) { return __builtin_amdgcn_exp2f(x); }
; DI float frcp(float x) { return __builtin_amdgcn_rcpf(x); }
;     DI void operator()(const f32x4 (&acc)[2][2][4][2], const pg8::Unit& u, int wr, int wc, int fr, int fq) const {
;     ...
;         if (pn >= 32) {
;             bf16_t* sa = g3 + 2 * ARR; bf16_t* rh = g3 + 4 * ARR; const int col0 = 128 * (pn - 32) + cl;
; #pragma unroll
;             for (int ai = 0; ai < 2; ++ai)
; #pragma unroll
;                 for (int m = 0; m < 4; ++m) { const size_t off = (size_t)(row0 + ai * 128 + m * 16) * D + col0;
;                     const f32x4 a0 = acc[ai][0][m][0], a1 = acc[ai][0][m][1], b0 = acc[ai][1][m][0], b1 = acc[ai][1][m][1];
;                     const float av[8] = {a0[0], a0[1], a0[2], a0[3], a1[0], a1[1], a1[2], a1[3]}, bv[8] = {b0[0], b0[1], b0[2], b0[3], b1[0], b1[1], b1[2], b1[3]};
;                     float sg[8], ro[8];
; #pragma unroll
;                     for (int j = 0; j < 8; ++j) { const float da = 1.0f + fexp2(-av[j] * LOG2E), db = 1.0f + fexp2(-bv[j] * LOG2E); sg[j] = frcp(da); ro[j] = fminf(da * frcp(db), 3.0e38f); }
;                     *(u32x4*)(sa + off) = (u32x4){pk2(sg[0], sg[1]), pk2(sg[2], sg[3]), pk2(sg[4], sg[5]), pk2(sg[6], sg[7])};
;                     *(u32x4*)(rh + off) = (u32x4){pk2(ro[0], ro[1]), pk2(ro[2], ro[3]), pk2(ro[4], ro[5]), pk2(ro[6], ro[7])}; }
;             return;
	v_add_f32_e32 v160, 1.0, v162
	v_ashrrev_i32_e32 v159, 31, v158
	v_rcp_f32_e32 v188, v160
	v_lshlrev_b64 v[158:159], 10, v[158:159]
	v_mul_f32_e32 v160, v160, v163
	v_lshl_add_u64 v[162:163], v[158:159], 0, v[48:49]
	v_lshlrev_b64 v[162:163], 1, v[162:163]
	v_min_f32_e32 v155, 0x7f61b1e6, v155
	v_min_f32_e32 v189, 0x7f61b1e6, v160
	v_cvt_pk_bf16_f32 v158, v161, v170
	v_cvt_pk_bf16_f32 v159, v171, v179
	v_cvt_pk_bf16_f32 v160, v181, v183
	v_cvt_pk_bf16_f32 v161, v185, v188
	v_lshl_add_u64 v[170:171], s[10:11], 0, v[162:163]
	global_store_dwordx4 v[170:171], v[158:161], off sc1
	v_lshl_add_u64 v[162:163], s[12:13], 0, v[162:163]
	v_mul_f32_e32 v171, 0xbfb8aa3b, v92
	v_cvt_pk_bf16_f32 v158, v155, v178
	v_cvt_pk_bf16_f32 v159, v180, v182
	v_cvt_pk_bf16_f32 v160, v184, v186
	v_cvt_pk_bf16_f32 v161, v187, v189
	global_store_dwordx4 v[162:163], v[158:161], off sc1
	v_mul_f32_e32 v155, 0xbfb8aa3b, v94
	v_exp_f32_e32 v155, v155
	v_mul_f32_e32 v159, 0xbfb8aa3b, v90
	v_exp_f32_e32 v160, v159
	v_mul_f32_e32 v162, 0xbfb8aa3b, v95
	v_mul_f32_e32 v163, 0xbfb8aa3b, v91
	v_exp_f32_e32 v162, v162
	v_add_f32_e32 v160, 1.0, v160
	v_rcp_f32_e32 v160, v160
	v_exp_f32_e32 v163, v163
	v_add_f32_e32 v155, 1.0, v155
	v_rcp_f32_e32 v161, v155
	v_mul_f32_e32 v155, v155, v160
	v_add_f32_e32 v160, 1.0, v162
	v_add_f32_e32 v162, 1.0, v163
	v_rcp_f32_e32 v162, v162
	v_exp_f32_e32 v171, v171
	v_mul_f32_e32 v163, 0xbfb8aa3b, v96
	v_exp_f32_e32 v163, v163
	v_rcp_f32_e32 v170, v160
	v_mul_f32_e32 v160, v160, v162
	v_add_f32_e32 v162, 1.0, v171
	v_mul_f32_e32 v179, 0xbfb8aa3b, v93
	v_rcp_f32_e32 v162, v162
	v_exp_f32_e32 v179, v179
	v_min_f32_e32 v178, 0x7f61b1e6, v160
	v_add_f32_e32 v160, 1.0, v163
	v_mul_f32_e32 v163, 0xbfb8aa3b, v97
	v_exp_f32_e32 v163, v163
	v_rcp_f32_e32 v171, v160
	v_mul_f32_e32 v160, v160, v162
	v_add_f32_e32 v162, 1.0, v179
	v_mul_f32_e32 v181, 0xbfb8aa3b, v82
	v_rcp_f32_e32 v162, v162
	v_exp_f32_e32 v181, v181
	v_min_f32_e32 v180, 0x7f61b1e6, v160
	v_add_f32_e32 v160, 1.0, v163
	v_mul_f32_e32 v163, 0xbfb8aa3b, v86
	v_exp_f32_e32 v163, v163
	v_rcp_f32_e32 v179, v160
	v_mul_f32_e32 v160, v160, v162
	v_add_f32_e32 v162, 1.0, v181
	v_mul_f32_e32 v183, 0xbfb8aa3b, v83
	v_rcp_f32_e32 v162, v162
	v_exp_f32_e32 v183, v183
	v_min_f32_e32 v182, 0x7f61b1e6, v160
	v_add_f32_e32 v160, 1.0, v163
	v_mul_f32_e32 v163, 0xbfb8aa3b, v87
	v_exp_f32_e32 v163, v163
	v_rcp_f32_e32 v181, v160
	v_mul_f32_e32 v160, v160, v162
	v_add_f32_e32 v162, 1.0, v183
	v_mul_f32_e32 v185, 0xbfb8aa3b, v84
	v_rcp_f32_e32 v162, v162
	v_exp_f32_e32 v185, v185
	v_min_f32_e32 v184, 0x7f61b1e6, v160
	v_add_f32_e32 v160, 1.0, v163
	v_mul_f32_e32 v163, 0xbfb8aa3b, v88
	v_exp_f32_e32 v163, v163
	v_rcp_f32_e32 v183, v160
	v_mul_f32_e32 v160, v160, v162
	v_add_f32_e32 v162, 1.0, v185
	v_rcp_f32_e32 v162, v162
	v_min_f32_e32 v186, 0x7f61b1e6, v160
	v_add_f32_e32 v160, 1.0, v163
	v_mul_f32_e32 v163, 0xbfb8aa3b, v85
	v_exp_f32_e32 v163, v163
	v_rcp_f32_e32 v185, v160
	v_mul_f32_e32 v160, v160, v162
	v_mul_f32_e32 v162, 0xbfb8aa3b, v89
	v_exp_f32_e32 v162, v162
	v_add_f32_e32 v163, 1.0, v163
	v_rcp_f32_e32 v163, v163
	v_or_b32_e32 v158, 32, v154
	v_min_f32_e32 v187, 0x7f61b1e6, v160
	v_add_f32_e32 v160, 1.0, v162
	v_ashrrev_i32_e32 v159, 31, v158
	v_rcp_f32_e32 v188, v160
	v_lshlrev_b64 v[158:159], 10, v[158:159]
	v_mul_f32_e32 v160, v160, v163
	v_lshl_add_u64 v[162:163], v[158:159], 0, v[48:49]
	v_lshlrev_b64 v[162:163], 1, v[162:163]
	v_min_f32_e32 v155, 0x7f61b1e6, v155
	v_min_f32_e32 v189, 0x7f61b1e6, v160
	v_cvt_pk_bf16_f32 v158, v161, v170
	v_cvt_pk_bf16_f32 v159, v171, v179
	v_cvt_pk_bf16_f32 v160, v181, v183
	v_cvt_pk_bf16_f32 v161, v185, v188
	v_lshl_add_u64 v[170:171], s[10:11], 0, v[162:163]
	global_store_dwordx4 v[170:171], v[158:161], off sc1
	v_lshl_add_u64 v[162:163], s[12:13], 0, v[162:163]
	v_mul_f32_e32 v171, 0xbfb8aa3b, v76
	v_cvt_pk_bf16_f32 v158, v155, v178
	v_cvt_pk_bf16_f32 v159, v180, v182
	v_cvt_pk_bf16_f32 v160, v184, v186
	v_cvt_pk_bf16_f32 v161, v187, v189
	global_store_dwordx4 v[162:163], v[158:161], off sc1
	v_mul_f32_e32 v155, 0xbfb8aa3b, v78
	v_exp_f32_e32 v155, v155
	v_mul_f32_e32 v159, 0xbfb8aa3b, v74
	v_exp_f32_e32 v160, v159
	v_mul_f32_e32 v162, 0xbfb8aa3b, v79
	v_mul_f32_e32 v163, 0xbfb8aa3b, v75
	v_exp_f32_e32 v162, v162
	v_add_f32_e32 v160, 1.0, v160
	v_rcp_f32_e32 v160, v160
	v_exp_f32_e32 v163, v163
	v_add_f32_e32 v155, 1.0, v155
	v_rcp_f32_e32 v161, v155
	v_mul_f32_e32 v155, v155, v160
	v_add_f32_e32 v160, 1.0, v162
	v_add_f32_e32 v162, 1.0, v163
	v_rcp_f32_e32 v162, v162
	v_exp_f32_e32 v171, v171
	v_mul_f32_e32 v163, 0xbfb8aa3b, v80
	v_exp_f32_e32 v163, v163
	v_rcp_f32_e32 v170, v160
	v_mul_f32_e32 v160, v160, v162
	v_add_f32_e32 v162, 1.0, v171
	v_mul_f32_e32 v179, 0xbfb8aa3b, v77
	v_rcp_f32_e32 v162, v162
	v_exp_f32_e32 v179, v179
	v_min_f32_e32 v178, 0x7f61b1e6, v160
	v_add_f32_e32 v160, 1.0, v163
	v_mul_f32_e32 v163, 0xbfb8aa3b, v81
	v_exp_f32_e32 v163, v163
	v_rcp_f32_e32 v171, v160
	v_mul_f32_e32 v160, v160, v162
	v_add_f32_e32 v162, 1.0, v179
	v_mul_f32_e32 v181, 0xbfb8aa3b, v66
	v_rcp_f32_e32 v162, v162
	v_exp_f32_e32 v181, v181
	v_min_f32_e32 v180, 0x7f61b1e6, v160
	v_add_f32_e32 v160, 1.0, v163
	v_mul_f32_e32 v163, 0xbfb8aa3b, v70
	v_exp_f32_e32 v163, v163
	v_rcp_f32_e32 v179, v160
	v_mul_f32_e32 v160, v160, v162
	v_add_f32_e32 v162, 1.0, v181
	v_mul_f32_e32 v183, 0xbfb8aa3b, v67
	v_rcp_f32_e32 v162, v162
	v_exp_f32_e32 v183, v183
	v_min_f32_e32 v182, 0x7f61b1e6, v160
	v_add_f32_e32 v160, 1.0, v163
	v_mul_f32_e32 v163, 0xbfb8aa3b, v71
	v_exp_f32_e32 v163, v163
	v_rcp_f32_e32 v181, v160
	v_mul_f32_e32 v160, v160, v162
	v_add_f32_e32 v162, 1.0, v183
; DI unsigned pk2(float lo, float hi) { f32x2 v = {lo, hi}; bf16v2 r = __builtin_convertvector(v, bf16v2); return __builtin_bit_cast(unsigned, r); }
; DI float fexp2(float x) { return __builtin_amdgcn_exp2f(x); }
; DI float frcp(float x) { return __builtin_amdgcn_rcpf(x); }
;     DI void operator()(const f32x4 (&acc)[2][2][4][2], const pg8::Unit& u, int wr, int wc, int fr, int fq) const {
;     ...
;         if (pn >= 32) {
;             bf16_t* sa = g3 + 2 * ARR; bf16_t* rh = g3 + 4 * ARR; const int col0 = 128 * (pn - 32) + cl;
; #pragma unroll
;             for (int ai = 0; ai < 2; ++ai)
; #pragma unroll
;                 for (int m = 0; m < 4; ++m) { const size_t off = (size_t)(row0 + ai * 128 + m * 16) * D + col0;
;                     const f32x4 a0 = acc[ai][0][m][0], a1 = acc[ai][0][m][1], b0 = acc[ai][1][m][0], b1 = acc[ai][1][m][1];
;                     const float av[8] = {a0[0], a0[1], a0[2], a0[3], a1[0], a1[1], a1[2], a1[3]}, bv[8] = {b0[0], b0[1], b0[2], b0[3], b1[0], b1[1], b1[2], b1[3]};
;                     float sg[8], ro[8];
; #pragma unroll
;                     for (int j = 0; j < 8; ++j) { const float da = 1.0f + fexp2(-av[j] * LOG2E), db = 1.0f + fexp2(-bv[j] * LOG2E); sg[j] = frcp(da); ro[j] = fminf(da * frcp(db), 3.0e38f); }
;                     *(u32x4*)(sa + off) = (u32x4){pk2(sg[0], sg[1]), pk2(sg[2], sg[3]), pk2(sg[4], sg[5]), pk2(sg[6], sg[7])};
;                     *(u32x4*)(rh + off) = (u32x4){pk2(ro[0], ro[1]), pk2(ro[2], ro[3]), pk2(ro[4], ro[5]), pk2(ro[6], ro[7])}; }
;             return;
	v_mul_f32_e32 v185, 0xbfb8aa3b, v68
	v_rcp_f32_e32 v162, v162
	v_exp_f32_e32 v185, v185
	v_min_f32_e32 v184, 0x7f61b1e6, v160
	v_add_f32_e32 v160, 1.0, v163
	v_mul_f32_e32 v163, 0xbfb8aa3b, v72
	v_exp_f32_e32 v163, v163
	v_rcp_f32_e32 v183, v160
	v_mul_f32_e32 v160, v160, v162
	v_add_f32_e32 v162, 1.0, v185
	v_rcp_f32_e32 v162, v162
	v_min_f32_e32 v186, 0x7f61b1e6, v160
	v_add_f32_e32 v160, 1.0, v163
	v_mul_f32_e32 v163, 0xbfb8aa3b, v69
	v_exp_f32_e32 v163, v163
	v_rcp_f32_e32 v185, v160
	v_mul_f32_e32 v160, v160, v162
	v_mul_f32_e32 v162, 0xbfb8aa3b, v73
	v_exp_f32_e32 v162, v162
	v_add_f32_e32 v163, 1.0, v163
	v_rcp_f32_e32 v163, v163
	v_or_b32_e32 v158, 48, v154
	v_min_f32_e32 v187, 0x7f61b1e6, v160
	v_add_f32_e32 v160, 1.0, v162
	v_ashrrev_i32_e32 v159, 31, v158
	v_rcp_f32_e32 v188, v160
	v_lshlrev_b64 v[158:159], 10, v[158:159]
	v_mul_f32_e32 v160, v160, v163
	v_lshl_add_u64 v[162:163], v[158:159], 0, v[48:49]
	v_lshlrev_b64 v[162:163], 1, v[162:163]
	v_min_f32_e32 v155, 0x7f61b1e6, v155
	v_min_f32_e32 v189, 0x7f61b1e6, v160
	v_cvt_pk_bf16_f32 v158, v161, v170
	v_cvt_pk_bf16_f32 v159, v171, v179
	v_cvt_pk_bf16_f32 v160, v181, v183
	v_cvt_pk_bf16_f32 v161, v185, v188
	v_lshl_add_u64 v[170:171], s[10:11], 0, v[162:163]
	global_store_dwordx4 v[170:171], v[158:161], off sc1
	v_mul_f32_e32 v48, 0xbfb8aa3b, v62
	v_lshl_add_u64 v[162:163], s[12:13], 0, v[162:163]
	v_cvt_pk_bf16_f32 v158, v155, v178
	v_mul_f32_e32 v155, 0xbfb8aa3b, v58
	v_exp_f32_e32 v155, v155
	v_cvt_pk_bf16_f32 v159, v180, v182
	v_cvt_pk_bf16_f32 v160, v184, v186
	v_cvt_pk_bf16_f32 v161, v187, v189
	v_exp_f32_e32 v48, v48
	global_store_dwordx4 v[162:163], v[158:161], off sc1
	v_add_f32_e32 v155, 1.0, v155
	v_rcp_f32_e32 v155, v155
	v_mul_f32_e32 v159, 0xbfb8aa3b, v63
	v_mul_f32_e32 v160, 0xbfb8aa3b, v59
	v_exp_f32_e32 v159, v159
	v_exp_f32_e32 v160, v160
	v_add_f32_e32 v48, 1.0, v48
	v_rcp_f32_e32 v158, v48
	v_mul_f32_e32 v48, v48, v155
	v_add_f32_e32 v155, 1.0, v159
	v_add_f32_e32 v159, 1.0, v160
	v_mul_f32_e32 v161, 0xbfb8aa3b, v64
	v_mul_f32_e32 v162, 0xbfb8aa3b, v60
	v_rcp_f32_e32 v159, v159
	v_exp_f32_e32 v161, v161
	v_exp_f32_e32 v162, v162
	v_rcp_f32_e32 v160, v155
	v_mul_f32_e32 v155, v155, v159
	v_add_f32_e32 v159, 1.0, v161
	v_add_f32_e32 v161, 1.0, v162
	v_mul_f32_e32 v170, 0xbfb8aa3b, v61
	v_rcp_f32_e32 v161, v161
	v_exp_f32_e32 v170, v170
	v_mul_f32_e32 v163, 0xbfb8aa3b, v65
	v_rcp_f32_e32 v162, v159
	v_exp_f32_e32 v163, v163
	v_mul_f32_e32 v159, v159, v161
	v_add_f32_e32 v161, 1.0, v170
	v_mul_f32_e32 v171, 0xbfb8aa3b, v50
	v_rcp_f32_e32 v161, v161
	v_exp_f32_e32 v171, v171
	v_min_f32_e32 v178, 0x7f61b1e6, v159
	v_add_f32_e32 v159, 1.0, v163
	v_mul_f32_e32 v170, 0xbfb8aa3b, v54
	v_rcp_f32_e32 v163, v159
	v_exp_f32_e32 v170, v170
	v_mul_f32_e32 v159, v159, v161
	v_add_f32_e32 v161, 1.0, v171
	v_mul_f32_e32 v180, 0xbfb8aa3b, v51
	v_rcp_f32_e32 v161, v161
	v_exp_f32_e32 v180, v180
	v_min_f32_e32 v179, 0x7f61b1e6, v159
	v_add_f32_e32 v159, 1.0, v170
	v_mul_f32_e32 v171, 0xbfb8aa3b, v55
	v_rcp_f32_e32 v170, v159
	v_exp_f32_e32 v171, v171
	v_mul_f32_e32 v159, v159, v161
	v_add_f32_e32 v161, 1.0, v180
	v_mul_f32_e32 v182, 0xbfb8aa3b, v52
	v_rcp_f32_e32 v161, v161
	v_exp_f32_e32 v182, v182
	v_min_f32_e32 v181, 0x7f61b1e6, v159
	v_add_f32_e32 v159, 1.0, v171
	v_mul_f32_e32 v180, 0xbfb8aa3b, v56
	v_rcp_f32_e32 v171, v159
	v_exp_f32_e32 v180, v180
	v_mul_f32_e32 v159, v159, v161
	v_add_f32_e32 v161, 1.0, v182
	v_rcp_f32_e32 v161, v161
	v_mul_f32_e32 v182, 0xbfb8aa3b, v53
	v_min_f32_e32 v183, 0x7f61b1e6, v159
	v_add_f32_e32 v159, 1.0, v180
	v_exp_f32_e32 v182, v182
	v_rcp_f32_e32 v180, v159
	v_mul_f32_e32 v159, v159, v161
	v_mul_f32_e32 v161, 0xbfb8aa3b, v57
	v_exp_f32_e32 v161, v161
	v_add_f32_e32 v182, 1.0, v182
	v_rcp_f32_e32 v182, v182
	v_min_f32_e32 v184, 0x7f61b1e6, v159
	v_add_f32_e32 v159, 1.0, v161
	v_rcp_f32_e32 v161, v159
	v_mul_f32_e32 v159, v159, v182
	s_mov_b64 s[2:3], 0x40000
	v_min_f32_e32 v182, 0x7f61b1e6, v159
	v_cvt_pk_bf16_f32 v159, v162, v163
	v_lshl_add_u64 v[162:163], v[156:157], 0, s[2:3]
	v_min_f32_e32 v48, 0x7f61b1e6, v48
	v_min_f32_e32 v155, 0x7f61b1e6, v155
	v_cvt_pk_bf16_f32 v158, v158, v160
	v_cvt_pk_bf16_f32 v160, v170, v171
	v_cvt_pk_bf16_f32 v161, v180, v161
	v_lshl_add_u64 v[170:171], s[10:11], 0, v[162:163]
	global_store_dwordx4 v[170:171], v[158:161], off sc1
	v_lshl_add_u64 v[162:163], s[12:13], 0, v[162:163]
	v_mul_f32_e32 v170, 0xbfb8aa3b, v43
	v_cvt_pk_bf16_f32 v158, v48, v155
	v_mul_f32_e32 v155, 0xbfb8aa3b, v40
	v_exp_f32_e32 v155, v155
	v_cvt_pk_bf16_f32 v159, v178, v179
	v_cvt_pk_bf16_f32 v160, v181, v183
	v_cvt_pk_bf16_f32 v161, v184, v182
	v_mul_f32_e32 v48, 0xbfb8aa3b, v44
	v_exp_f32_e32 v48, v48
	global_store_dwordx4 v[162:163], v[158:161], off sc1
	v_add_f32_e32 v155, 1.0, v155
	v_rcp_f32_e32 v155, v155
	v_mul_f32_e32 v159, 0xbfb8aa3b, v45
	v_mul_f32_e32 v160, 0xbfb8aa3b, v41
	v_exp_f32_e32 v159, v159
	v_exp_f32_e32 v160, v160
	v_add_f32_e32 v48, 1.0, v48
	v_rcp_f32_e32 v158, v48
	v_mul_f32_e32 v48, v48, v155
	v_add_f32_e32 v155, 1.0, v159
	v_add_f32_e32 v159, 1.0, v160
	v_mul_f32_e32 v161, 0xbfb8aa3b, v46
	v_mul_f32_e32 v162, 0xbfb8aa3b, v42
	v_rcp_f32_e32 v159, v159
	v_exp_f32_e32 v161, v161
	v_exp_f32_e32 v162, v162
	v_rcp_f32_e32 v160, v155
	v_mul_f32_e32 v155, v155, v159
	v_add_f32_e32 v159, 1.0, v161
	v_add_f32_e32 v161, 1.0, v162
	v_rcp_f32_e32 v161, v161
	v_exp_f32_e32 v170, v170
	v_mul_f32_e32 v163, 0xbfb8aa3b, v47
	v_rcp_f32_e32 v162, v159
	v_exp_f32_e32 v163, v163
	v_mul_f32_e32 v159, v159, v161
	v_add_f32_e32 v161, 1.0, v170
	v_mul_f32_e32 v171, 0xbfb8aa3b, v32
	v_rcp_f32_e32 v161, v161
	v_exp_f32_e32 v171, v171
; DI unsigned pk2(float lo, float hi) { f32x2 v = {lo, hi}; bf16v2 r = __builtin_convertvector(v, bf16v2); return __builtin_bit_cast(unsigned, r); }
; DI float fexp2(float x) { return __builtin_amdgcn_exp2f(x); }
; DI float frcp(float x) { return __builtin_amdgcn_rcpf(x); }
;     DI void operator()(const f32x4 (&acc)[2][2][4][2], const pg8::Unit& u, int wr, int wc, int fr, int fq) const {
;     ...
;         if (pn >= 32) {
;             bf16_t* sa = g3 + 2 * ARR; bf16_t* rh = g3 + 4 * ARR; const int col0 = 128 * (pn - 32) + cl;
; #pragma unroll
;             for (int ai = 0; ai < 2; ++ai)
; #pragma unroll
;                 for (int m = 0; m < 4; ++m) { const size_t off = (size_t)(row0 + ai * 128 + m * 16) * D + col0;
;                     const f32x4 a0 = acc[ai][0][m][0], a1 = acc[ai][0][m][1], b0 = acc[ai][1][m][0], b1 = acc[ai][1][m][1];
;                     const float av[8] = {a0[0], a0[1], a0[2], a0[3], a1[0], a1[1], a1[2], a1[3]}, bv[8] = {b0[0], b0[1], b0[2], b0[3], b1[0], b1[1], b1[2], b1[3]};
;                     float sg[8], ro[8];
; #pragma unroll
;                     for (int j = 0; j < 8; ++j) { const float da = 1.0f + fexp2(-av[j] * LOG2E), db = 1.0f + fexp2(-bv[j] * LOG2E); sg[j] = frcp(da); ro[j] = fminf(da * frcp(db), 3.0e38f); }
;                     *(u32x4*)(sa + off) = (u32x4){pk2(sg[0], sg[1]), pk2(sg[2], sg[3]), pk2(sg[4], sg[5]), pk2(sg[6], sg[7])};
;                     *(u32x4*)(rh + off) = (u32x4){pk2(ro[0], ro[1]), pk2(ro[2], ro[3]), pk2(ro[4], ro[5]), pk2(ro[6], ro[7])}; }
;             return;
	v_min_f32_e32 v178, 0x7f61b1e6, v159
	v_add_f32_e32 v159, 1.0, v163
	v_mul_f32_e32 v170, 0xbfb8aa3b, v36
	v_rcp_f32_e32 v163, v159
	v_exp_f32_e32 v170, v170
	v_mul_f32_e32 v159, v159, v161
	v_add_f32_e32 v161, 1.0, v171
	v_mul_f32_e32 v180, 0xbfb8aa3b, v33
	v_rcp_f32_e32 v161, v161
	v_exp_f32_e32 v180, v180
	v_min_f32_e32 v179, 0x7f61b1e6, v159
	v_add_f32_e32 v159, 1.0, v170
	v_mul_f32_e32 v171, 0xbfb8aa3b, v37
	v_rcp_f32_e32 v170, v159
	v_exp_f32_e32 v171, v171
	v_mul_f32_e32 v159, v159, v161
	v_add_f32_e32 v161, 1.0, v180
	v_mul_f32_e32 v182, 0xbfb8aa3b, v34
	v_rcp_f32_e32 v161, v161
	v_exp_f32_e32 v182, v182
	v_min_f32_e32 v181, 0x7f61b1e6, v159
	v_add_f32_e32 v159, 1.0, v171
	v_mul_f32_e32 v180, 0xbfb8aa3b, v38
	v_rcp_f32_e32 v171, v159
	v_exp_f32_e32 v180, v180
	v_mul_f32_e32 v159, v159, v161
	v_add_f32_e32 v161, 1.0, v182
	v_rcp_f32_e32 v161, v161
	v_mul_f32_e32 v182, 0xbfb8aa3b, v35
	v_min_f32_e32 v183, 0x7f61b1e6, v159
	v_add_f32_e32 v159, 1.0, v180
	v_exp_f32_e32 v182, v182
	v_rcp_f32_e32 v180, v159
	v_mul_f32_e32 v159, v159, v161
	v_mul_f32_e32 v161, 0xbfb8aa3b, v39
	v_exp_f32_e32 v161, v161
	v_add_f32_e32 v182, 1.0, v182
	v_rcp_f32_e32 v182, v182
	v_min_f32_e32 v184, 0x7f61b1e6, v159
	v_add_f32_e32 v159, 1.0, v161
	v_rcp_f32_e32 v161, v159
	v_mul_f32_e32 v159, v159, v182
	s_mov_b64 s[2:3], 0x48000
	v_min_f32_e32 v182, 0x7f61b1e6, v159
	v_cvt_pk_bf16_f32 v159, v162, v163
	v_lshl_add_u64 v[162:163], v[156:157], 0, s[2:3]
	v_min_f32_e32 v48, 0x7f61b1e6, v48
	v_min_f32_e32 v155, 0x7f61b1e6, v155
	v_cvt_pk_bf16_f32 v158, v158, v160
	v_cvt_pk_bf16_f32 v160, v170, v171
	v_cvt_pk_bf16_f32 v161, v180, v161
	v_lshl_add_u64 v[170:171], s[10:11], 0, v[162:163]
	global_store_dwordx4 v[170:171], v[158:161], off sc1
	v_lshl_add_u64 v[162:163], s[12:13], 0, v[162:163]
	v_mul_f32_e32 v170, 0xbfb8aa3b, v27
	v_cvt_pk_bf16_f32 v158, v48, v155
	v_mul_f32_e32 v155, 0xbfb8aa3b, v24
	v_exp_f32_e32 v155, v155
	v_cvt_pk_bf16_f32 v159, v178, v179
	v_cvt_pk_bf16_f32 v160, v181, v183
	v_cvt_pk_bf16_f32 v161, v184, v182
	v_mul_f32_e32 v48, 0xbfb8aa3b, v28
	v_exp_f32_e32 v48, v48
	global_store_dwordx4 v[162:163], v[158:161], off sc1
	v_add_f32_e32 v155, 1.0, v155
	v_rcp_f32_e32 v155, v155
	v_mul_f32_e32 v159, 0xbfb8aa3b, v29
	v_mul_f32_e32 v160, 0xbfb8aa3b, v25
	v_exp_f32_e32 v159, v159
	v_exp_f32_e32 v160, v160
	v_add_f32_e32 v48, 1.0, v48
	v_rcp_f32_e32 v158, v48
	v_mul_f32_e32 v48, v48, v155
	v_add_f32_e32 v155, 1.0, v159
	v_add_f32_e32 v159, 1.0, v160
	v_mul_f32_e32 v161, 0xbfb8aa3b, v30
	v_mul_f32_e32 v162, 0xbfb8aa3b, v26
	v_rcp_f32_e32 v159, v159
	v_exp_f32_e32 v161, v161
	v_exp_f32_e32 v162, v162
	v_rcp_f32_e32 v160, v155
	v_mul_f32_e32 v155, v155, v159
	v_add_f32_e32 v159, 1.0, v161
	v_add_f32_e32 v161, 1.0, v162
	v_rcp_f32_e32 v161, v161
	v_exp_f32_e32 v170, v170
	v_mul_f32_e32 v163, 0xbfb8aa3b, v31
	v_rcp_f32_e32 v162, v159
	v_exp_f32_e32 v163, v163
	v_mul_f32_e32 v159, v159, v161
	v_add_f32_e32 v161, 1.0, v170
	v_mul_f32_e32 v171, 0xbfb8aa3b, v16
	v_rcp_f32_e32 v161, v161
	v_exp_f32_e32 v171, v171
	v_min_f32_e32 v178, 0x7f61b1e6, v159
	v_add_f32_e32 v159, 1.0, v163
	v_mul_f32_e32 v170, 0xbfb8aa3b, v20
	v_rcp_f32_e32 v163, v159
	v_exp_f32_e32 v170, v170
	v_mul_f32_e32 v159, v159, v161
	v_add_f32_e32 v161, 1.0, v171
	v_mul_f32_e32 v180, 0xbfb8aa3b, v17
	v_rcp_f32_e32 v161, v161
	v_exp_f32_e32 v180, v180
	v_min_f32_e32 v179, 0x7f61b1e6, v159
	v_add_f32_e32 v159, 1.0, v170
	v_mul_f32_e32 v171, 0xbfb8aa3b, v21
	v_rcp_f32_e32 v170, v159
	v_exp_f32_e32 v171, v171
	v_mul_f32_e32 v159, v159, v161
	v_add_f32_e32 v161, 1.0, v180
	v_mul_f32_e32 v182, 0xbfb8aa3b, v18
	v_rcp_f32_e32 v161, v161
	v_exp_f32_e32 v182, v182
	v_min_f32_e32 v181, 0x7f61b1e6, v159
	v_add_f32_e32 v159, 1.0, v171
	v_mul_f32_e32 v180, 0xbfb8aa3b, v22
	v_rcp_f32_e32 v171, v159
	v_exp_f32_e32 v180, v180
	v_mul_f32_e32 v159, v159, v161
	v_add_f32_e32 v161, 1.0, v182
	v_rcp_f32_e32 v161, v161
	v_mul_f32_e32 v182, 0xbfb8aa3b, v19
	v_min_f32_e32 v183, 0x7f61b1e6, v159
	v_add_f32_e32 v159, 1.0, v180
	v_exp_f32_e32 v182, v182
; DI unsigned pk2(float lo, float hi) { f32x2 v = {lo, hi}; bf16v2 r = __builtin_convertvector(v, bf16v2); return __builtin_bit_cast(unsigned, r); }
; DI float fexp2(float x) { return __builtin_amdgcn_exp2f(x); }
; DI float frcp(float x) { return __builtin_amdgcn_rcpf(x); }
;     DI void operator()(const f32x4 (&acc)[2][2][4][2], const pg8::Unit& u, int wr, int wc, int fr, int fq) const {
;     ...
;         if (pn >= 32) {
;             bf16_t* sa = g3 + 2 * ARR; bf16_t* rh = g3 + 4 * ARR; const int col0 = 128 * (pn - 32) + cl;
; #pragma unroll
;             for (int ai = 0; ai < 2; ++ai)
; #pragma unroll
;                 for (int m = 0; m < 4; ++m) { const size_t off = (size_t)(row0 + ai * 128 + m * 16) * D + col0;
;                     const f32x4 a0 = acc[ai][0][m][0], a1 = acc[ai][0][m][1], b0 = acc[ai][1][m][0], b1 = acc[ai][1][m][1];
;                     const float av[8] = {a0[0], a0[1], a0[2], a0[3], a1[0], a1[1], a1[2], a1[3]}, bv[8] = {b0[0], b0[1], b0[2], b0[3], b1[0], b1[1], b1[2], b1[3]};
;                     float sg[8], ro[8];
; #pragma unroll
;                     for (int j = 0; j < 8; ++j) { const float da = 1.0f + fexp2(-av[j] * LOG2E), db = 1.0f + fexp2(-bv[j] * LOG2E); sg[j] = frcp(da); ro[j] = fminf(da * frcp(db), 3.0e38f); }
;                     *(u32x4*)(sa + off) = (u32x4){pk2(sg[0], sg[1]), pk2(sg[2], sg[3]), pk2(sg[4], sg[5]), pk2(sg[6], sg[7])};
;                     *(u32x4*)(rh + off) = (u32x4){pk2(ro[0], ro[1]), pk2(ro[2], ro[3]), pk2(ro[4], ro[5]), pk2(ro[6], ro[7])}; }
;             return;
	v_rcp_f32_e32 v180, v159
	v_mul_f32_e32 v159, v159, v161
	v_mul_f32_e32 v161, 0xbfb8aa3b, v23
	v_exp_f32_e32 v161, v161
	v_add_f32_e32 v182, 1.0, v182
	v_rcp_f32_e32 v182, v182
	v_min_f32_e32 v184, 0x7f61b1e6, v159
	v_add_f32_e32 v159, 1.0, v161
	v_rcp_f32_e32 v161, v159
	v_mul_f32_e32 v159, v159, v182
	s_mov_b64 s[2:3], 0x50000
	v_min_f32_e32 v182, 0x7f61b1e6, v159
	v_cvt_pk_bf16_f32 v159, v162, v163
	v_lshl_add_u64 v[162:163], v[156:157], 0, s[2:3]
	v_min_f32_e32 v48, 0x7f61b1e6, v48
	v_min_f32_e32 v155, 0x7f61b1e6, v155
	v_cvt_pk_bf16_f32 v158, v158, v160
	v_cvt_pk_bf16_f32 v160, v170, v171
	v_cvt_pk_bf16_f32 v161, v180, v161
	v_lshl_add_u64 v[170:171], s[10:11], 0, v[162:163]
	global_store_dwordx4 v[170:171], v[158:161], off sc1
	v_lshl_add_u64 v[162:163], s[12:13], 0, v[162:163]
	v_mul_f32_e32 v170, 0xbfb8aa3b, v11
	v_cvt_pk_bf16_f32 v158, v48, v155
	v_mul_f32_e32 v155, 0xbfb8aa3b, v8
	v_exp_f32_e32 v155, v155
	v_cvt_pk_bf16_f32 v159, v178, v179
	v_cvt_pk_bf16_f32 v160, v181, v183
	v_cvt_pk_bf16_f32 v161, v184, v182
	v_mul_f32_e32 v48, 0xbfb8aa3b, v12
	v_exp_f32_e32 v48, v48
	global_store_dwordx4 v[162:163], v[158:161], off sc1
	v_add_f32_e32 v155, 1.0, v155
	v_rcp_f32_e32 v155, v155
	v_mul_f32_e32 v159, 0xbfb8aa3b, v13
	v_mul_f32_e32 v160, 0xbfb8aa3b, v9
	v_exp_f32_e32 v159, v159
	v_exp_f32_e32 v160, v160
	v_add_f32_e32 v48, 1.0, v48
	v_rcp_f32_e32 v158, v48
	v_mul_f32_e32 v48, v48, v155
	v_add_f32_e32 v155, 1.0, v159
	v_add_f32_e32 v159, 1.0, v160
	v_mul_f32_e32 v161, 0xbfb8aa3b, v14
	v_mul_f32_e32 v162, 0xbfb8aa3b, v10
	v_rcp_f32_e32 v159, v159
	v_exp_f32_e32 v161, v161
	v_exp_f32_e32 v162, v162
	v_rcp_f32_e32 v160, v155
	v_mul_f32_e32 v155, v155, v159
	v_add_f32_e32 v159, 1.0, v161
	v_add_f32_e32 v161, 1.0, v162
	v_rcp_f32_e32 v161, v161
	v_exp_f32_e32 v170, v170
	v_mul_f32_e32 v163, 0xbfb8aa3b, v15
	v_rcp_f32_e32 v162, v159
	v_exp_f32_e32 v163, v163
	v_mul_f32_e32 v159, v159, v161
	v_add_f32_e32 v161, 1.0, v170
	v_mul_f32_e32 v178, 0xbfb8aa3b, v0
	v_rcp_f32_e32 v161, v161
	v_exp_f32_e32 v178, v178
	v_min_f32_e32 v171, 0x7f61b1e6, v159
	v_add_f32_e32 v159, 1.0, v163
	v_mul_f32_e32 v170, 0xbfb8aa3b, v4
	v_rcp_f32_e32 v163, v159
	v_exp_f32_e32 v170, v170
	v_mul_f32_e32 v159, v159, v161
	v_add_f32_e32 v161, 1.0, v178
	v_mul_f32_e32 v180, 0xbfb8aa3b, v1
	v_rcp_f32_e32 v161, v161
	v_exp_f32_e32 v180, v180
	v_min_f32_e32 v179, 0x7f61b1e6, v159
	v_add_f32_e32 v159, 1.0, v170
	v_mul_f32_e32 v178, 0xbfb8aa3b, v5
	v_rcp_f32_e32 v170, v159
	v_exp_f32_e32 v178, v178
	v_mul_f32_e32 v159, v159, v161
	v_add_f32_e32 v161, 1.0, v180
	v_mul_f32_e32 v182, 0xbfb8aa3b, v2
	v_rcp_f32_e32 v161, v161
	v_exp_f32_e32 v182, v182
	v_min_f32_e32 v181, 0x7f61b1e6, v159
	v_add_f32_e32 v159, 1.0, v178
	v_mul_f32_e32 v180, 0xbfb8aa3b, v6
	v_rcp_f32_e32 v178, v159
	v_exp_f32_e32 v180, v180
	v_mul_f32_e32 v159, v159, v161
	v_add_f32_e32 v161, 1.0, v182
	v_rcp_f32_e32 v161, v161
	v_mul_f32_e32 v182, 0xbfb8aa3b, v3
	v_min_f32_e32 v183, 0x7f61b1e6, v159
	v_add_f32_e32 v159, 1.0, v180
	v_exp_f32_e32 v182, v182
	v_rcp_f32_e32 v180, v159
	v_mul_f32_e32 v159, v159, v161
	v_mul_f32_e32 v161, 0xbfb8aa3b, v7
	v_exp_f32_e32 v161, v161
	v_add_f32_e32 v182, 1.0, v182
	v_rcp_f32_e32 v182, v182
	v_min_f32_e32 v184, 0x7f61b1e6, v159
	v_add_f32_e32 v159, 1.0, v161
	v_rcp_f32_e32 v161, v159
	v_mul_f32_e32 v159, v159, v182
	s_mov_b64 s[2:3], 0x58000
	v_min_f32_e32 v182, 0x7f61b1e6, v159
	v_cvt_pk_bf16_f32 v159, v162, v163
	v_lshl_add_u64 v[162:163], v[156:157], 0, s[2:3]
	v_min_f32_e32 v48, 0x7f61b1e6, v48
	v_min_f32_e32 v155, 0x7f61b1e6, v155
	v_cvt_pk_bf16_f32 v158, v158, v160
	v_cvt_pk_bf16_f32 v160, v170, v178
	v_cvt_pk_bf16_f32 v161, v180, v161
	v_lshl_add_u64 v[156:157], s[10:11], 0, v[162:163]
	global_store_dwordx4 v[156:157], v[158:161], off sc1
	v_cvt_pk_bf16_f32 v156, v48, v155
	v_cvt_pk_bf16_f32 v157, v171, v179
	v_cvt_pk_bf16_f32 v158, v181, v183
	v_cvt_pk_bf16_f32 v159, v184, v182
	v_lshl_add_u64 v[160:161], s[12:13], 0, v[162:163]
	global_store_dwordx4 v[160:161], v[156:159], off sc1

; DI unsigned pk2(float lo, float hi) { f32x2 v = {lo, hi}; bf16v2 r = __builtin_convertvector(v, bf16v2); return __builtin_bit_cast(unsigned, r); }
; DI float fexp2(float x) { return __builtin_amdgcn_exp2f(x); }
; DI float frcp(float x) { return __builtin_amdgcn_rcpf(x); }
; DI float sigmoidf_(float x) { return frcp(1.0f + fexp2(-x * LOG2E)); }
; DI float siluf_(float x) { return x * sigmoidf_(x); }
; DI float geluf_(float x) { const float t = x + 0.044715f * x * x * x; return x * frcp(1.0f + fexp2(-2.3022082f * t)); }
;     DI void operator()(const f32x4 (&acc)[2][2][4][2], const pg8::Unit& u, int wr, int wc, int fr, int fq) const {
;     ...
;         if (pn >= 20 && pn < 28) {
;             bf16_t* base = g3; const int col0 = 128 * (pn - 20) + cl;
; #pragma unroll
;             for (int ai = 0; ai < 2; ++ai)
; #pragma unroll
;                 for (int m = 0; m < 4; ++m) { bf16_t* rowp = base + (size_t)(row0 + ai * 128 + m * 16) * D + col0;
;                     const f32x4 u0 = acc[ai][0][m][0], u1 = acc[ai][0][m][1], g0 = acc[ai][1][m][0], g1 = acc[ai][1][m][1];
;                     u32x4 w; w.x = pk2(geluf_(u0[0]) * siluf_(g0[0]), geluf_(u0[1]) * siluf_(g0[1])); w.y = pk2(geluf_(u0[2]) * siluf_(g0[2]), geluf_(u0[3]) * siluf_(g0[3]));
;                     w.z = pk2(geluf_(u1[0]) * siluf_(g1[0]), geluf_(u1[1]) * siluf_(g1[1])); w.w = pk2(geluf_(u1[2]) * siluf_(g1[2]), geluf_(u1[3]) * siluf_(g1[3]));
;                     *(u32x4*)rowp = w; }
;             return;
;         }
.LBB0_260:
	v_readlane_b32 s2, v241, 54
	v_lshl_add_u32 v48, s36, 7, v168
	v_readlane_b32 s3, v241, 55
	v_ashrrev_i32_e32 v155, 31, v154
	v_lshlrev_b64 v[156:157], 11, v[154:155]
	v_lshl_add_u64 v[158:159], v[48:49], 1, s[2:3]
	v_mul_f32_e32 v48, 0x3d372713, v126
	v_mul_f32_e32 v48, v126, v48
	v_fma_f32 v48, v126, v48, v126
	v_mul_f32_e32 v48, 0xc0135761, v48
	v_exp_f32_e32 v48, v48
	v_mul_f32_e32 v155, 0x3d372713, v127
	v_mul_f32_e32 v155, v127, v155
	v_mul_f32_e32 v161, 0xbfb8aa3b, v123
	v_add_f32_e32 v48, 1.0, v48
	v_rcp_f32_e32 v160, v48
	v_mul_f32_e32 v48, 0xbfb8aa3b, v122
	v_exp_f32_e32 v48, v48
	v_fma_f32 v155, v127, v155, v127
	v_exp_f32_e32 v163, v161
	v_mul_f32_e32 v155, 0xc0135761, v155
	v_exp_f32_e32 v155, v155
	v_add_f32_e32 v48, 1.0, v48
	v_rcp_f32_e32 v162, v48
	v_add_f32_e32 v48, 1.0, v163
	v_rcp_f32_e32 v163, v48
	v_mul_f32_e32 v48, 0x3d372713, v128
	v_add_f32_e32 v155, 1.0, v155
	v_mul_f32_e32 v48, v128, v48
	v_rcp_f32_e32 v161, v155
	v_fma_f32 v48, v128, v48, v128
	v_mul_f32_e32 v48, 0xc0135761, v48
	v_exp_f32_e32 v48, v48
	v_pk_mul_f32 v[126:127], v[126:127], v[160:161]
	v_pk_mul_f32 v[122:123], v[122:123], v[162:163]
	v_lshl_add_u64 v[156:157], v[158:159], 0, v[156:157]
	v_pk_mul_f32 v[122:123], v[126:127], v[122:123]
	v_add_f32_e32 v48, 1.0, v48
	v_cvt_pk_bf16_f32 v122, v122, v123
	v_mul_f32_e32 v123, 0x3d372713, v129
	v_rcp_f32_e32 v126, v48
	v_mul_f32_e32 v48, 0xbfb8aa3b, v124
	v_mul_f32_e32 v123, v129, v123
	v_exp_f32_e32 v48, v48
	v_fma_f32 v123, v129, v123, v129
	v_mul_f32_e32 v127, 0xbfb8aa3b, v125
	v_mul_f32_e32 v123, 0xc0135761, v123
	v_exp_f32_e32 v155, v127
	v_exp_f32_e32 v123, v123
	v_add_f32_e32 v48, 1.0, v48
	v_rcp_f32_e32 v160, v48
	v_add_f32_e32 v48, 1.0, v155
	v_add_f32_e32 v123, 1.0, v123
	v_rcp_f32_e32 v161, v48
	v_mul_f32_e32 v48, 0x3d372713, v118
	v_rcp_f32_e32 v127, v123
	v_mul_f32_e32 v48, v118, v48
	v_fma_f32 v48, v118, v48, v118
	v_mul_f32_e32 v48, 0xc0135761, v48
	v_exp_f32_e32 v48, v48
	v_pk_mul_f32 v[126:127], v[128:129], v[126:127]
	v_pk_mul_f32 v[124:125], v[124:125], v[160:161]
	s_mov_b32 s2, 0x40000
	v_pk_mul_f32 v[124:125], v[126:127], v[124:125]
	v_add_f32_e32 v48, 1.0, v48
	v_cvt_pk_bf16_f32 v123, v124, v125
	v_mul_f32_e32 v125, 0x3d372713, v119
	v_mul_f32_e32 v125, v119, v125
	v_rcp_f32_e32 v124, v48
	v_mul_f32_e32 v48, 0xbfb8aa3b, v114
	v_fma_f32 v125, v119, v125, v119
	v_exp_f32_e32 v48, v48
	v_mul_f32_e32 v125, 0xc0135761, v125
	v_mul_f32_e32 v126, 0xbfb8aa3b, v115
	v_exp_f32_e32 v125, v125
	v_exp_f32_e32 v127, v126
	v_add_f32_e32 v48, 1.0, v48
	v_rcp_f32_e32 v126, v48
	v_add_f32_e32 v125, 1.0, v125
	v_add_f32_e32 v48, 1.0, v127
	v_rcp_f32_e32 v125, v125
	v_rcp_f32_e32 v127, v48
	v_mul_f32_e32 v48, 0x3d372713, v120
	v_mul_f32_e32 v48, v120, v48
	v_fma_f32 v48, v120, v48, v120
	v_mul_f32_e32 v48, 0xc0135761, v48
	v_pk_mul_f32 v[118:119], v[118:119], v[124:125]
	v_exp_f32_e32 v48, v48
	v_mul_f32_e32 v124, 0xbfb8aa3b, v116
	v_exp_f32_e32 v124, v124
	v_pk_mul_f32 v[114:115], v[114:115], v[126:127]
	v_add_f32_e32 v48, 1.0, v48
	v_rcp_f32_e32 v126, v48
	v_add_f32_e32 v48, 1.0, v124
	v_mul_f32_e32 v124, 0x3d372713, v121
	v_mul_f32_e32 v124, v121, v124
	v_fma_f32 v124, v121, v124, v121
	v_mul_f32_e32 v124, 0xc0135761, v124
	v_exp_f32_e32 v124, v124
	v_mul_f32_e32 v125, 0xbfb8aa3b, v117
	v_exp_f32_e32 v125, v125
	v_rcp_f32_e32 v128, v48
	v_add_f32_e32 v48, 1.0, v124
	v_rcp_f32_e32 v127, v48
	v_add_f32_e32 v48, 1.0, v125
	v_rcp_f32_e32 v129, v48
	v_mul_f32_e32 v48, 0x3d372713, v110
	v_mul_f32_e32 v48, v110, v48
	v_fma_f32 v48, v110, v48, v110
	v_mul_f32_e32 v48, 0xc0135761, v48
	v_exp_f32_e32 v48, v48
	v_pk_mul_f32 v[114:115], v[118:119], v[114:115]
	v_pk_mul_f32 v[116:117], v[116:117], v[128:129]
	v_cvt_pk_bf16_f32 v124, v114, v115
	v_pk_mul_f32 v[114:115], v[120:121], v[126:127]
	v_add_f32_e32 v48, 1.0, v48
	v_pk_mul_f32 v[114:115], v[114:115], v[116:117]
	v_rcp_f32_e32 v116, v48
	v_mul_f32_e32 v48, 0xbfb8aa3b, v106
	v_mul_f32_e32 v117, 0x3d372713, v111
	v_exp_f32_e32 v48, v48
	v_mul_f32_e32 v117, v111, v117
	v_mul_f32_e32 v118, 0xbfb8aa3b, v107
	v_fma_f32 v117, v111, v117, v111
	v_exp_f32_e32 v119, v118
	v_mul_f32_e32 v117, 0xc0135761, v117
	v_exp_f32_e32 v117, v117
	v_add_f32_e32 v48, 1.0, v48
	v_rcp_f32_e32 v118, v48
	v_add_f32_e32 v48, 1.0, v119
	v_rcp_f32_e32 v119, v48
	v_mul_f32_e32 v48, 0x3d372713, v112
	v_add_f32_e32 v117, 1.0, v117
	v_mul_f32_e32 v48, v112, v48
	v_rcp_f32_e32 v117, v117
	v_fma_f32 v48, v112, v48, v112
	v_mul_f32_e32 v48, 0xc0135761, v48
	v_exp_f32_e32 v48, v48
	v_pk_mul_f32 v[110:111], v[110:111], v[116:117]
	v_pk_mul_f32 v[106:107], v[106:107], v[118:119]
	v_cvt_pk_bf16_f32 v125, v114, v115
	v_pk_mul_f32 v[106:107], v[110:111], v[106:107]
	v_add_f32_e32 v48, 1.0, v48
	v_cvt_pk_bf16_f32 v106, v106, v107
	v_mul_f32_e32 v107, 0x3d372713, v113
	v_rcp_f32_e32 v110, v48
	v_mul_f32_e32 v48, 0xbfb8aa3b, v108
	v_mul_f32_e32 v107, v113, v107
	v_exp_f32_e32 v48, v48
	v_fma_f32 v107, v113, v107, v113
	v_mul_f32_e32 v111, 0xbfb8aa3b, v109
	v_mul_f32_e32 v107, 0xc0135761, v107
	v_exp_f32_e32 v117, v111
	v_exp_f32_e32 v107, v107
	v_add_f32_e32 v48, 1.0, v48
	v_rcp_f32_e32 v116, v48
	v_add_f32_e32 v48, 1.0, v117
	v_add_f32_e32 v107, 1.0, v107
	v_rcp_f32_e32 v117, v48
	v_mul_f32_e32 v48, 0x3d372713, v102
	v_rcp_f32_e32 v111, v107
	v_mul_f32_e32 v48, v102, v48
	v_fma_f32 v48, v102, v48, v102
	v_mul_f32_e32 v48, 0xc0135761, v48
	v_exp_f32_e32 v48, v48
	v_pk_mul_f32 v[110:111], v[112:113], v[110:111]
	v_pk_mul_f32 v[108:109], v[108:109], v[116:117]
	v_or_b32_e32 v114, 16, v154
	v_pk_mul_f32 v[108:109], v[110:111], v[108:109]
	v_add_f32_e32 v48, 1.0, v48
	v_cvt_pk_bf16_f32 v107, v108, v109
; DI unsigned pk2(float lo, float hi) { f32x2 v = {lo, hi}; bf16v2 r = __builtin_convertvector(v, bf16v2); return __builtin_bit_cast(unsigned, r); }
; DI float fexp2(float x) { return __builtin_amdgcn_exp2f(x); }
; DI float frcp(float x) { return __builtin_amdgcn_rcpf(x); }
; DI float sigmoidf_(float x) { return frcp(1.0f + fexp2(-x * LOG2E)); }
; DI float siluf_(float x) { return x * sigmoidf_(x); }
; DI float geluf_(float x) { const float t = x + 0.044715f * x * x * x; return x * frcp(1.0f + fexp2(-2.3022082f * t)); }
;     DI void operator()(const f32x4 (&acc)[2][2][4][2], const pg8::Unit& u, int wr, int wc, int fr, int fq) const {
;     ...
;         if (pn >= 20 && pn < 28) {
;             bf16_t* base = g3; const int col0 = 128 * (pn - 20) + cl;
; #pragma unroll
;             for (int ai = 0; ai < 2; ++ai)
; #pragma unroll
;                 for (int m = 0; m < 4; ++m) { bf16_t* rowp = base + (size_t)(row0 + ai * 128 + m * 16) * D + col0;
;                     const f32x4 u0 = acc[ai][0][m][0], u1 = acc[ai][0][m][1], g0 = acc[ai][1][m][0], g1 = acc[ai][1][m][1];
;                     u32x4 w; w.x = pk2(geluf_(u0[0]) * siluf_(g0[0]), geluf_(u0[1]) * siluf_(g0[1])); w.y = pk2(geluf_(u0[2]) * siluf_(g0[2]), geluf_(u0[3]) * siluf_(g0[3]));
;                     w.z = pk2(geluf_(u1[0]) * siluf_(g1[0]), geluf_(u1[1]) * siluf_(g1[1])); w.w = pk2(geluf_(u1[2]) * siluf_(g1[2]), geluf_(u1[3]) * siluf_(g1[3]));
;                     *(u32x4*)rowp = w; }
;             return;
;         }
	v_mul_f32_e32 v109, 0x3d372713, v103
	v_mul_f32_e32 v109, v103, v109
	v_rcp_f32_e32 v108, v48
	v_mul_f32_e32 v48, 0xbfb8aa3b, v98
	v_fma_f32 v109, v103, v109, v103
	v_exp_f32_e32 v48, v48
	v_mul_f32_e32 v109, 0xc0135761, v109
	v_mul_f32_e32 v110, 0xbfb8aa3b, v99
	v_exp_f32_e32 v109, v109
	v_exp_f32_e32 v111, v110
	v_add_f32_e32 v48, 1.0, v48
	v_rcp_f32_e32 v110, v48
	v_add_f32_e32 v109, 1.0, v109
	v_add_f32_e32 v48, 1.0, v111
	v_rcp_f32_e32 v109, v109
	v_rcp_f32_e32 v111, v48
	v_mul_f32_e32 v48, 0x3d372713, v104
	v_mul_f32_e32 v48, v104, v48
	v_fma_f32 v48, v104, v48, v104
	v_mul_f32_e32 v48, 0xc0135761, v48
	v_pk_mul_f32 v[102:103], v[102:103], v[108:109]
	v_exp_f32_e32 v48, v48
	v_mul_f32_e32 v108, 0xbfb8aa3b, v100
	v_exp_f32_e32 v108, v108
	v_pk_mul_f32 v[98:99], v[98:99], v[110:111]
	v_add_f32_e32 v48, 1.0, v48
	v_rcp_f32_e32 v110, v48
	v_add_f32_e32 v48, 1.0, v108
	v_mul_f32_e32 v108, 0x3d372713, v105
	v_mul_f32_e32 v108, v105, v108
	v_fma_f32 v108, v105, v108, v105
	v_mul_f32_e32 v108, 0xc0135761, v108
	v_exp_f32_e32 v108, v108
	v_mul_f32_e32 v109, 0xbfb8aa3b, v101
	v_exp_f32_e32 v109, v109
	v_rcp_f32_e32 v112, v48
	v_add_f32_e32 v48, 1.0, v108
	v_rcp_f32_e32 v111, v48
	v_add_f32_e32 v48, 1.0, v109
	v_rcp_f32_e32 v113, v48
	v_mul_f32_e32 v48, 0x3d372713, v94
	v_mul_f32_e32 v48, v94, v48
	v_fma_f32 v48, v94, v48, v94
	v_mul_f32_e32 v48, 0xc0135761, v48
	v_exp_f32_e32 v48, v48
	v_pk_mul_f32 v[98:99], v[102:103], v[98:99]
	v_pk_mul_f32 v[100:101], v[100:101], v[112:113]
	v_cvt_pk_bf16_f32 v108, v98, v99
	v_pk_mul_f32 v[98:99], v[104:105], v[110:111]
	v_add_f32_e32 v48, 1.0, v48
	v_pk_mul_f32 v[98:99], v[98:99], v[100:101]
	v_rcp_f32_e32 v100, v48
	v_mul_f32_e32 v48, 0xbfb8aa3b, v90
	v_mul_f32_e32 v101, 0x3d372713, v95
	v_exp_f32_e32 v48, v48
	v_mul_f32_e32 v101, v95, v101
	v_mul_f32_e32 v102, 0xbfb8aa3b, v91
	v_fma_f32 v101, v95, v101, v95
	v_exp_f32_e32 v103, v102
	v_mul_f32_e32 v101, 0xc0135761, v101
	v_exp_f32_e32 v101, v101
	v_add_f32_e32 v48, 1.0, v48
	v_rcp_f32_e32 v102, v48
	v_add_f32_e32 v48, 1.0, v103
	v_rcp_f32_e32 v103, v48
	v_mul_f32_e32 v48, 0x3d372713, v96
	v_add_f32_e32 v101, 1.0, v101
	v_mul_f32_e32 v48, v96, v48
	v_rcp_f32_e32 v101, v101
	v_fma_f32 v48, v96, v48, v96
	v_mul_f32_e32 v48, 0xc0135761, v48
	v_exp_f32_e32 v48, v48
	v_pk_mul_f32 v[94:95], v[94:95], v[100:101]
	v_pk_mul_f32 v[90:91], v[90:91], v[102:103]
	v_cvt_pk_bf16_f32 v109, v98, v99
	v_pk_mul_f32 v[90:91], v[94:95], v[90:91]
	v_add_f32_e32 v48, 1.0, v48
	v_cvt_pk_bf16_f32 v90, v90, v91
	v_mul_f32_e32 v91, 0x3d372713, v97
	v_rcp_f32_e32 v94, v48
	v_mul_f32_e32 v48, 0xbfb8aa3b, v92
	v_mul_f32_e32 v91, v97, v91
	v_exp_f32_e32 v48, v48
	v_fma_f32 v91, v97, v91, v97
	v_mul_f32_e32 v95, 0xbfb8aa3b, v93
	v_mul_f32_e32 v91, 0xc0135761, v91
	v_exp_f32_e32 v101, v95
	v_exp_f32_e32 v91, v91
	v_add_f32_e32 v48, 1.0, v48
	v_rcp_f32_e32 v100, v48
	v_add_f32_e32 v48, 1.0, v101
	v_add_f32_e32 v91, 1.0, v91
	v_rcp_f32_e32 v101, v48
	v_mul_f32_e32 v48, 0x3d372713, v86
	v_rcp_f32_e32 v95, v91
	v_mul_f32_e32 v48, v86, v48
	v_fma_f32 v48, v86, v48, v86
	v_mul_f32_e32 v48, 0xc0135761, v48
	v_exp_f32_e32 v48, v48
	v_pk_mul_f32 v[94:95], v[96:97], v[94:95]
	v_pk_mul_f32 v[92:93], v[92:93], v[100:101]
	v_or_b32_e32 v98, 32, v154
	v_pk_mul_f32 v[92:93], v[94:95], v[92:93]
	v_add_f32_e32 v48, 1.0, v48
	v_cvt_pk_bf16_f32 v91, v92, v93
	v_mul_f32_e32 v93, 0x3d372713, v87
	v_mul_f32_e32 v93, v87, v93
	v_rcp_f32_e32 v92, v48
	v_mul_f32_e32 v48, 0xbfb8aa3b, v82
	v_fma_f32 v93, v87, v93, v87
	v_exp_f32_e32 v48, v48
	v_mul_f32_e32 v93, 0xc0135761, v93
	v_mul_f32_e32 v94, 0xbfb8aa3b, v83
	v_exp_f32_e32 v93, v93
	v_exp_f32_e32 v95, v94
	v_add_f32_e32 v48, 1.0, v48
	v_rcp_f32_e32 v94, v48
	v_add_f32_e32 v93, 1.0, v93
	v_add_f32_e32 v48, 1.0, v95
	v_rcp_f32_e32 v93, v93
	v_rcp_f32_e32 v95, v48
	v_mul_f32_e32 v48, 0x3d372713, v88
	v_mul_f32_e32 v48, v88, v48
	v_fma_f32 v48, v88, v48, v88
	v_mul_f32_e32 v48, 0xc0135761, v48
	v_pk_mul_f32 v[86:87], v[86:87], v[92:93]
	v_exp_f32_e32 v48, v48
	v_mul_f32_e32 v92, 0xbfb8aa3b, v84
	v_exp_f32_e32 v92, v92
	v_pk_mul_f32 v[82:83], v[82:83], v[94:95]
	v_add_f32_e32 v48, 1.0, v48
	v_rcp_f32_e32 v94, v48
	v_add_f32_e32 v48, 1.0, v92
	v_mul_f32_e32 v92, 0x3d372713, v89
	v_mul_f32_e32 v92, v89, v92
	v_fma_f32 v92, v89, v92, v89
	v_mul_f32_e32 v92, 0xc0135761, v92
	v_exp_f32_e32 v92, v92
	v_mul_f32_e32 v93, 0xbfb8aa3b, v85
	v_exp_f32_e32 v93, v93
	v_rcp_f32_e32 v96, v48
	v_add_f32_e32 v48, 1.0, v92
	v_rcp_f32_e32 v95, v48
	v_add_f32_e32 v48, 1.0, v93
	v_rcp_f32_e32 v97, v48
	v_mul_f32_e32 v48, 0x3d372713, v78
	v_mul_f32_e32 v48, v78, v48
	v_fma_f32 v48, v78, v48, v78
	v_mul_f32_e32 v48, 0xc0135761, v48
	v_exp_f32_e32 v48, v48
	v_pk_mul_f32 v[82:83], v[86:87], v[82:83]
	v_pk_mul_f32 v[84:85], v[84:85], v[96:97]
	v_cvt_pk_bf16_f32 v92, v82, v83
	v_pk_mul_f32 v[82:83], v[88:89], v[94:95]
	v_add_f32_e32 v48, 1.0, v48
	v_pk_mul_f32 v[82:83], v[82:83], v[84:85]
	v_rcp_f32_e32 v84, v48
	v_mul_f32_e32 v48, 0xbfb8aa3b, v74
	v_mul_f32_e32 v85, 0x3d372713, v79
	v_exp_f32_e32 v48, v48
	v_mul_f32_e32 v85, v79, v85
	v_mul_f32_e32 v86, 0xbfb8aa3b, v75
	v_fma_f32 v85, v79, v85, v79
	v_exp_f32_e32 v87, v86
	v_mul_f32_e32 v85, 0xc0135761, v85
	v_exp_f32_e32 v85, v85
	v_add_f32_e32 v48, 1.0, v48
	v_rcp_f32_e32 v86, v48
	v_add_f32_e32 v48, 1.0, v87
	v_rcp_f32_e32 v87, v48
	v_mul_f32_e32 v48, 0x3d372713, v80
	v_add_f32_e32 v85, 1.0, v85
	v_mul_f32_e32 v48, v80, v48
	v_rcp_f32_e32 v85, v85
	v_fma_f32 v48, v80, v48, v80
	v_mul_f32_e32 v48, 0xc0135761, v48
	v_exp_f32_e32 v48, v48
	v_pk_mul_f32 v[78:79], v[78:79], v[84:85]
	v_pk_mul_f32 v[74:75], v[74:75], v[86:87]
; DI unsigned pk2(float lo, float hi) { f32x2 v = {lo, hi}; bf16v2 r = __builtin_convertvector(v, bf16v2); return __builtin_bit_cast(unsigned, r); }
; DI float fexp2(float x) { return __builtin_amdgcn_exp2f(x); }
; DI float frcp(float x) { return __builtin_amdgcn_rcpf(x); }
; DI float sigmoidf_(float x) { return frcp(1.0f + fexp2(-x * LOG2E)); }
; DI float siluf_(float x) { return x * sigmoidf_(x); }
; DI float geluf_(float x) { const float t = x + 0.044715f * x * x * x; return x * frcp(1.0f + fexp2(-2.3022082f * t)); }
;     DI void operator()(const f32x4 (&acc)[2][2][4][2], const pg8::Unit& u, int wr, int wc, int fr, int fq) const {
;     ...
;         if (pn >= 20 && pn < 28) {
;             bf16_t* base = g3; const int col0 = 128 * (pn - 20) + cl;
; #pragma unroll
;             for (int ai = 0; ai < 2; ++ai)
; #pragma unroll
;                 for (int m = 0; m < 4; ++m) { bf16_t* rowp = base + (size_t)(row0 + ai * 128 + m * 16) * D + col0;
;                     const f32x4 u0 = acc[ai][0][m][0], u1 = acc[ai][0][m][1], g0 = acc[ai][1][m][0], g1 = acc[ai][1][m][1];
;                     u32x4 w; w.x = pk2(geluf_(u0[0]) * siluf_(g0[0]), geluf_(u0[1]) * siluf_(g0[1])); w.y = pk2(geluf_(u0[2]) * siluf_(g0[2]), geluf_(u0[3]) * siluf_(g0[3]));
;                     w.z = pk2(geluf_(u1[0]) * siluf_(g1[0]), geluf_(u1[1]) * siluf_(g1[1])); w.w = pk2(geluf_(u1[2]) * siluf_(g1[2]), geluf_(u1[3]) * siluf_(g1[3]));
;                     *(u32x4*)rowp = w; }
;             return;
;         }
	v_cvt_pk_bf16_f32 v93, v82, v83
	v_pk_mul_f32 v[74:75], v[78:79], v[74:75]
	v_add_f32_e32 v48, 1.0, v48
	v_cvt_pk_bf16_f32 v74, v74, v75
	v_mul_f32_e32 v75, 0x3d372713, v81
	v_rcp_f32_e32 v78, v48
	v_mul_f32_e32 v48, 0xbfb8aa3b, v76
	v_mul_f32_e32 v75, v81, v75
	v_exp_f32_e32 v48, v48
	v_fma_f32 v75, v81, v75, v81
	v_mul_f32_e32 v79, 0xbfb8aa3b, v77
	v_mul_f32_e32 v75, 0xc0135761, v75
	v_exp_f32_e32 v85, v79
	v_exp_f32_e32 v75, v75
	v_add_f32_e32 v48, 1.0, v48
	v_rcp_f32_e32 v84, v48
	v_add_f32_e32 v48, 1.0, v85
	v_add_f32_e32 v75, 1.0, v75
	v_rcp_f32_e32 v85, v48
	v_mul_f32_e32 v48, 0x3d372713, v70
	v_rcp_f32_e32 v79, v75
	v_mul_f32_e32 v48, v70, v48
	v_fma_f32 v48, v70, v48, v70
	v_mul_f32_e32 v48, 0xc0135761, v48
	v_exp_f32_e32 v48, v48
	v_pk_mul_f32 v[78:79], v[80:81], v[78:79]
	v_pk_mul_f32 v[76:77], v[76:77], v[84:85]
	v_or_b32_e32 v82, 48, v154
	v_pk_mul_f32 v[76:77], v[78:79], v[76:77]
	v_add_f32_e32 v48, 1.0, v48
	v_cvt_pk_bf16_f32 v75, v76, v77
	v_mul_f32_e32 v77, 0x3d372713, v71
	v_mul_f32_e32 v77, v71, v77
	v_rcp_f32_e32 v76, v48
	v_mul_f32_e32 v48, 0xbfb8aa3b, v66
	v_fma_f32 v77, v71, v77, v71
	v_exp_f32_e32 v48, v48
	v_mul_f32_e32 v77, 0xc0135761, v77
	v_mul_f32_e32 v78, 0xbfb8aa3b, v67
	v_exp_f32_e32 v77, v77
	v_exp_f32_e32 v79, v78
	v_add_f32_e32 v48, 1.0, v48
	v_rcp_f32_e32 v78, v48
	v_add_f32_e32 v77, 1.0, v77
	v_add_f32_e32 v48, 1.0, v79
	v_rcp_f32_e32 v77, v77
	v_rcp_f32_e32 v79, v48
	v_mul_f32_e32 v48, 0x3d372713, v72
	v_mul_f32_e32 v48, v72, v48
	v_fma_f32 v48, v72, v48, v72
	v_mul_f32_e32 v48, 0xc0135761, v48
	v_pk_mul_f32 v[70:71], v[70:71], v[76:77]
	v_exp_f32_e32 v48, v48
	v_mul_f32_e32 v76, 0xbfb8aa3b, v68
	v_exp_f32_e32 v76, v76
	v_pk_mul_f32 v[66:67], v[66:67], v[78:79]
	v_add_f32_e32 v48, 1.0, v48
	v_rcp_f32_e32 v78, v48
	v_add_f32_e32 v48, 1.0, v76
	v_mul_f32_e32 v76, 0x3d372713, v73
	v_mul_f32_e32 v76, v73, v76
	v_fma_f32 v76, v73, v76, v73
	v_mul_f32_e32 v76, 0xc0135761, v76
	v_exp_f32_e32 v76, v76
	v_mul_f32_e32 v77, 0xbfb8aa3b, v69
	v_exp_f32_e32 v77, v77
	v_rcp_f32_e32 v80, v48
	v_add_f32_e32 v48, 1.0, v76
	v_rcp_f32_e32 v79, v48
	v_add_f32_e32 v48, 1.0, v77
	v_rcp_f32_e32 v81, v48
	v_mul_f32_e32 v48, 0x3d372713, v62
	v_mul_f32_e32 v48, v62, v48
	v_fma_f32 v48, v62, v48, v62
	v_mul_f32_e32 v48, 0xc0135761, v48
	v_exp_f32_e32 v48, v48
	v_pk_mul_f32 v[66:67], v[70:71], v[66:67]
	v_pk_mul_f32 v[68:69], v[68:69], v[80:81]
	v_cvt_pk_bf16_f32 v76, v66, v67
	v_pk_mul_f32 v[66:67], v[72:73], v[78:79]
	v_add_f32_e32 v48, 1.0, v48
	v_pk_mul_f32 v[66:67], v[66:67], v[68:69]
	v_mul_f32_e32 v68, 0xbfb8aa3b, v59
	v_cvt_pk_bf16_f32 v77, v66, v67
	v_rcp_f32_e32 v66, v48
	v_mul_f32_e32 v48, 0xbfb8aa3b, v58
	v_mul_f32_e32 v67, 0x3d372713, v63
	v_exp_f32_e32 v48, v48
	v_mul_f32_e32 v67, v63, v67
	v_fma_f32 v67, v63, v67, v63
	v_exp_f32_e32 v69, v68
	v_mul_f32_e32 v67, 0xc0135761, v67
	v_exp_f32_e32 v67, v67
	v_add_f32_e32 v48, 1.0, v48
	v_rcp_f32_e32 v68, v48
	v_add_f32_e32 v48, 1.0, v69
	v_rcp_f32_e32 v69, v48
	v_mul_f32_e32 v48, 0x3d372713, v64
	v_add_f32_e32 v67, 1.0, v67
	v_mul_f32_e32 v48, v64, v48
	v_rcp_f32_e32 v67, v67
	v_fma_f32 v48, v64, v48, v64
	v_mul_f32_e32 v48, 0xc0135761, v48
	v_exp_f32_e32 v48, v48
	v_pk_mul_f32 v[62:63], v[62:63], v[66:67]
	v_pk_mul_f32 v[58:59], v[58:59], v[68:69]
	v_ashrrev_i32_e32 v115, 31, v114
	v_pk_mul_f32 v[58:59], v[62:63], v[58:59]
	v_add_f32_e32 v48, 1.0, v48
	v_cvt_pk_bf16_f32 v58, v58, v59
	v_mul_f32_e32 v59, 0x3d372713, v65
	v_rcp_f32_e32 v62, v48
	v_mul_f32_e32 v48, 0xbfb8aa3b, v60
	v_mul_f32_e32 v59, v65, v59
	v_exp_f32_e32 v48, v48
	v_fma_f32 v59, v65, v59, v65
	v_mul_f32_e32 v63, 0xbfb8aa3b, v61
	v_mul_f32_e32 v59, 0xc0135761, v59
	v_exp_f32_e32 v67, v63
	v_exp_f32_e32 v59, v59
	v_add_f32_e32 v48, 1.0, v48
	v_rcp_f32_e32 v66, v48
	v_add_f32_e32 v48, 1.0, v67
	v_add_f32_e32 v59, 1.0, v59
	v_rcp_f32_e32 v67, v48
	v_mul_f32_e32 v48, 0x3d372713, v54
	v_rcp_f32_e32 v63, v59
	v_mul_f32_e32 v48, v54, v48
	v_fma_f32 v48, v54, v48, v54
	v_mul_f32_e32 v48, 0xc0135761, v48
	v_exp_f32_e32 v48, v48
	v_pk_mul_f32 v[62:63], v[64:65], v[62:63]
	v_pk_mul_f32 v[60:61], v[60:61], v[66:67]
	v_ashrrev_i32_e32 v99, 31, v98
	v_pk_mul_f32 v[60:61], v[62:63], v[60:61]
	v_add_f32_e32 v48, 1.0, v48
	v_cvt_pk_bf16_f32 v59, v60, v61
	v_mul_f32_e32 v61, 0x3d372713, v55
	v_mul_f32_e32 v61, v55, v61
	v_rcp_f32_e32 v60, v48
	v_mul_f32_e32 v48, 0xbfb8aa3b, v50
	v_fma_f32 v61, v55, v61, v55
	v_exp_f32_e32 v48, v48
	v_mul_f32_e32 v61, 0xc0135761, v61
	v_mul_f32_e32 v62, 0xbfb8aa3b, v51
	v_exp_f32_e32 v61, v61
	v_exp_f32_e32 v63, v62
	v_add_f32_e32 v48, 1.0, v48
	v_rcp_f32_e32 v62, v48
	v_add_f32_e32 v61, 1.0, v61
	v_add_f32_e32 v48, 1.0, v63
	v_rcp_f32_e32 v61, v61
	v_rcp_f32_e32 v63, v48
	v_mul_f32_e32 v48, 0x3d372713, v56
	v_mul_f32_e32 v48, v56, v48
	v_fma_f32 v48, v56, v48, v56
	v_mul_f32_e32 v48, 0xc0135761, v48
	v_pk_mul_f32 v[54:55], v[54:55], v[60:61]
	v_exp_f32_e32 v48, v48
	v_mul_f32_e32 v60, 0xbfb8aa3b, v52
	v_exp_f32_e32 v60, v60
	v_pk_mul_f32 v[50:51], v[50:51], v[62:63]
	v_add_f32_e32 v48, 1.0, v48
	v_rcp_f32_e32 v62, v48
	v_add_f32_e32 v48, 1.0, v60
	v_mul_f32_e32 v60, 0x3d372713, v57
	v_mul_f32_e32 v60, v57, v60
	v_fma_f32 v60, v57, v60, v57
	v_mul_f32_e32 v60, 0xc0135761, v60
	v_exp_f32_e32 v60, v60
	v_mul_f32_e32 v61, 0xbfb8aa3b, v53
	v_exp_f32_e32 v61, v61
	v_rcp_f32_e32 v64, v48
	v_add_f32_e32 v48, 1.0, v60
	v_rcp_f32_e32 v63, v48
	v_add_f32_e32 v48, 1.0, v61
	v_rcp_f32_e32 v65, v48
	v_mul_f32_e32 v48, 0x3d372713, v44
	v_mul_f32_e32 v48, v44, v48
	v_fma_f32 v48, v44, v48, v44
	v_mul_f32_e32 v48, 0xc0135761, v48
	v_pk_mul_f32 v[50:51], v[54:55], v[50:51]
	v_exp_f32_e32 v48, v48
; DI unsigned pk2(float lo, float hi) { f32x2 v = {lo, hi}; bf16v2 r = __builtin_convertvector(v, bf16v2); return __builtin_bit_cast(unsigned, r); }
; DI float fexp2(float x) { return __builtin_amdgcn_exp2f(x); }
; DI float frcp(float x) { return __builtin_amdgcn_rcpf(x); }
; DI float sigmoidf_(float x) { return frcp(1.0f + fexp2(-x * LOG2E)); }
; DI float siluf_(float x) { return x * sigmoidf_(x); }
; DI float geluf_(float x) { const float t = x + 0.044715f * x * x * x; return x * frcp(1.0f + fexp2(-2.3022082f * t)); }
;     DI void operator()(const f32x4 (&acc)[2][2][4][2], const pg8::Unit& u, int wr, int wc, int fr, int fq) const {
;     ...
;         if (pn >= 20 && pn < 28) {
;             bf16_t* base = g3; const int col0 = 128 * (pn - 20) + cl;
; #pragma unroll
;             for (int ai = 0; ai < 2; ++ai)
; #pragma unroll
;                 for (int m = 0; m < 4; ++m) { bf16_t* rowp = base + (size_t)(row0 + ai * 128 + m * 16) * D + col0;
;                     const f32x4 u0 = acc[ai][0][m][0], u1 = acc[ai][0][m][1], g0 = acc[ai][1][m][0], g1 = acc[ai][1][m][1];
;                     u32x4 w; w.x = pk2(geluf_(u0[0]) * siluf_(g0[0]), geluf_(u0[1]) * siluf_(g0[1])); w.y = pk2(geluf_(u0[2]) * siluf_(g0[2]), geluf_(u0[3]) * siluf_(g0[3]));
;                     w.z = pk2(geluf_(u1[0]) * siluf_(g1[0]), geluf_(u1[1]) * siluf_(g1[1])); w.w = pk2(geluf_(u1[2]) * siluf_(g1[2]), geluf_(u1[3]) * siluf_(g1[3]));
;                     *(u32x4*)rowp = w; }
;             return;
;         }
	v_cvt_pk_bf16_f32 v60, v50, v51
	v_pk_mul_f32 v[50:51], v[56:57], v[62:63]
	v_pk_mul_f32 v[52:53], v[52:53], v[64:65]
	v_add_f32_e32 v48, 1.0, v48
	v_pk_mul_f32 v[50:51], v[50:51], v[52:53]
	v_mul_f32_e32 v52, 0xbfb8aa3b, v41
	v_cvt_pk_bf16_f32 v61, v50, v51
	v_add_co_u32_e32 v50, vcc, s2, v156
	v_exp_f32_e32 v53, v52
	s_nop 0
	v_addc_co_u32_e32 v51, vcc, 0, v157, vcc
	global_store_dwordx4 v[50:51], v[58:61], off sc1
	v_rcp_f32_e32 v50, v48
	v_mul_f32_e32 v48, 0xbfb8aa3b, v40
	v_mul_f32_e32 v51, 0x3d372713, v45
	v_exp_f32_e32 v48, v48
	v_mul_f32_e32 v51, v45, v51
	v_fma_f32 v51, v45, v51, v45
	v_mul_f32_e32 v51, 0xc0135761, v51
	v_exp_f32_e32 v51, v51
	v_add_f32_e32 v48, 1.0, v48
	v_rcp_f32_e32 v52, v48
	v_add_f32_e32 v48, 1.0, v53
	v_rcp_f32_e32 v53, v48
	v_mul_f32_e32 v48, 0x3d372713, v46
	v_add_f32_e32 v51, 1.0, v51
	v_mul_f32_e32 v48, v46, v48
	v_rcp_f32_e32 v51, v51
	v_fma_f32 v48, v46, v48, v46
	v_mul_f32_e32 v48, 0xc0135761, v48
	v_exp_f32_e32 v48, v48
	v_pk_mul_f32 v[44:45], v[44:45], v[50:51]
	v_pk_mul_f32 v[40:41], v[40:41], v[52:53]
	s_mov_b32 s2, 0x48000
	v_pk_mul_f32 v[40:41], v[44:45], v[40:41]
	v_mul_f32_e32 v45, 0x3d372713, v47
	v_cvt_pk_bf16_f32 v40, v40, v41
	v_add_f32_e32 v41, 1.0, v48
	v_mul_f32_e32 v45, v47, v45
	v_rcp_f32_e32 v44, v41
	v_mul_f32_e32 v41, 0xbfb8aa3b, v42
	v_fma_f32 v45, v47, v45, v47
	v_exp_f32_e32 v41, v41
	v_mul_f32_e32 v45, 0xc0135761, v45
	v_mul_f32_e32 v48, 0xbfb8aa3b, v43
	v_exp_f32_e32 v45, v45
	v_exp_f32_e32 v48, v48
	v_add_f32_e32 v41, 1.0, v41
	v_rcp_f32_e32 v50, v41
	v_add_f32_e32 v45, 1.0, v45
	v_add_f32_e32 v41, 1.0, v48
	v_rcp_f32_e32 v45, v45
	v_rcp_f32_e32 v51, v41
	v_mul_f32_e32 v41, 0x3d372713, v36
	v_mul_f32_e32 v41, v36, v41
	v_pk_mul_f32 v[44:45], v[46:47], v[44:45]
	v_pk_mul_f32 v[42:43], v[42:43], v[50:51]
	v_fma_f32 v41, v36, v41, v36
	v_pk_mul_f32 v[42:43], v[44:45], v[42:43]
	v_mul_f32_e32 v44, 0x3d372713, v37
	v_mul_f32_e32 v41, 0xc0135761, v41
	v_mul_f32_e32 v44, v37, v44
	v_exp_f32_e32 v46, v41
	v_cvt_pk_bf16_f32 v41, v42, v43
	v_mul_f32_e32 v43, 0xbfb8aa3b, v32
	v_fma_f32 v44, v37, v44, v37
	v_exp_f32_e32 v43, v43
	v_mul_f32_e32 v44, 0xc0135761, v44
	v_exp_f32_e32 v44, v44
	v_add_f32_e32 v42, 1.0, v46
	v_add_f32_e32 v45, 1.0, v43
	v_mul_f32_e32 v43, 0xbfb8aa3b, v33
	v_exp_f32_e32 v46, v43
	v_add_f32_e32 v43, 1.0, v44
	v_rcp_f32_e32 v42, v42
	v_rcp_f32_e32 v43, v43
	v_rcp_f32_e32 v44, v45
	v_add_f32_e32 v45, 1.0, v46
	v_rcp_f32_e32 v45, v45
	v_pk_mul_f32 v[36:37], v[36:37], v[42:43]
	v_mul_f32_e32 v42, 0x3d372713, v38
	v_mul_f32_e32 v42, v38, v42
	v_fma_f32 v42, v38, v42, v38
	v_mul_f32_e32 v42, 0xc0135761, v42
	v_exp_f32_e32 v42, v42
	v_mul_f32_e32 v43, 0xbfb8aa3b, v34
	v_exp_f32_e32 v43, v43
	v_pk_mul_f32 v[32:33], v[32:33], v[44:45]
	v_add_f32_e32 v42, 1.0, v42
	v_rcp_f32_e32 v44, v42
	v_add_f32_e32 v42, 1.0, v43
	v_mul_f32_e32 v43, 0x3d372713, v39
	v_mul_f32_e32 v43, v39, v43
	v_fma_f32 v43, v39, v43, v39
	v_mul_f32_e32 v43, 0xc0135761, v43
	v_exp_f32_e32 v43, v43
	v_mul_f32_e32 v45, 0xbfb8aa3b, v35
	v_exp_f32_e32 v47, v45
	v_rcp_f32_e32 v46, v42
	v_add_f32_e32 v42, 1.0, v43
	v_rcp_f32_e32 v45, v42
	v_add_f32_e32 v42, 1.0, v47
	v_rcp_f32_e32 v47, v42
	v_pk_mul_f32 v[32:33], v[36:37], v[32:33]
	v_ashrrev_i32_e32 v83, 31, v82
	v_cvt_pk_bf16_f32 v42, v32, v33
	v_pk_mul_f32 v[32:33], v[38:39], v[44:45]
	v_pk_mul_f32 v[34:35], v[34:35], v[46:47]
	v_lshlrev_b64 v[114:115], 11, v[114:115]
	v_pk_mul_f32 v[32:33], v[32:33], v[34:35]
	v_lshlrev_b64 v[98:99], 11, v[98:99]
	v_cvt_pk_bf16_f32 v43, v32, v33
	v_mul_f32_e32 v32, 0x3d372713, v28
	v_mul_f32_e32 v32, v28, v32
	v_fma_f32 v32, v28, v32, v28
	v_mul_f32_e32 v32, 0xc0135761, v32
	v_exp_f32_e32 v34, v32
	v_add_co_u32_e32 v32, vcc, s2, v156
	s_mov_b32 s2, 0x50000
	s_nop 0
	v_addc_co_u32_e32 v33, vcc, 0, v157, vcc
	global_store_dwordx4 v[32:33], v[40:43], off sc1
	v_add_f32_e32 v32, 1.0, v34
	v_mul_f32_e32 v34, 0x3d372713, v29
	v_mul_f32_e32 v34, v29, v34
	v_mul_f32_e32 v33, 0xbfb8aa3b, v24
	v_fma_f32 v34, v29, v34, v29
	v_exp_f32_e32 v33, v33
	v_mul_f32_e32 v34, 0xc0135761, v34
	v_exp_f32_e32 v34, v34
	v_rcp_f32_e32 v32, v32
	v_add_f32_e32 v35, 1.0, v33
	v_mul_f32_e32 v33, 0xbfb8aa3b, v25
	v_exp_f32_e32 v36, v33
	v_add_f32_e32 v33, 1.0, v34
	v_rcp_f32_e32 v33, v33
	v_rcp_f32_e32 v34, v35
	v_add_f32_e32 v35, 1.0, v36
	v_rcp_f32_e32 v35, v35
	v_pk_mul_f32 v[28:29], v[28:29], v[32:33]
	v_mul_f32_e32 v32, 0x3d372713, v30
	v_mul_f32_e32 v32, v30, v32
	v_fma_f32 v32, v30, v32, v30
	v_mul_f32_e32 v32, 0xc0135761, v32
	v_exp_f32_e32 v32, v32
	v_pk_mul_f32 v[24:25], v[24:25], v[34:35]
	v_lshlrev_b64 v[82:83], 11, v[82:83]
	v_pk_mul_f32 v[24:25], v[28:29], v[24:25]
	v_mul_f32_e32 v29, 0x3d372713, v31
	v_cvt_pk_bf16_f32 v24, v24, v25
	v_add_f32_e32 v25, 1.0, v32
	v_mul_f32_e32 v29, v31, v29
	v_rcp_f32_e32 v28, v25
	v_mul_f32_e32 v25, 0xbfb8aa3b, v26
	v_fma_f32 v29, v31, v29, v31
	v_exp_f32_e32 v25, v25
	v_mul_f32_e32 v29, 0xc0135761, v29
	v_mul_f32_e32 v32, 0xbfb8aa3b, v27
	v_exp_f32_e32 v29, v29
	v_exp_f32_e32 v33, v32
	v_add_f32_e32 v25, 1.0, v25
	v_rcp_f32_e32 v32, v25
	v_add_f32_e32 v29, 1.0, v29
	v_add_f32_e32 v25, 1.0, v33
	v_rcp_f32_e32 v29, v29
	v_rcp_f32_e32 v33, v25
	v_mul_f32_e32 v25, 0x3d372713, v20
	v_mul_f32_e32 v25, v20, v25
	v_pk_mul_f32 v[28:29], v[30:31], v[28:29]
	v_pk_mul_f32 v[26:27], v[26:27], v[32:33]
	v_fma_f32 v25, v20, v25, v20
	v_pk_mul_f32 v[26:27], v[28:29], v[26:27]
; DI unsigned pk2(float lo, float hi) { f32x2 v = {lo, hi}; bf16v2 r = __builtin_convertvector(v, bf16v2); return __builtin_bit_cast(unsigned, r); }
; DI float siluf_(float x) { return x * sigmoidf_(x); }
; DI float geluf_(float x) { const float t = x + 0.044715f * x * x * x; return x * frcp(1.0f + fexp2(-2.3022082f * t)); }
; #define PG8_BAR __builtin_amdgcn_s_barrier()
; template <class Epi>
; DI void gemm_phase(LAS unsigned char* lds, const Gemm g, const Order& S, const Epi& E) {
;     ...
;         if (!has_next) break;
;         if (!keep)
; #pragma unroll
;         for (int a = 0; a < 2; ++a)
; #pragma unroll
;             for (int b = 0; b < 2; ++b)
; #pragma unroll
;                 for (int m = 0; m < 4; ++m)
; #pragma unroll
;                     for (int n = 0; n < 2; ++n) acc[a][b][m][n] = (f32x4){0.f, 0.f, 0.f, 0.f};
;         cur = nxt; cA = nA; cB = nB; ++ui;
;         if (wr == 1) PG8_BAR;
;     DI void operator()(const f32x4 (&acc)[2][2][4][2], const pg8::Unit& u, int wr, int wc, int fr, int fq) const {
;     ...
;         if (pn >= 20 && pn < 28) {
;             bf16_t* base = g3; const int col0 = 128 * (pn - 20) + cl;
; #pragma unroll
;             for (int ai = 0; ai < 2; ++ai)
; #pragma unroll
;                 for (int m = 0; m < 4; ++m) { bf16_t* rowp = base + (size_t)(row0 + ai * 128 + m * 16) * D + col0;
;                     const f32x4 u0 = acc[ai][0][m][0], u1 = acc[ai][0][m][1], g0 = acc[ai][1][m][0], g1 = acc[ai][1][m][1];
;                     u32x4 w; w.x = pk2(geluf_(u0[0]) * siluf_(g0[0]), geluf_(u0[1]) * siluf_(g0[1])); w.y = pk2(geluf_(u0[2]) * siluf_(g0[2]), geluf_(u0[3]) * siluf_(g0[3]));
;                     w.z = pk2(geluf_(u1[0]) * siluf_(g1[0]), geluf_(u1[1]) * siluf_(g1[1])); w.w = pk2(geluf_(u1[2]) * siluf_(g1[2]), geluf_(u1[3]) * siluf_(g1[3]));
;                     *(u32x4*)rowp = w; }
;             return;
;         }
	v_mul_f32_e32 v28, 0x3d372713, v21
	v_mul_f32_e32 v25, 0xc0135761, v25
	v_mul_f32_e32 v28, v21, v28
	v_exp_f32_e32 v30, v25
	v_cvt_pk_bf16_f32 v25, v26, v27
	v_mul_f32_e32 v27, 0xbfb8aa3b, v16
	v_fma_f32 v28, v21, v28, v21
	v_exp_f32_e32 v27, v27
	v_mul_f32_e32 v28, 0xc0135761, v28
	v_exp_f32_e32 v28, v28
	v_add_f32_e32 v26, 1.0, v30
	v_add_f32_e32 v29, 1.0, v27
	v_mul_f32_e32 v27, 0xbfb8aa3b, v17
	v_exp_f32_e32 v30, v27
	v_add_f32_e32 v27, 1.0, v28
	v_rcp_f32_e32 v26, v26
	v_rcp_f32_e32 v27, v27
	v_rcp_f32_e32 v28, v29
	v_add_f32_e32 v29, 1.0, v30
	v_rcp_f32_e32 v29, v29
	v_pk_mul_f32 v[20:21], v[20:21], v[26:27]
	v_mul_f32_e32 v26, 0x3d372713, v22
	v_mul_f32_e32 v26, v22, v26
	v_fma_f32 v26, v22, v26, v22
	v_mul_f32_e32 v26, 0xc0135761, v26
	v_exp_f32_e32 v26, v26
	v_mul_f32_e32 v27, 0xbfb8aa3b, v18
	v_exp_f32_e32 v27, v27
	v_pk_mul_f32 v[16:17], v[16:17], v[28:29]
	v_add_f32_e32 v26, 1.0, v26
	v_rcp_f32_e32 v28, v26
	v_add_f32_e32 v26, 1.0, v27
	v_mul_f32_e32 v27, 0x3d372713, v23
	v_mul_f32_e32 v27, v23, v27
	v_fma_f32 v27, v23, v27, v23
	v_mul_f32_e32 v27, 0xc0135761, v27
	v_exp_f32_e32 v27, v27
	v_mul_f32_e32 v29, 0xbfb8aa3b, v19
	v_exp_f32_e32 v31, v29
	v_rcp_f32_e32 v30, v26
	v_add_f32_e32 v26, 1.0, v27
	v_rcp_f32_e32 v29, v26
	v_add_f32_e32 v26, 1.0, v31
	v_rcp_f32_e32 v31, v26
	v_pk_mul_f32 v[16:17], v[20:21], v[16:17]
	v_lshl_add_u64 v[114:115], v[158:159], 0, v[114:115]
	v_cvt_pk_bf16_f32 v26, v16, v17
	v_pk_mul_f32 v[16:17], v[22:23], v[28:29]
	v_pk_mul_f32 v[18:19], v[18:19], v[30:31]
	v_lshl_add_u64 v[98:99], v[158:159], 0, v[98:99]
	v_pk_mul_f32 v[16:17], v[16:17], v[18:19]
	v_lshl_add_u64 v[82:83], v[158:159], 0, v[82:83]
	v_cvt_pk_bf16_f32 v27, v16, v17
	v_mul_f32_e32 v16, 0x3d372713, v12
	v_mul_f32_e32 v16, v12, v16
	v_fma_f32 v16, v12, v16, v12
	v_mul_f32_e32 v16, 0xc0135761, v16
	v_exp_f32_e32 v18, v16
	v_add_co_u32_e32 v16, vcc, s2, v156
	global_store_dwordx4 v[156:157], v[122:125], off sc1
	s_nop 0
	v_addc_co_u32_e32 v17, vcc, 0, v157, vcc
	global_store_dwordx4 v[16:17], v[24:27], off sc1
	v_add_f32_e32 v16, 1.0, v18
	v_mul_f32_e32 v18, 0x3d372713, v13
	v_mul_f32_e32 v18, v13, v18
	v_mul_f32_e32 v17, 0xbfb8aa3b, v8
	v_fma_f32 v18, v13, v18, v13
	v_exp_f32_e32 v17, v17
	v_mul_f32_e32 v18, 0xc0135761, v18
	v_exp_f32_e32 v18, v18
	v_rcp_f32_e32 v16, v16
	v_add_f32_e32 v19, 1.0, v17
	v_mul_f32_e32 v17, 0xbfb8aa3b, v9
	v_exp_f32_e32 v20, v17
	v_add_f32_e32 v17, 1.0, v18
	v_rcp_f32_e32 v17, v17
	v_rcp_f32_e32 v18, v19
	v_add_f32_e32 v19, 1.0, v20
	v_rcp_f32_e32 v19, v19
	v_pk_mul_f32 v[12:13], v[12:13], v[16:17]
	v_mul_f32_e32 v16, 0x3d372713, v14
	v_mul_f32_e32 v16, v14, v16
	v_fma_f32 v16, v14, v16, v14
	v_mul_f32_e32 v16, 0xc0135761, v16
	v_exp_f32_e32 v16, v16
	v_pk_mul_f32 v[8:9], v[8:9], v[18:19]
	global_store_dwordx4 v[114:115], v[106:109], off sc1
	v_pk_mul_f32 v[8:9], v[12:13], v[8:9]
	v_mul_f32_e32 v13, 0x3d372713, v15
	v_cvt_pk_bf16_f32 v8, v8, v9
	v_add_f32_e32 v9, 1.0, v16
	v_mul_f32_e32 v13, v15, v13
	v_rcp_f32_e32 v12, v9
	v_mul_f32_e32 v9, 0xbfb8aa3b, v10
	v_fma_f32 v13, v15, v13, v15
	v_exp_f32_e32 v9, v9
	v_mul_f32_e32 v13, 0xc0135761, v13
	v_mul_f32_e32 v16, 0xbfb8aa3b, v11
	v_exp_f32_e32 v13, v13
	v_exp_f32_e32 v17, v16
	v_add_f32_e32 v9, 1.0, v9
	v_rcp_f32_e32 v16, v9
	v_add_f32_e32 v13, 1.0, v13
	v_add_f32_e32 v9, 1.0, v17
	v_rcp_f32_e32 v13, v13
	v_rcp_f32_e32 v17, v9
	v_mul_f32_e32 v9, 0x3d372713, v4
	v_mul_f32_e32 v9, v4, v9
	v_pk_mul_f32 v[12:13], v[14:15], v[12:13]
	v_pk_mul_f32 v[10:11], v[10:11], v[16:17]
	v_fma_f32 v9, v4, v9, v4
	v_pk_mul_f32 v[10:11], v[12:13], v[10:11]
	v_mul_f32_e32 v12, 0x3d372713, v5
	v_mul_f32_e32 v9, 0xc0135761, v9
	v_mul_f32_e32 v12, v5, v12
	v_exp_f32_e32 v14, v9
	v_cvt_pk_bf16_f32 v9, v10, v11
	v_mul_f32_e32 v11, 0xbfb8aa3b, v0
	v_fma_f32 v12, v5, v12, v5
	v_exp_f32_e32 v11, v11
	v_mul_f32_e32 v12, 0xc0135761, v12
	v_exp_f32_e32 v12, v12
	v_add_f32_e32 v10, 1.0, v14
	v_add_f32_e32 v13, 1.0, v11
	v_mul_f32_e32 v11, 0xbfb8aa3b, v1
	v_exp_f32_e32 v14, v11
	v_add_f32_e32 v11, 1.0, v12
	v_rcp_f32_e32 v10, v10
	v_rcp_f32_e32 v11, v11
	v_rcp_f32_e32 v12, v13
	v_add_f32_e32 v13, 1.0, v14
	v_rcp_f32_e32 v13, v13
	v_pk_mul_f32 v[4:5], v[4:5], v[10:11]
	v_mul_f32_e32 v10, 0x3d372713, v6
	v_mul_f32_e32 v10, v6, v10
	v_fma_f32 v10, v6, v10, v6
	v_mul_f32_e32 v10, 0xc0135761, v10
	v_exp_f32_e32 v10, v10
	v_mul_f32_e32 v11, 0xbfb8aa3b, v2
	v_exp_f32_e32 v11, v11
	v_pk_mul_f32 v[0:1], v[0:1], v[12:13]
	v_add_f32_e32 v10, 1.0, v10
	v_rcp_f32_e32 v12, v10
	v_add_f32_e32 v10, 1.0, v11
	v_mul_f32_e32 v11, 0x3d372713, v7
	v_mul_f32_e32 v11, v7, v11
	v_fma_f32 v11, v7, v11, v7
	v_mul_f32_e32 v11, 0xc0135761, v11
	v_exp_f32_e32 v11, v11
	v_mul_f32_e32 v13, 0xbfb8aa3b, v3
	v_exp_f32_e32 v15, v13
	v_rcp_f32_e32 v14, v10
	v_add_f32_e32 v10, 1.0, v11
	v_rcp_f32_e32 v13, v10
	v_add_f32_e32 v10, 1.0, v15
	v_rcp_f32_e32 v15, v10
	v_pk_mul_f32 v[0:1], v[4:5], v[0:1]
	global_store_dwordx4 v[98:99], v[90:93], off sc1
	v_cvt_pk_bf16_f32 v10, v0, v1
	v_pk_mul_f32 v[0:1], v[6:7], v[12:13]
	v_pk_mul_f32 v[2:3], v[2:3], v[14:15]
	global_store_dwordx4 v[82:83], v[74:77], off sc1
	v_pk_mul_f32 v[0:1], v[0:1], v[2:3]
	s_nop 0
	v_cvt_pk_bf16_f32 v11, v0, v1
	v_add_co_u32_e32 v0, vcc, 0x58000, v156
	s_nop 1
	v_addc_co_u32_e32 v1, vcc, 0, v157, vcc
	global_store_dwordx4 v[0:1], v[8:11], off sc1
	s_andn2_b64 vcc, exec, s[6:7]
	s_mov_b64 s[2:3], -1
	s_cbranch_vccnz .LBB0_234
